# GEMM K-loops: counter/pointer increments and the loop compare hoisted ahead of the last LOAD segment's waits, leaving only the branch behind the closing barrier
# baseline (speedup 1.0000x reference)
.LBB0_125:
	s_ashr_i32 s77, s76, 31
	s_lshl_b64 s[18:19], s[76:77], 21
	s_add_u32 s58, s86, s18
	s_addc_u32 s59, s87, s19
	s_and_b64 s[18:19], s[6:7], exec
	s_cselect_b32 s11, s59, s9
	s_cselect_b32 s13, s58, s8
	s_ashr_i32 s17, s16, 31
	s_lshl_b64 s[18:19], s[16:17], 21
	s_add_u32 s36, s96, s18
	s_addc_u32 s37, s97, s19
	s_and_b64 s[18:19], s[6:7], exec
	s_cselect_b32 s17, s37, s15
	s_cselect_b32 s20, s36, s14
	s_add_u32 s8, s8, 0x100080
	s_addc_u32 s9, s9, 0
	s_add_u32 s21, s14, 0x100
	s_addc_u32 s28, s15, 0
	s_mov_b32 s29, -2
	ds_read_b128 v[130:133], v176
	ds_read_b128 v[134:137], v176 offset:1024
	ds_read_b128 v[170:173], v176 offset:2048
	ds_read_b128 v[180:183], v176 offset:3072
	ds_read_b128 v[184:187], v177
	ds_read_b128 v[188:191], v177 offset:1024
	ds_read_b128 v[192:195], v177 offset:2048
	ds_read_b128 v[198:201], v177 offset:3072
	s_add_u32 s14, s8, 0xfff00080
	s_addc_u32 s15, s9, -1
	s_cmp_eq_u32 s29, 60
	s_cselect_b32 s19, s11, s15
	s_cselect_b32 s18, s13, s14
	s_cselect_b32 s15, s17, s28
	s_cselect_b32 s14, s20, s21
	s_add_i32 m0, s73, 0xc000
	ds_read_b128 v[202:205], v178
	ds_read_b128 v[206:209], v178 offset:1024
	ds_read_b128 v[210:213], v178 offset:2048
	ds_read_b128 v[214:217], v178 offset:3072
	ds_read_b128 v[218:221], v178 offset:4096
	ds_read_b128 v[222:225], v178 offset:5120
	ds_read_b128 v[226:229], v178 offset:6144
	ds_read_b128 v[230:233], v178 offset:7168
	global_load_lds_dwordx4 v160, s[8:9]
	s_add_i32 m0, s73, 0xe000
	s_nop 0
	global_load_lds_dwordx4 v162, s[8:9]
	s_waitcnt vmcnt(8)
	s_waitcnt lgkmcnt(0)
	s_setprio 1
	s_barrier
	v_mfma_f32_16x16x32_bf16 v[126:129], v[130:133], v[202:205], 0
	v_mfma_f32_16x16x32_bf16 v[122:125], v[170:173], v[202:205], 0
	v_mfma_f32_16x16x32_bf16 v[110:113], v[130:133], v[210:213], 0
	v_mfma_f32_16x16x32_bf16 v[106:109], v[170:173], v[210:213], 0
	v_mfma_f32_16x16x32_bf16 v[94:97], v[130:133], v[218:221], 0
	v_mfma_f32_16x16x32_bf16 v[90:93], v[170:173], v[218:221], 0
	v_mfma_f32_16x16x32_bf16 v[78:81], v[130:133], v[226:229], 0
	v_mfma_f32_16x16x32_bf16 v[74:77], v[170:173], v[226:229], 0
	v_mfma_f32_16x16x32_bf16 v[126:129], v[134:137], v[206:209], v[126:129]
	v_mfma_f32_16x16x32_bf16 v[122:125], v[180:183], v[206:209], v[122:125]
	v_mfma_f32_16x16x32_bf16 v[110:113], v[134:137], v[214:217], v[110:113]
	v_mfma_f32_16x16x32_bf16 v[106:109], v[180:183], v[214:217], v[106:109]
	v_mfma_f32_16x16x32_bf16 v[94:97], v[134:137], v[222:225], v[94:97]
	v_mfma_f32_16x16x32_bf16 v[90:93], v[180:183], v[222:225], v[90:93]
	v_mfma_f32_16x16x32_bf16 v[78:81], v[134:137], v[230:233], v[78:81]
	v_mfma_f32_16x16x32_bf16 v[74:77], v[180:183], v[230:233], v[74:77]
	v_mfma_f32_16x16x32_bf16 v[118:121], v[184:187], v[202:205], 0
	v_mfma_f32_16x16x32_bf16 v[114:117], v[192:195], v[202:205], 0
	v_mfma_f32_16x16x32_bf16 v[102:105], v[184:187], v[210:213], 0
	v_mfma_f32_16x16x32_bf16 v[98:101], v[192:195], v[210:213], 0
	v_mfma_f32_16x16x32_bf16 v[86:89], v[184:187], v[218:221], 0
	v_mfma_f32_16x16x32_bf16 v[82:85], v[192:195], v[218:221], 0
	v_mfma_f32_16x16x32_bf16 v[70:73], v[184:187], v[226:229], 0
	v_mfma_f32_16x16x32_bf16 v[66:69], v[192:195], v[226:229], 0
	v_mfma_f32_16x16x32_bf16 v[118:121], v[188:191], v[206:209], v[118:121]
	v_mfma_f32_16x16x32_bf16 v[114:117], v[198:201], v[206:209], v[114:117]
	v_mfma_f32_16x16x32_bf16 v[102:105], v[188:191], v[214:217], v[102:105]
	v_mfma_f32_16x16x32_bf16 v[98:101], v[198:201], v[214:217], v[98:101]
	v_mfma_f32_16x16x32_bf16 v[86:89], v[188:191], v[222:225], v[86:89]
	v_mfma_f32_16x16x32_bf16 v[82:85], v[198:201], v[222:225], v[82:85]
	v_mfma_f32_16x16x32_bf16 v[70:73], v[188:191], v[230:233], v[70:73]
	v_mfma_f32_16x16x32_bf16 v[66:69], v[198:201], v[230:233], v[66:69]
	s_barrier
	s_setprio 0
	s_add_i32 s30, s69, s35
	s_mov_b32 m0, s30
	ds_read_b128 v[202:205], v178 offset:16384
	ds_read_b128 v[206:209], v178 offset:17408
	ds_read_b128 v[210:213], v178 offset:18432
	ds_read_b128 v[214:217], v178 offset:19456
	ds_read_b128 v[218:221], v178 offset:20480
	ds_read_b128 v[222:225], v178 offset:21504
	ds_read_b128 v[226:229], v178 offset:22528
	ds_read_b128 v[230:233], v178 offset:23552
	global_load_lds_dwordx4 v140, s[14:15]
	s_add_i32 m0, s30, 0x2000
	s_add_u32 s30, s14, 0x100000
	s_addc_u32 s31, s15, 0
	s_add_i32 s38, s70, s35
	global_load_lds_dwordx4 v144, s[14:15]
	s_mov_b32 m0, s38
	global_load_lds_dwordx4 v140, s[30:31]
	s_add_i32 m0, s38, 0x2000
	s_nop 0
	global_load_lds_dwordx4 v144, s[30:31]
	s_mov_b32 m0, s73
	s_nop 0
	global_load_lds_dwordx4 v138, s[18:19]
	s_mov_b32 m0, s66
	s_nop 0
	global_load_lds_dwordx4 v142, s[18:19]
	s_waitcnt vmcnt(8)
	s_waitcnt lgkmcnt(0)
	s_setprio 1
	s_barrier
	v_mfma_f32_16x16x32_bf16 v[62:65], v[130:133], v[202:205], 0
	v_mfma_f32_16x16x32_bf16 v[58:61], v[170:173], v[202:205], 0
	v_mfma_f32_16x16x32_bf16 v[46:49], v[130:133], v[210:213], 0
	v_mfma_f32_16x16x32_bf16 v[42:45], v[170:173], v[210:213], 0
	v_mfma_f32_16x16x32_bf16 v[30:33], v[130:133], v[218:221], 0
	v_mfma_f32_16x16x32_bf16 v[26:29], v[170:173], v[218:221], 0
	v_mfma_f32_16x16x32_bf16 v[14:17], v[130:133], v[226:229], 0
	v_mfma_f32_16x16x32_bf16 v[10:13], v[170:173], v[226:229], 0
	v_mfma_f32_16x16x32_bf16 v[62:65], v[134:137], v[206:209], v[62:65]
	v_mfma_f32_16x16x32_bf16 v[58:61], v[180:183], v[206:209], v[58:61]
	v_mfma_f32_16x16x32_bf16 v[46:49], v[134:137], v[214:217], v[46:49]
	v_mfma_f32_16x16x32_bf16 v[42:45], v[180:183], v[214:217], v[42:45]
	v_mfma_f32_16x16x32_bf16 v[30:33], v[134:137], v[222:225], v[30:33]
	v_mfma_f32_16x16x32_bf16 v[26:29], v[180:183], v[222:225], v[26:29]
	v_mfma_f32_16x16x32_bf16 v[14:17], v[134:137], v[230:233], v[14:17]
	v_mfma_f32_16x16x32_bf16 v[10:13], v[180:183], v[230:233], v[10:13]
	v_mfma_f32_16x16x32_bf16 v[54:57], v[184:187], v[202:205], 0
	v_mfma_f32_16x16x32_bf16 v[50:53], v[192:195], v[202:205], 0
	v_mfma_f32_16x16x32_bf16 v[38:41], v[184:187], v[210:213], 0
	v_mfma_f32_16x16x32_bf16 v[34:37], v[192:195], v[210:213], 0
	v_mfma_f32_16x16x32_bf16 v[22:25], v[184:187], v[218:221], 0
	v_mfma_f32_16x16x32_bf16 v[18:21], v[192:195], v[218:221], 0
	v_mfma_f32_16x16x32_bf16 v[6:9], v[184:187], v[226:229], 0
	v_mfma_f32_16x16x32_bf16 v[2:5], v[192:195], v[226:229], 0
	v_mfma_f32_16x16x32_bf16 v[54:57], v[188:191], v[206:209], v[54:57]
	v_mfma_f32_16x16x32_bf16 v[50:53], v[198:201], v[206:209], v[50:53]
	v_mfma_f32_16x16x32_bf16 v[38:41], v[188:191], v[214:217], v[38:41]
	v_mfma_f32_16x16x32_bf16 v[34:37], v[198:201], v[214:217], v[34:37]
	v_mfma_f32_16x16x32_bf16 v[22:25], v[188:191], v[222:225], v[22:25]
	v_mfma_f32_16x16x32_bf16 v[18:21], v[198:201], v[222:225], v[18:21]
	v_mfma_f32_16x16x32_bf16 v[6:9], v[188:191], v[230:233], v[6:9]
	v_mfma_f32_16x16x32_bf16 v[2:5], v[198:201], v[230:233], v[2:5]
	s_barrier
	s_setprio 0
	s_add_i32 s30, 0, 0x18000
	v_add_u32_e32 v146, s30, v155
	s_add_i32 s31, 0, 0x1c000
	ds_read_b128 v[130:133], v146
	ds_read_b128 v[134:137], v146 offset:1024
	ds_read_b128 v[170:173], v146 offset:2048
	ds_read_b128 v[180:183], v146 offset:3072
	v_add_u32_e32 v146, s31, v155
	ds_read_b128 v[184:187], v146
	ds_read_b128 v[188:191], v146 offset:1024
	ds_read_b128 v[192:195], v146 offset:2048
	ds_read_b128 v[198:201], v146 offset:3072
	s_add_u32 s18, s18, 0x100000
	s_addc_u32 s19, s19, 0
	s_mov_b32 m0, s67
	ds_read_b128 v[202:205], v178 offset:32768
	ds_read_b128 v[206:209], v178 offset:33792
	ds_read_b128 v[210:213], v178 offset:34816
	ds_read_b128 v[214:217], v178 offset:35840
	ds_read_b128 v[218:221], v178 offset:36864
	ds_read_b128 v[222:225], v178 offset:37888
	ds_read_b128 v[226:229], v178 offset:38912
	ds_read_b128 v[230:233], v178 offset:39936
	global_load_lds_dwordx4 v138, s[18:19]
	s_mov_b32 m0, s88
	s_nop 0
	global_load_lds_dwordx4 v142, s[18:19]
	s_waitcnt vmcnt(8)
	s_waitcnt lgkmcnt(0)
	s_setprio 1
	s_barrier
	v_mfma_f32_16x16x32_bf16 v[126:129], v[130:133], v[202:205], v[126:129]
	v_mfma_f32_16x16x32_bf16 v[122:125], v[170:173], v[202:205], v[122:125]
	v_mfma_f32_16x16x32_bf16 v[110:113], v[130:133], v[210:213], v[110:113]
	v_mfma_f32_16x16x32_bf16 v[106:109], v[170:173], v[210:213], v[106:109]
	v_mfma_f32_16x16x32_bf16 v[94:97], v[130:133], v[218:221], v[94:97]
	v_mfma_f32_16x16x32_bf16 v[90:93], v[170:173], v[218:221], v[90:93]
	v_mfma_f32_16x16x32_bf16 v[78:81], v[130:133], v[226:229], v[78:81]
	v_mfma_f32_16x16x32_bf16 v[74:77], v[170:173], v[226:229], v[74:77]
	v_mfma_f32_16x16x32_bf16 v[126:129], v[134:137], v[206:209], v[126:129]
	v_mfma_f32_16x16x32_bf16 v[122:125], v[180:183], v[206:209], v[122:125]
	v_mfma_f32_16x16x32_bf16 v[110:113], v[134:137], v[214:217], v[110:113]
	v_mfma_f32_16x16x32_bf16 v[106:109], v[180:183], v[214:217], v[106:109]
	v_mfma_f32_16x16x32_bf16 v[94:97], v[134:137], v[222:225], v[94:97]
	v_mfma_f32_16x16x32_bf16 v[90:93], v[180:183], v[222:225], v[90:93]
	v_mfma_f32_16x16x32_bf16 v[78:81], v[134:137], v[230:233], v[78:81]
	v_mfma_f32_16x16x32_bf16 v[74:77], v[180:183], v[230:233], v[74:77]
	v_mfma_f32_16x16x32_bf16 v[118:121], v[184:187], v[202:205], v[118:121]
	v_mfma_f32_16x16x32_bf16 v[114:117], v[192:195], v[202:205], v[114:117]
	v_mfma_f32_16x16x32_bf16 v[102:105], v[184:187], v[210:213], v[102:105]
	v_mfma_f32_16x16x32_bf16 v[98:101], v[192:195], v[210:213], v[98:101]
	v_mfma_f32_16x16x32_bf16 v[86:89], v[184:187], v[218:221], v[86:89]
	v_mfma_f32_16x16x32_bf16 v[82:85], v[192:195], v[218:221], v[82:85]
	v_mfma_f32_16x16x32_bf16 v[70:73], v[184:187], v[226:229], v[70:73]
	v_mfma_f32_16x16x32_bf16 v[66:69], v[192:195], v[226:229], v[66:69]
	v_mfma_f32_16x16x32_bf16 v[118:121], v[188:191], v[206:209], v[118:121]
	v_mfma_f32_16x16x32_bf16 v[114:117], v[198:201], v[206:209], v[114:117]
	v_mfma_f32_16x16x32_bf16 v[102:105], v[188:191], v[214:217], v[102:105]
	v_mfma_f32_16x16x32_bf16 v[98:101], v[198:201], v[214:217], v[98:101]
	v_mfma_f32_16x16x32_bf16 v[86:89], v[188:191], v[222:225], v[86:89]
	v_mfma_f32_16x16x32_bf16 v[82:85], v[198:201], v[222:225], v[82:85]
	v_mfma_f32_16x16x32_bf16 v[70:73], v[188:191], v[230:233], v[70:73]
	v_mfma_f32_16x16x32_bf16 v[66:69], v[198:201], v[230:233], v[66:69]
	s_barrier
	s_setprio 0
	s_add_u32 s14, s14, 0x80
	s_addc_u32 s15, s15, 0
	s_add_i32 m0, s35, 0x18000
	ds_read_b128 v[202:205], v178 offset:49152
	ds_read_b128 v[206:209], v178 offset:50176
	ds_read_b128 v[210:213], v178 offset:51200
	ds_read_b128 v[214:217], v178 offset:52224
	ds_read_b128 v[218:221], v178 offset:53248
	ds_read_b128 v[222:225], v178 offset:54272
	ds_read_b128 v[226:229], v178 offset:55296
	ds_read_b128 v[230:233], v178 offset:56320
	global_load_lds_dwordx4 v140, s[14:15]
	s_add_i32 m0, s35, 0x1a000
	s_add_u32 s18, s18, 0xfff00080
	global_load_lds_dwordx4 v144, s[14:15]
	s_addc_u32 s19, s19, -1
	s_add_u32 s14, s14, 0x100000
	s_addc_u32 s15, s15, 0
	s_add_i32 m0, s35, 0x1c000
	s_nop 0
	global_load_lds_dwordx4 v140, s[14:15]
	s_add_i32 m0, s35, 0x1e000
	s_nop 0
	global_load_lds_dwordx4 v144, s[14:15]
	s_mov_b32 m0, s89
	s_nop 0
	global_load_lds_dwordx4 v138, s[18:19]
	s_mov_b32 m0, s68
	s_nop 0
	global_load_lds_dwordx4 v142, s[18:19]
	s_add_i32 s29, s29, 2
	s_add_u32 s8, s8, 0x100
	s_addc_u32 s9, s9, 0
	s_add_u32 s21, s21, 0x100
	s_addc_u32 s28, s28, 0
	s_cmp_gt_u32 s29, 61
	s_waitcnt vmcnt(8)
	s_waitcnt lgkmcnt(0)
	s_setprio 1
	s_barrier
	v_mfma_f32_16x16x32_bf16 v[62:65], v[130:133], v[202:205], v[62:65]
	v_mfma_f32_16x16x32_bf16 v[58:61], v[170:173], v[202:205], v[58:61]
	v_mfma_f32_16x16x32_bf16 v[46:49], v[130:133], v[210:213], v[46:49]
	v_mfma_f32_16x16x32_bf16 v[42:45], v[170:173], v[210:213], v[42:45]
	v_mfma_f32_16x16x32_bf16 v[30:33], v[130:133], v[218:221], v[30:33]
	v_mfma_f32_16x16x32_bf16 v[26:29], v[170:173], v[218:221], v[26:29]
	v_mfma_f32_16x16x32_bf16 v[14:17], v[130:133], v[226:229], v[14:17]
	v_mfma_f32_16x16x32_bf16 v[10:13], v[170:173], v[226:229], v[10:13]
	v_mfma_f32_16x16x32_bf16 v[62:65], v[134:137], v[206:209], v[62:65]
	v_mfma_f32_16x16x32_bf16 v[58:61], v[180:183], v[206:209], v[58:61]
	v_mfma_f32_16x16x32_bf16 v[46:49], v[134:137], v[214:217], v[46:49]
	v_mfma_f32_16x16x32_bf16 v[42:45], v[180:183], v[214:217], v[42:45]
	v_mfma_f32_16x16x32_bf16 v[30:33], v[134:137], v[222:225], v[30:33]
	v_mfma_f32_16x16x32_bf16 v[26:29], v[180:183], v[222:225], v[26:29]
	v_mfma_f32_16x16x32_bf16 v[14:17], v[134:137], v[230:233], v[14:17]
	v_mfma_f32_16x16x32_bf16 v[10:13], v[180:183], v[230:233], v[10:13]
	v_mfma_f32_16x16x32_bf16 v[54:57], v[184:187], v[202:205], v[54:57]
	v_mfma_f32_16x16x32_bf16 v[50:53], v[192:195], v[202:205], v[50:53]
	v_mfma_f32_16x16x32_bf16 v[38:41], v[184:187], v[210:213], v[38:41]
	v_mfma_f32_16x16x32_bf16 v[34:37], v[192:195], v[210:213], v[34:37]
	v_mfma_f32_16x16x32_bf16 v[22:25], v[184:187], v[218:221], v[22:25]
	v_mfma_f32_16x16x32_bf16 v[18:21], v[192:195], v[218:221], v[18:21]
	v_mfma_f32_16x16x32_bf16 v[6:9], v[184:187], v[226:229], v[6:9]
	v_mfma_f32_16x16x32_bf16 v[2:5], v[192:195], v[226:229], v[2:5]
	v_mfma_f32_16x16x32_bf16 v[54:57], v[188:191], v[206:209], v[54:57]
	v_mfma_f32_16x16x32_bf16 v[50:53], v[198:201], v[206:209], v[50:53]
	v_mfma_f32_16x16x32_bf16 v[38:41], v[188:191], v[214:217], v[38:41]
	v_mfma_f32_16x16x32_bf16 v[34:37], v[198:201], v[214:217], v[34:37]
	v_mfma_f32_16x16x32_bf16 v[22:25], v[188:191], v[222:225], v[22:25]
	v_mfma_f32_16x16x32_bf16 v[18:21], v[198:201], v[222:225], v[18:21]
	v_mfma_f32_16x16x32_bf16 v[6:9], v[188:191], v[230:233], v[6:9]
	v_mfma_f32_16x16x32_bf16 v[2:5], v[198:201], v[230:233], v[2:5]
	s_barrier
	s_setprio 0
	.p2align	8
.LBB0_126:
	ds_read_b128 v[130:133], v176
	ds_read_b128 v[134:137], v176 offset:1024
	ds_read_b128 v[170:173], v176 offset:2048
	ds_read_b128 v[180:183], v176 offset:3072
	ds_read_b128 v[184:187], v177
	ds_read_b128 v[188:191], v177 offset:1024
	ds_read_b128 v[192:195], v177 offset:2048
	ds_read_b128 v[198:201], v177 offset:3072
	s_add_u32 s14, s8, 0xfff00080
	s_addc_u32 s15, s9, -1
	s_cmp_eq_u32 s29, 60
	s_cselect_b32 s19, s11, s15
	s_cselect_b32 s18, s13, s14
	s_cselect_b32 s15, s17, s28
	s_cselect_b32 s14, s20, s21
	s_add_i32 m0, s73, 0xc000
	ds_read_b128 v[202:205], v178
	ds_read_b128 v[206:209], v178 offset:1024
	ds_read_b128 v[210:213], v178 offset:2048
	ds_read_b128 v[214:217], v178 offset:3072
	ds_read_b128 v[218:221], v178 offset:4096
	ds_read_b128 v[222:225], v178 offset:5120
	ds_read_b128 v[226:229], v178 offset:6144
	ds_read_b128 v[230:233], v178 offset:7168
	global_load_lds_dwordx4 v160, s[8:9]
	s_add_i32 m0, s73, 0xe000
	s_nop 0
	global_load_lds_dwordx4 v162, s[8:9]
	s_waitcnt vmcnt(8)
	s_waitcnt lgkmcnt(0)
	s_setprio 1
	s_barrier
	v_mfma_f32_16x16x32_bf16 v[126:129], v[130:133], v[202:205], v[126:129]
	v_mfma_f32_16x16x32_bf16 v[122:125], v[170:173], v[202:205], v[122:125]
	v_mfma_f32_16x16x32_bf16 v[110:113], v[130:133], v[210:213], v[110:113]
	v_mfma_f32_16x16x32_bf16 v[106:109], v[170:173], v[210:213], v[106:109]
	v_mfma_f32_16x16x32_bf16 v[94:97], v[130:133], v[218:221], v[94:97]
	v_mfma_f32_16x16x32_bf16 v[90:93], v[170:173], v[218:221], v[90:93]
	v_mfma_f32_16x16x32_bf16 v[78:81], v[130:133], v[226:229], v[78:81]
	v_mfma_f32_16x16x32_bf16 v[74:77], v[170:173], v[226:229], v[74:77]
	v_mfma_f32_16x16x32_bf16 v[126:129], v[134:137], v[206:209], v[126:129]
	v_mfma_f32_16x16x32_bf16 v[122:125], v[180:183], v[206:209], v[122:125]
	v_mfma_f32_16x16x32_bf16 v[110:113], v[134:137], v[214:217], v[110:113]
	v_mfma_f32_16x16x32_bf16 v[106:109], v[180:183], v[214:217], v[106:109]
	v_mfma_f32_16x16x32_bf16 v[94:97], v[134:137], v[222:225], v[94:97]
	v_mfma_f32_16x16x32_bf16 v[90:93], v[180:183], v[222:225], v[90:93]
	v_mfma_f32_16x16x32_bf16 v[78:81], v[134:137], v[230:233], v[78:81]
	v_mfma_f32_16x16x32_bf16 v[74:77], v[180:183], v[230:233], v[74:77]
	v_mfma_f32_16x16x32_bf16 v[118:121], v[184:187], v[202:205], v[118:121]
	v_mfma_f32_16x16x32_bf16 v[114:117], v[192:195], v[202:205], v[114:117]
	v_mfma_f32_16x16x32_bf16 v[102:105], v[184:187], v[210:213], v[102:105]
	v_mfma_f32_16x16x32_bf16 v[98:101], v[192:195], v[210:213], v[98:101]
	v_mfma_f32_16x16x32_bf16 v[86:89], v[184:187], v[218:221], v[86:89]
	v_mfma_f32_16x16x32_bf16 v[82:85], v[192:195], v[218:221], v[82:85]
	v_mfma_f32_16x16x32_bf16 v[70:73], v[184:187], v[226:229], v[70:73]
	v_mfma_f32_16x16x32_bf16 v[66:69], v[192:195], v[226:229], v[66:69]
	v_mfma_f32_16x16x32_bf16 v[118:121], v[188:191], v[206:209], v[118:121]
	v_mfma_f32_16x16x32_bf16 v[114:117], v[198:201], v[206:209], v[114:117]
	v_mfma_f32_16x16x32_bf16 v[102:105], v[188:191], v[214:217], v[102:105]
	v_mfma_f32_16x16x32_bf16 v[98:101], v[198:201], v[214:217], v[98:101]
	v_mfma_f32_16x16x32_bf16 v[86:89], v[188:191], v[222:225], v[86:89]
	v_mfma_f32_16x16x32_bf16 v[82:85], v[198:201], v[222:225], v[82:85]
	v_mfma_f32_16x16x32_bf16 v[70:73], v[188:191], v[230:233], v[70:73]
	v_mfma_f32_16x16x32_bf16 v[66:69], v[198:201], v[230:233], v[66:69]
	s_barrier
	s_setprio 0
	s_add_i32 s30, s69, s35
	s_mov_b32 m0, s30
	ds_read_b128 v[202:205], v178 offset:16384
	ds_read_b128 v[206:209], v178 offset:17408
	ds_read_b128 v[210:213], v178 offset:18432
	ds_read_b128 v[214:217], v178 offset:19456
	ds_read_b128 v[218:221], v178 offset:20480
	ds_read_b128 v[222:225], v178 offset:21504
	ds_read_b128 v[226:229], v178 offset:22528
	ds_read_b128 v[230:233], v178 offset:23552
	global_load_lds_dwordx4 v140, s[14:15]
	s_add_i32 m0, s30, 0x2000
	s_add_u32 s30, s14, 0x100000
	s_addc_u32 s31, s15, 0
	s_add_i32 s38, s70, s35
	global_load_lds_dwordx4 v144, s[14:15]
	s_mov_b32 m0, s38
	global_load_lds_dwordx4 v140, s[30:31]
	s_add_i32 m0, s38, 0x2000
	s_nop 0
	global_load_lds_dwordx4 v144, s[30:31]
	s_mov_b32 m0, s73
	s_nop 0
	global_load_lds_dwordx4 v138, s[18:19]
	s_mov_b32 m0, s66
	s_nop 0
	global_load_lds_dwordx4 v142, s[18:19]
	s_waitcnt vmcnt(8)
	s_waitcnt lgkmcnt(0)
	s_setprio 1
	s_barrier
	v_mfma_f32_16x16x32_bf16 v[62:65], v[130:133], v[202:205], v[62:65]
	v_mfma_f32_16x16x32_bf16 v[58:61], v[170:173], v[202:205], v[58:61]
	v_mfma_f32_16x16x32_bf16 v[46:49], v[130:133], v[210:213], v[46:49]
	v_mfma_f32_16x16x32_bf16 v[42:45], v[170:173], v[210:213], v[42:45]
	v_mfma_f32_16x16x32_bf16 v[30:33], v[130:133], v[218:221], v[30:33]
	v_mfma_f32_16x16x32_bf16 v[26:29], v[170:173], v[218:221], v[26:29]
	v_mfma_f32_16x16x32_bf16 v[14:17], v[130:133], v[226:229], v[14:17]
	v_mfma_f32_16x16x32_bf16 v[10:13], v[170:173], v[226:229], v[10:13]
	v_mfma_f32_16x16x32_bf16 v[62:65], v[134:137], v[206:209], v[62:65]
	v_mfma_f32_16x16x32_bf16 v[58:61], v[180:183], v[206:209], v[58:61]
	v_mfma_f32_16x16x32_bf16 v[46:49], v[134:137], v[214:217], v[46:49]
	v_mfma_f32_16x16x32_bf16 v[42:45], v[180:183], v[214:217], v[42:45]
	v_mfma_f32_16x16x32_bf16 v[30:33], v[134:137], v[222:225], v[30:33]
	v_mfma_f32_16x16x32_bf16 v[26:29], v[180:183], v[222:225], v[26:29]
	v_mfma_f32_16x16x32_bf16 v[14:17], v[134:137], v[230:233], v[14:17]
	v_mfma_f32_16x16x32_bf16 v[10:13], v[180:183], v[230:233], v[10:13]
	v_mfma_f32_16x16x32_bf16 v[54:57], v[184:187], v[202:205], v[54:57]
	v_mfma_f32_16x16x32_bf16 v[50:53], v[192:195], v[202:205], v[50:53]
	v_mfma_f32_16x16x32_bf16 v[38:41], v[184:187], v[210:213], v[38:41]
	v_mfma_f32_16x16x32_bf16 v[34:37], v[192:195], v[210:213], v[34:37]
	v_mfma_f32_16x16x32_bf16 v[22:25], v[184:187], v[218:221], v[22:25]
	v_mfma_f32_16x16x32_bf16 v[18:21], v[192:195], v[218:221], v[18:21]
	v_mfma_f32_16x16x32_bf16 v[6:9], v[184:187], v[226:229], v[6:9]
	v_mfma_f32_16x16x32_bf16 v[2:5], v[192:195], v[226:229], v[2:5]
	v_mfma_f32_16x16x32_bf16 v[54:57], v[188:191], v[206:209], v[54:57]
	v_mfma_f32_16x16x32_bf16 v[50:53], v[198:201], v[206:209], v[50:53]
	v_mfma_f32_16x16x32_bf16 v[38:41], v[188:191], v[214:217], v[38:41]
	v_mfma_f32_16x16x32_bf16 v[34:37], v[198:201], v[214:217], v[34:37]
	v_mfma_f32_16x16x32_bf16 v[22:25], v[188:191], v[222:225], v[22:25]
	v_mfma_f32_16x16x32_bf16 v[18:21], v[198:201], v[222:225], v[18:21]
	v_mfma_f32_16x16x32_bf16 v[6:9], v[188:191], v[230:233], v[6:9]
	v_mfma_f32_16x16x32_bf16 v[2:5], v[198:201], v[230:233], v[2:5]
	s_barrier
	s_setprio 0
	s_add_i32 s30, 0, 0x18000
	v_add_u32_e32 v146, s30, v155
	s_add_i32 s31, 0, 0x1c000
	ds_read_b128 v[130:133], v146
	ds_read_b128 v[134:137], v146 offset:1024
	ds_read_b128 v[170:173], v146 offset:2048
	ds_read_b128 v[180:183], v146 offset:3072
	v_add_u32_e32 v146, s31, v155
	ds_read_b128 v[184:187], v146
	ds_read_b128 v[188:191], v146 offset:1024
	ds_read_b128 v[192:195], v146 offset:2048
	ds_read_b128 v[198:201], v146 offset:3072
	s_add_u32 s18, s18, 0x100000
	s_addc_u32 s19, s19, 0
	s_mov_b32 m0, s67
	ds_read_b128 v[202:205], v178 offset:32768
	ds_read_b128 v[206:209], v178 offset:33792
	ds_read_b128 v[210:213], v178 offset:34816
	ds_read_b128 v[214:217], v178 offset:35840
	ds_read_b128 v[218:221], v178 offset:36864
	ds_read_b128 v[222:225], v178 offset:37888
	ds_read_b128 v[226:229], v178 offset:38912
	ds_read_b128 v[230:233], v178 offset:39936
	global_load_lds_dwordx4 v138, s[18:19]
	s_mov_b32 m0, s88
	s_nop 0
	global_load_lds_dwordx4 v142, s[18:19]
	s_waitcnt vmcnt(8)
	s_waitcnt lgkmcnt(0)
	s_setprio 1
	s_barrier
	v_mfma_f32_16x16x32_bf16 v[126:129], v[130:133], v[202:205], v[126:129]
	v_mfma_f32_16x16x32_bf16 v[122:125], v[170:173], v[202:205], v[122:125]
	v_mfma_f32_16x16x32_bf16 v[110:113], v[130:133], v[210:213], v[110:113]
	v_mfma_f32_16x16x32_bf16 v[106:109], v[170:173], v[210:213], v[106:109]
	v_mfma_f32_16x16x32_bf16 v[94:97], v[130:133], v[218:221], v[94:97]
	v_mfma_f32_16x16x32_bf16 v[90:93], v[170:173], v[218:221], v[90:93]
	v_mfma_f32_16x16x32_bf16 v[78:81], v[130:133], v[226:229], v[78:81]
	v_mfma_f32_16x16x32_bf16 v[74:77], v[170:173], v[226:229], v[74:77]
	v_mfma_f32_16x16x32_bf16 v[126:129], v[134:137], v[206:209], v[126:129]
	v_mfma_f32_16x16x32_bf16 v[122:125], v[180:183], v[206:209], v[122:125]
	v_mfma_f32_16x16x32_bf16 v[110:113], v[134:137], v[214:217], v[110:113]
	v_mfma_f32_16x16x32_bf16 v[106:109], v[180:183], v[214:217], v[106:109]
	v_mfma_f32_16x16x32_bf16 v[94:97], v[134:137], v[222:225], v[94:97]
	v_mfma_f32_16x16x32_bf16 v[90:93], v[180:183], v[222:225], v[90:93]
	v_mfma_f32_16x16x32_bf16 v[78:81], v[134:137], v[230:233], v[78:81]
	v_mfma_f32_16x16x32_bf16 v[74:77], v[180:183], v[230:233], v[74:77]
	v_mfma_f32_16x16x32_bf16 v[118:121], v[184:187], v[202:205], v[118:121]
	v_mfma_f32_16x16x32_bf16 v[114:117], v[192:195], v[202:205], v[114:117]
	v_mfma_f32_16x16x32_bf16 v[102:105], v[184:187], v[210:213], v[102:105]
	v_mfma_f32_16x16x32_bf16 v[98:101], v[192:195], v[210:213], v[98:101]
	v_mfma_f32_16x16x32_bf16 v[86:89], v[184:187], v[218:221], v[86:89]
	v_mfma_f32_16x16x32_bf16 v[82:85], v[192:195], v[218:221], v[82:85]
	v_mfma_f32_16x16x32_bf16 v[70:73], v[184:187], v[226:229], v[70:73]
	v_mfma_f32_16x16x32_bf16 v[66:69], v[192:195], v[226:229], v[66:69]
	v_mfma_f32_16x16x32_bf16 v[118:121], v[188:191], v[206:209], v[118:121]
	v_mfma_f32_16x16x32_bf16 v[114:117], v[198:201], v[206:209], v[114:117]
	v_mfma_f32_16x16x32_bf16 v[102:105], v[188:191], v[214:217], v[102:105]
	v_mfma_f32_16x16x32_bf16 v[98:101], v[198:201], v[214:217], v[98:101]
	v_mfma_f32_16x16x32_bf16 v[86:89], v[188:191], v[222:225], v[86:89]
	v_mfma_f32_16x16x32_bf16 v[82:85], v[198:201], v[222:225], v[82:85]
	v_mfma_f32_16x16x32_bf16 v[70:73], v[188:191], v[230:233], v[70:73]
	v_mfma_f32_16x16x32_bf16 v[66:69], v[198:201], v[230:233], v[66:69]
	s_barrier
	s_setprio 0
	s_add_u32 s14, s14, 0x80
	s_addc_u32 s15, s15, 0
	s_add_i32 m0, s35, 0x18000
	ds_read_b128 v[202:205], v178 offset:49152
	ds_read_b128 v[206:209], v178 offset:50176
	ds_read_b128 v[210:213], v178 offset:51200
	ds_read_b128 v[214:217], v178 offset:52224
	ds_read_b128 v[218:221], v178 offset:53248
	ds_read_b128 v[222:225], v178 offset:54272
	ds_read_b128 v[226:229], v178 offset:55296
	ds_read_b128 v[230:233], v178 offset:56320
	global_load_lds_dwordx4 v140, s[14:15]
	s_add_i32 m0, s35, 0x1a000
	s_add_u32 s18, s18, 0xfff00080
	global_load_lds_dwordx4 v144, s[14:15]
	s_addc_u32 s19, s19, -1
	s_add_u32 s14, s14, 0x100000
	s_addc_u32 s15, s15, 0
	s_add_i32 m0, s35, 0x1c000
	s_nop 0
	global_load_lds_dwordx4 v140, s[14:15]
	s_add_i32 m0, s35, 0x1e000
	s_nop 0
	global_load_lds_dwordx4 v144, s[14:15]
	s_mov_b32 m0, s89
	s_nop 0
	global_load_lds_dwordx4 v138, s[18:19]
	s_mov_b32 m0, s68
	s_nop 0
	global_load_lds_dwordx4 v142, s[18:19]
	s_add_i32 s29, s29, 2
	s_add_u32 s8, s8, 0x100
	s_addc_u32 s9, s9, 0
	s_add_u32 s21, s21, 0x100
	s_addc_u32 s28, s28, 0
	s_cmp_gt_u32 s29, 61
	s_waitcnt vmcnt(8)
	s_waitcnt lgkmcnt(0)
	s_setprio 1
	s_barrier
	v_mfma_f32_16x16x32_bf16 v[62:65], v[130:133], v[202:205], v[62:65]
	v_mfma_f32_16x16x32_bf16 v[58:61], v[170:173], v[202:205], v[58:61]
	v_mfma_f32_16x16x32_bf16 v[46:49], v[130:133], v[210:213], v[46:49]
	v_mfma_f32_16x16x32_bf16 v[42:45], v[170:173], v[210:213], v[42:45]
	v_mfma_f32_16x16x32_bf16 v[30:33], v[130:133], v[218:221], v[30:33]
	v_mfma_f32_16x16x32_bf16 v[26:29], v[170:173], v[218:221], v[26:29]
	v_mfma_f32_16x16x32_bf16 v[14:17], v[130:133], v[226:229], v[14:17]
	v_mfma_f32_16x16x32_bf16 v[10:13], v[170:173], v[226:229], v[10:13]
	v_mfma_f32_16x16x32_bf16 v[62:65], v[134:137], v[206:209], v[62:65]
	v_mfma_f32_16x16x32_bf16 v[58:61], v[180:183], v[206:209], v[58:61]
	v_mfma_f32_16x16x32_bf16 v[46:49], v[134:137], v[214:217], v[46:49]
	v_mfma_f32_16x16x32_bf16 v[42:45], v[180:183], v[214:217], v[42:45]
	v_mfma_f32_16x16x32_bf16 v[30:33], v[134:137], v[222:225], v[30:33]
	v_mfma_f32_16x16x32_bf16 v[26:29], v[180:183], v[222:225], v[26:29]
	v_mfma_f32_16x16x32_bf16 v[14:17], v[134:137], v[230:233], v[14:17]
	v_mfma_f32_16x16x32_bf16 v[10:13], v[180:183], v[230:233], v[10:13]
	v_mfma_f32_16x16x32_bf16 v[54:57], v[184:187], v[202:205], v[54:57]
	v_mfma_f32_16x16x32_bf16 v[50:53], v[192:195], v[202:205], v[50:53]
	v_mfma_f32_16x16x32_bf16 v[38:41], v[184:187], v[210:213], v[38:41]
	v_mfma_f32_16x16x32_bf16 v[34:37], v[192:195], v[210:213], v[34:37]
	v_mfma_f32_16x16x32_bf16 v[22:25], v[184:187], v[218:221], v[22:25]
	v_mfma_f32_16x16x32_bf16 v[18:21], v[192:195], v[218:221], v[18:21]
	v_mfma_f32_16x16x32_bf16 v[6:9], v[184:187], v[226:229], v[6:9]
	v_mfma_f32_16x16x32_bf16 v[2:5], v[192:195], v[226:229], v[2:5]
	v_mfma_f32_16x16x32_bf16 v[54:57], v[188:191], v[206:209], v[54:57]
	v_mfma_f32_16x16x32_bf16 v[50:53], v[198:201], v[206:209], v[50:53]
	v_mfma_f32_16x16x32_bf16 v[38:41], v[188:191], v[214:217], v[38:41]
	v_mfma_f32_16x16x32_bf16 v[34:37], v[198:201], v[214:217], v[34:37]
	v_mfma_f32_16x16x32_bf16 v[22:25], v[188:191], v[222:225], v[22:25]
	v_mfma_f32_16x16x32_bf16 v[18:21], v[198:201], v[222:225], v[18:21]
	v_mfma_f32_16x16x32_bf16 v[6:9], v[188:191], v[230:233], v[6:9]
	v_mfma_f32_16x16x32_bf16 v[2:5], v[198:201], v[230:233], v[2:5]
	s_barrier
	s_setprio 0
	s_cbranch_scc0 .LBB0_126
	v_readlane_b32 s8, v249, 56
	v_readlane_b32 s9, v249, 57
	s_and_b64 vcc, exec, s[8:9]
	s_cbranch_vccz .LBB0_129
	s_barrier

.LBB0_677:
	s_ashr_i32 s47, s46, 31
	s_lshl_b64 s[48:49], s[46:47], 21
	s_add_u32 s48, s86, s48
	s_addc_u32 s49, s87, s49
	s_and_b64 s[50:51], s[4:5], exec
	s_cselect_b32 s7, s49, s59
	s_cselect_b32 s47, s48, s58
	s_ashr_i32 s45, s44, 31
	s_lshl_b64 s[50:51], s[44:45], 21
	s_add_u32 s50, s82, s50
	s_addc_u32 s51, s83, s51
	s_and_b64 s[62:63], s[4:5], exec
	s_cselect_b32 s45, s51, s61
	s_cselect_b32 s57, s50, s60
	s_add_u32 s58, s58, 0x100080
	s_addc_u32 s59, s59, 0
	s_add_u32 s76, s60, 0x100
	s_addc_u32 s77, s61, 0
	s_mov_b32 s78, -2
	s_waitcnt lgkmcnt(0)
	ds_read_b128 v[148:151], v159
	ds_read_b128 v[152:155], v159 offset:1024
	ds_read_b128 v[164:167], v159 offset:2048
	ds_read_b128 v[168:171], v159 offset:3072
	ds_read_b128 v[172:175], v160
	ds_read_b128 v[176:179], v160 offset:1024
	ds_read_b128 v[180:183], v160 offset:2048
	ds_read_b128 v[184:187], v160 offset:3072
	s_add_u32 s60, s58, 0xfff00080
	s_addc_u32 s61, s59, -1
	s_cmp_eq_u32 s78, 60
	s_cselect_b32 s63, s7, s61
	s_cselect_b32 s62, s47, s60
	s_cselect_b32 s61, s45, s77
	s_cselect_b32 s60, s57, s76
	s_add_i32 m0, s64, 0xc000
	ds_read_b128 v[188:191], v161
	ds_read_b128 v[192:195], v161 offset:1024
	ds_read_b128 v[198:201], v161 offset:2048
	ds_read_b128 v[202:205], v161 offset:3072
	ds_read_b128 v[206:209], v161 offset:4096
	ds_read_b128 v[210:213], v161 offset:5120
	ds_read_b128 v[214:217], v161 offset:6144
	ds_read_b128 v[218:221], v161 offset:7168
	global_load_lds_dwordx4 v140, s[58:59]
	s_add_i32 m0, s64, 0xe000
	s_nop 0
	global_load_lds_dwordx4 v142, s[58:59]
	s_waitcnt vmcnt(32)
	s_waitcnt lgkmcnt(0)
	s_setprio 1
	s_barrier
	v_mfma_f32_16x16x32_bf16 v[126:129], v[148:151], v[188:191], 0
	v_mfma_f32_16x16x32_bf16 v[122:125], v[164:167], v[188:191], 0
	v_mfma_f32_16x16x32_bf16 v[110:113], v[148:151], v[198:201], 0
	v_mfma_f32_16x16x32_bf16 v[106:109], v[164:167], v[198:201], 0
	v_mfma_f32_16x16x32_bf16 v[94:97], v[148:151], v[206:209], 0
	v_mfma_f32_16x16x32_bf16 v[90:93], v[164:167], v[206:209], 0
	v_mfma_f32_16x16x32_bf16 v[78:81], v[148:151], v[214:217], 0
	v_mfma_f32_16x16x32_bf16 v[74:77], v[164:167], v[214:217], 0
	v_mfma_f32_16x16x32_bf16 v[126:129], v[152:155], v[192:195], v[126:129]
	v_mfma_f32_16x16x32_bf16 v[122:125], v[168:171], v[192:195], v[122:125]
	v_mfma_f32_16x16x32_bf16 v[110:113], v[152:155], v[202:205], v[110:113]
	v_mfma_f32_16x16x32_bf16 v[106:109], v[168:171], v[202:205], v[106:109]
	v_mfma_f32_16x16x32_bf16 v[94:97], v[152:155], v[210:213], v[94:97]
	v_mfma_f32_16x16x32_bf16 v[90:93], v[168:171], v[210:213], v[90:93]
	v_mfma_f32_16x16x32_bf16 v[78:81], v[152:155], v[218:221], v[78:81]
	v_mfma_f32_16x16x32_bf16 v[74:77], v[168:171], v[218:221], v[74:77]
	v_mfma_f32_16x16x32_bf16 v[118:121], v[172:175], v[188:191], 0
	v_mfma_f32_16x16x32_bf16 v[114:117], v[180:183], v[188:191], 0
	v_mfma_f32_16x16x32_bf16 v[102:105], v[172:175], v[198:201], 0
	v_mfma_f32_16x16x32_bf16 v[98:101], v[180:183], v[198:201], 0
	v_mfma_f32_16x16x32_bf16 v[86:89], v[172:175], v[206:209], 0
	v_mfma_f32_16x16x32_bf16 v[82:85], v[180:183], v[206:209], 0
	v_mfma_f32_16x16x32_bf16 v[70:73], v[172:175], v[214:217], 0
	v_mfma_f32_16x16x32_bf16 v[66:69], v[180:183], v[214:217], 0
	v_mfma_f32_16x16x32_bf16 v[118:121], v[176:179], v[192:195], v[118:121]
	v_mfma_f32_16x16x32_bf16 v[114:117], v[184:187], v[192:195], v[114:117]
	v_mfma_f32_16x16x32_bf16 v[102:105], v[176:179], v[202:205], v[102:105]
	v_mfma_f32_16x16x32_bf16 v[98:101], v[184:187], v[202:205], v[98:101]
	v_mfma_f32_16x16x32_bf16 v[86:89], v[176:179], v[210:213], v[86:89]
	v_mfma_f32_16x16x32_bf16 v[82:85], v[184:187], v[210:213], v[82:85]
	v_mfma_f32_16x16x32_bf16 v[70:73], v[176:179], v[218:221], v[70:73]
	v_mfma_f32_16x16x32_bf16 v[66:69], v[184:187], v[218:221], v[66:69]
	s_barrier
	s_setprio 0
	s_add_i32 s79, s74, s33
	s_mov_b32 m0, s79
	ds_read_b128 v[188:191], v161 offset:16384
	ds_read_b128 v[192:195], v161 offset:17408
	ds_read_b128 v[198:201], v161 offset:18432
	ds_read_b128 v[202:205], v161 offset:19456
	ds_read_b128 v[206:209], v161 offset:20480
	ds_read_b128 v[210:213], v161 offset:21504
	ds_read_b128 v[214:217], v161 offset:22528
	ds_read_b128 v[218:221], v161 offset:23552
	global_load_lds_dwordx4 v132, s[60:61]
	s_add_i32 m0, s79, 0x2000
	s_add_u32 s80, s60, 0x100000
	s_addc_u32 s81, s61, 0
	s_add_i32 s79, s75, s33
	global_load_lds_dwordx4 v136, s[60:61]
	s_mov_b32 m0, s79
	global_load_lds_dwordx4 v132, s[80:81]
	s_add_i32 m0, s79, 0x2000
	s_nop 0
	global_load_lds_dwordx4 v136, s[80:81]
	s_mov_b32 m0, s64
	s_nop 0
	global_load_lds_dwordx4 v130, s[62:63]
	s_mov_b32 m0, s65
	s_nop 0
	global_load_lds_dwordx4 v134, s[62:63]
	s_waitcnt vmcnt(32)
	s_waitcnt lgkmcnt(0)
	s_setprio 1
	s_barrier
	v_mfma_f32_16x16x32_bf16 v[62:65], v[148:151], v[188:191], 0
	v_mfma_f32_16x16x32_bf16 v[58:61], v[164:167], v[188:191], 0
	v_mfma_f32_16x16x32_bf16 v[46:49], v[148:151], v[198:201], 0
	v_mfma_f32_16x16x32_bf16 v[42:45], v[164:167], v[198:201], 0
	v_mfma_f32_16x16x32_bf16 v[30:33], v[148:151], v[206:209], 0
	v_mfma_f32_16x16x32_bf16 v[26:29], v[164:167], v[206:209], 0
	v_mfma_f32_16x16x32_bf16 v[14:17], v[148:151], v[214:217], 0
	v_mfma_f32_16x16x32_bf16 v[10:13], v[164:167], v[214:217], 0
	v_mfma_f32_16x16x32_bf16 v[62:65], v[152:155], v[192:195], v[62:65]
	v_mfma_f32_16x16x32_bf16 v[58:61], v[168:171], v[192:195], v[58:61]
	v_mfma_f32_16x16x32_bf16 v[46:49], v[152:155], v[202:205], v[46:49]
	v_mfma_f32_16x16x32_bf16 v[42:45], v[168:171], v[202:205], v[42:45]
	v_mfma_f32_16x16x32_bf16 v[30:33], v[152:155], v[210:213], v[30:33]
	v_mfma_f32_16x16x32_bf16 v[26:29], v[168:171], v[210:213], v[26:29]
	v_mfma_f32_16x16x32_bf16 v[14:17], v[152:155], v[218:221], v[14:17]
	v_mfma_f32_16x16x32_bf16 v[10:13], v[168:171], v[218:221], v[10:13]
	v_mfma_f32_16x16x32_bf16 v[54:57], v[172:175], v[188:191], 0
	v_mfma_f32_16x16x32_bf16 v[50:53], v[180:183], v[188:191], 0
	v_mfma_f32_16x16x32_bf16 v[38:41], v[172:175], v[198:201], 0
	v_mfma_f32_16x16x32_bf16 v[34:37], v[180:183], v[198:201], 0
	v_mfma_f32_16x16x32_bf16 v[22:25], v[172:175], v[206:209], 0
	v_mfma_f32_16x16x32_bf16 v[18:21], v[180:183], v[206:209], 0
	v_mfma_f32_16x16x32_bf16 v[6:9], v[172:175], v[214:217], 0
	v_mfma_f32_16x16x32_bf16 v[2:5], v[180:183], v[214:217], 0
	v_mfma_f32_16x16x32_bf16 v[54:57], v[176:179], v[192:195], v[54:57]
	v_mfma_f32_16x16x32_bf16 v[50:53], v[184:187], v[192:195], v[50:53]
	v_mfma_f32_16x16x32_bf16 v[38:41], v[176:179], v[202:205], v[38:41]
	v_mfma_f32_16x16x32_bf16 v[34:37], v[184:187], v[202:205], v[34:37]
	v_mfma_f32_16x16x32_bf16 v[22:25], v[176:179], v[210:213], v[22:25]
	v_mfma_f32_16x16x32_bf16 v[18:21], v[184:187], v[210:213], v[18:21]
	v_mfma_f32_16x16x32_bf16 v[6:9], v[176:179], v[218:221], v[6:9]
	v_mfma_f32_16x16x32_bf16 v[2:5], v[184:187], v[218:221], v[2:5]
	s_barrier
	s_setprio 0
	s_add_i32 s79, 0, 0x18000
	v_add_u32_e32 v138, s79, v157
	s_add_i32 s80, 0, 0x1c000
	ds_read_b128 v[148:151], v138
	ds_read_b128 v[152:155], v138 offset:1024
	ds_read_b128 v[164:167], v138 offset:2048
	ds_read_b128 v[168:171], v138 offset:3072
	v_add_u32_e32 v138, s80, v157
	ds_read_b128 v[172:175], v138
	ds_read_b128 v[176:179], v138 offset:1024
	ds_read_b128 v[180:183], v138 offset:2048
	ds_read_b128 v[184:187], v138 offset:3072
	s_add_u32 s62, s62, 0x100000
	s_addc_u32 s63, s63, 0
	s_mov_b32 m0, s66
	ds_read_b128 v[188:191], v161 offset:32768
	ds_read_b128 v[192:195], v161 offset:33792
	ds_read_b128 v[198:201], v161 offset:34816
	ds_read_b128 v[202:205], v161 offset:35840
	ds_read_b128 v[206:209], v161 offset:36864
	ds_read_b128 v[210:213], v161 offset:37888
	ds_read_b128 v[214:217], v161 offset:38912
	ds_read_b128 v[218:221], v161 offset:39936
	global_load_lds_dwordx4 v130, s[62:63]
	s_mov_b32 m0, s67
	s_nop 0
	global_load_lds_dwordx4 v134, s[62:63]
	s_waitcnt vmcnt(8)
	s_waitcnt lgkmcnt(0)
	s_setprio 1
	s_barrier
	v_mfma_f32_16x16x32_bf16 v[126:129], v[148:151], v[188:191], v[126:129]
	v_mfma_f32_16x16x32_bf16 v[122:125], v[164:167], v[188:191], v[122:125]
	v_mfma_f32_16x16x32_bf16 v[110:113], v[148:151], v[198:201], v[110:113]
	v_mfma_f32_16x16x32_bf16 v[106:109], v[164:167], v[198:201], v[106:109]
	v_mfma_f32_16x16x32_bf16 v[94:97], v[148:151], v[206:209], v[94:97]
	v_mfma_f32_16x16x32_bf16 v[90:93], v[164:167], v[206:209], v[90:93]
	v_mfma_f32_16x16x32_bf16 v[78:81], v[148:151], v[214:217], v[78:81]
	v_mfma_f32_16x16x32_bf16 v[74:77], v[164:167], v[214:217], v[74:77]
	v_mfma_f32_16x16x32_bf16 v[126:129], v[152:155], v[192:195], v[126:129]
	v_mfma_f32_16x16x32_bf16 v[122:125], v[168:171], v[192:195], v[122:125]
	v_mfma_f32_16x16x32_bf16 v[110:113], v[152:155], v[202:205], v[110:113]
	v_mfma_f32_16x16x32_bf16 v[106:109], v[168:171], v[202:205], v[106:109]
	v_mfma_f32_16x16x32_bf16 v[94:97], v[152:155], v[210:213], v[94:97]
	v_mfma_f32_16x16x32_bf16 v[90:93], v[168:171], v[210:213], v[90:93]
	v_mfma_f32_16x16x32_bf16 v[78:81], v[152:155], v[218:221], v[78:81]
	v_mfma_f32_16x16x32_bf16 v[74:77], v[168:171], v[218:221], v[74:77]
	v_mfma_f32_16x16x32_bf16 v[118:121], v[172:175], v[188:191], v[118:121]
	v_mfma_f32_16x16x32_bf16 v[114:117], v[180:183], v[188:191], v[114:117]
	v_mfma_f32_16x16x32_bf16 v[102:105], v[172:175], v[198:201], v[102:105]
	v_mfma_f32_16x16x32_bf16 v[98:101], v[180:183], v[198:201], v[98:101]
	v_mfma_f32_16x16x32_bf16 v[86:89], v[172:175], v[206:209], v[86:89]
	v_mfma_f32_16x16x32_bf16 v[82:85], v[180:183], v[206:209], v[82:85]
	v_mfma_f32_16x16x32_bf16 v[70:73], v[172:175], v[214:217], v[70:73]
	v_mfma_f32_16x16x32_bf16 v[66:69], v[180:183], v[214:217], v[66:69]
	v_mfma_f32_16x16x32_bf16 v[118:121], v[176:179], v[192:195], v[118:121]
	v_mfma_f32_16x16x32_bf16 v[114:117], v[184:187], v[192:195], v[114:117]
	v_mfma_f32_16x16x32_bf16 v[102:105], v[176:179], v[202:205], v[102:105]
	v_mfma_f32_16x16x32_bf16 v[98:101], v[184:187], v[202:205], v[98:101]
	v_mfma_f32_16x16x32_bf16 v[86:89], v[176:179], v[210:213], v[86:89]
	v_mfma_f32_16x16x32_bf16 v[82:85], v[184:187], v[210:213], v[82:85]
	v_mfma_f32_16x16x32_bf16 v[70:73], v[176:179], v[218:221], v[70:73]
	v_mfma_f32_16x16x32_bf16 v[66:69], v[184:187], v[218:221], v[66:69]
	s_barrier
	s_setprio 0
	s_add_u32 s60, s60, 0x80
	s_addc_u32 s61, s61, 0
	s_add_i32 m0, s33, 0x18000
	ds_read_b128 v[188:191], v161 offset:49152
	ds_read_b128 v[192:195], v161 offset:50176
	ds_read_b128 v[198:201], v161 offset:51200
	ds_read_b128 v[202:205], v161 offset:52224
	ds_read_b128 v[206:209], v161 offset:53248
	ds_read_b128 v[210:213], v161 offset:54272
	ds_read_b128 v[214:217], v161 offset:55296
	ds_read_b128 v[218:221], v161 offset:56320
	global_load_lds_dwordx4 v132, s[60:61]
	s_add_i32 m0, s33, 0x1a000
	s_add_u32 s62, s62, 0xfff00080
	global_load_lds_dwordx4 v136, s[60:61]
	s_addc_u32 s63, s63, -1
	s_add_u32 s60, s60, 0x100000
	s_addc_u32 s61, s61, 0
	s_add_i32 m0, s33, 0x1c000
	s_nop 0
	global_load_lds_dwordx4 v132, s[60:61]
	s_add_i32 m0, s33, 0x1e000
	s_nop 0
	global_load_lds_dwordx4 v136, s[60:61]
	s_mov_b32 m0, s69
	s_nop 0
	global_load_lds_dwordx4 v130, s[62:63]
	s_mov_b32 m0, s70
	s_nop 0
	global_load_lds_dwordx4 v134, s[62:63]
	s_add_i32 s78, s78, 2
	s_add_u32 s58, s58, 0x100
	s_addc_u32 s59, s59, 0
	s_add_u32 s76, s76, 0x100
	s_addc_u32 s77, s77, 0
	s_cmp_gt_u32 s78, 61
	s_waitcnt vmcnt(8)
	s_waitcnt lgkmcnt(0)
	s_setprio 1
	s_barrier
	v_mfma_f32_16x16x32_bf16 v[62:65], v[148:151], v[188:191], v[62:65]
	v_mfma_f32_16x16x32_bf16 v[58:61], v[164:167], v[188:191], v[58:61]
	v_mfma_f32_16x16x32_bf16 v[46:49], v[148:151], v[198:201], v[46:49]
	v_mfma_f32_16x16x32_bf16 v[42:45], v[164:167], v[198:201], v[42:45]
	v_mfma_f32_16x16x32_bf16 v[30:33], v[148:151], v[206:209], v[30:33]
	v_mfma_f32_16x16x32_bf16 v[26:29], v[164:167], v[206:209], v[26:29]
	v_mfma_f32_16x16x32_bf16 v[14:17], v[148:151], v[214:217], v[14:17]
	v_mfma_f32_16x16x32_bf16 v[10:13], v[164:167], v[214:217], v[10:13]
	v_mfma_f32_16x16x32_bf16 v[62:65], v[152:155], v[192:195], v[62:65]
	v_mfma_f32_16x16x32_bf16 v[58:61], v[168:171], v[192:195], v[58:61]
	v_mfma_f32_16x16x32_bf16 v[46:49], v[152:155], v[202:205], v[46:49]
	v_mfma_f32_16x16x32_bf16 v[42:45], v[168:171], v[202:205], v[42:45]
	v_mfma_f32_16x16x32_bf16 v[30:33], v[152:155], v[210:213], v[30:33]
	v_mfma_f32_16x16x32_bf16 v[26:29], v[168:171], v[210:213], v[26:29]
	v_mfma_f32_16x16x32_bf16 v[14:17], v[152:155], v[218:221], v[14:17]
	v_mfma_f32_16x16x32_bf16 v[10:13], v[168:171], v[218:221], v[10:13]
	v_mfma_f32_16x16x32_bf16 v[54:57], v[172:175], v[188:191], v[54:57]
	v_mfma_f32_16x16x32_bf16 v[50:53], v[180:183], v[188:191], v[50:53]
	v_mfma_f32_16x16x32_bf16 v[38:41], v[172:175], v[198:201], v[38:41]
	v_mfma_f32_16x16x32_bf16 v[34:37], v[180:183], v[198:201], v[34:37]
	v_mfma_f32_16x16x32_bf16 v[22:25], v[172:175], v[206:209], v[22:25]
	v_mfma_f32_16x16x32_bf16 v[18:21], v[180:183], v[206:209], v[18:21]
	v_mfma_f32_16x16x32_bf16 v[6:9], v[172:175], v[214:217], v[6:9]
	v_mfma_f32_16x16x32_bf16 v[2:5], v[180:183], v[214:217], v[2:5]
	v_mfma_f32_16x16x32_bf16 v[54:57], v[176:179], v[192:195], v[54:57]
	v_mfma_f32_16x16x32_bf16 v[50:53], v[184:187], v[192:195], v[50:53]
	v_mfma_f32_16x16x32_bf16 v[38:41], v[176:179], v[202:205], v[38:41]
	v_mfma_f32_16x16x32_bf16 v[34:37], v[184:187], v[202:205], v[34:37]
	v_mfma_f32_16x16x32_bf16 v[22:25], v[176:179], v[210:213], v[22:25]
	v_mfma_f32_16x16x32_bf16 v[18:21], v[184:187], v[210:213], v[18:21]
	v_mfma_f32_16x16x32_bf16 v[6:9], v[176:179], v[218:221], v[6:9]
	v_mfma_f32_16x16x32_bf16 v[2:5], v[184:187], v[218:221], v[2:5]
	s_barrier
	s_setprio 0
	.p2align	8
.LBB0_678:
	ds_read_b128 v[148:151], v159
	ds_read_b128 v[152:155], v159 offset:1024
	ds_read_b128 v[164:167], v159 offset:2048
	ds_read_b128 v[168:171], v159 offset:3072
	ds_read_b128 v[172:175], v160
	ds_read_b128 v[176:179], v160 offset:1024
	ds_read_b128 v[180:183], v160 offset:2048
	ds_read_b128 v[184:187], v160 offset:3072
	s_add_u32 s60, s58, 0xfff00080
	s_addc_u32 s61, s59, -1
	s_cmp_eq_u32 s78, 60
	s_cselect_b32 s63, s7, s61
	s_cselect_b32 s62, s47, s60
	s_cselect_b32 s61, s45, s77
	s_cselect_b32 s60, s57, s76
	s_add_i32 m0, s64, 0xc000
	ds_read_b128 v[188:191], v161
	ds_read_b128 v[192:195], v161 offset:1024
	ds_read_b128 v[198:201], v161 offset:2048
	ds_read_b128 v[202:205], v161 offset:3072
	ds_read_b128 v[206:209], v161 offset:4096
	ds_read_b128 v[210:213], v161 offset:5120
	ds_read_b128 v[214:217], v161 offset:6144
	ds_read_b128 v[218:221], v161 offset:7168
	global_load_lds_dwordx4 v140, s[58:59]
	s_add_i32 m0, s64, 0xe000
	s_nop 0
	global_load_lds_dwordx4 v142, s[58:59]
	s_waitcnt vmcnt(8)
	s_waitcnt lgkmcnt(0)
	s_setprio 1
	s_barrier
	v_mfma_f32_16x16x32_bf16 v[126:129], v[148:151], v[188:191], v[126:129]
	v_mfma_f32_16x16x32_bf16 v[122:125], v[164:167], v[188:191], v[122:125]
	v_mfma_f32_16x16x32_bf16 v[110:113], v[148:151], v[198:201], v[110:113]
	v_mfma_f32_16x16x32_bf16 v[106:109], v[164:167], v[198:201], v[106:109]
	v_mfma_f32_16x16x32_bf16 v[94:97], v[148:151], v[206:209], v[94:97]
	v_mfma_f32_16x16x32_bf16 v[90:93], v[164:167], v[206:209], v[90:93]
	v_mfma_f32_16x16x32_bf16 v[78:81], v[148:151], v[214:217], v[78:81]
	v_mfma_f32_16x16x32_bf16 v[74:77], v[164:167], v[214:217], v[74:77]
	v_mfma_f32_16x16x32_bf16 v[126:129], v[152:155], v[192:195], v[126:129]
	v_mfma_f32_16x16x32_bf16 v[122:125], v[168:171], v[192:195], v[122:125]
	v_mfma_f32_16x16x32_bf16 v[110:113], v[152:155], v[202:205], v[110:113]
	v_mfma_f32_16x16x32_bf16 v[106:109], v[168:171], v[202:205], v[106:109]
	v_mfma_f32_16x16x32_bf16 v[94:97], v[152:155], v[210:213], v[94:97]
	v_mfma_f32_16x16x32_bf16 v[90:93], v[168:171], v[210:213], v[90:93]
	v_mfma_f32_16x16x32_bf16 v[78:81], v[152:155], v[218:221], v[78:81]
	v_mfma_f32_16x16x32_bf16 v[74:77], v[168:171], v[218:221], v[74:77]
	v_mfma_f32_16x16x32_bf16 v[118:121], v[172:175], v[188:191], v[118:121]
	v_mfma_f32_16x16x32_bf16 v[114:117], v[180:183], v[188:191], v[114:117]
	v_mfma_f32_16x16x32_bf16 v[102:105], v[172:175], v[198:201], v[102:105]
	v_mfma_f32_16x16x32_bf16 v[98:101], v[180:183], v[198:201], v[98:101]
	v_mfma_f32_16x16x32_bf16 v[86:89], v[172:175], v[206:209], v[86:89]
	v_mfma_f32_16x16x32_bf16 v[82:85], v[180:183], v[206:209], v[82:85]
	v_mfma_f32_16x16x32_bf16 v[70:73], v[172:175], v[214:217], v[70:73]
	v_mfma_f32_16x16x32_bf16 v[66:69], v[180:183], v[214:217], v[66:69]
	v_mfma_f32_16x16x32_bf16 v[118:121], v[176:179], v[192:195], v[118:121]
	v_mfma_f32_16x16x32_bf16 v[114:117], v[184:187], v[192:195], v[114:117]
	v_mfma_f32_16x16x32_bf16 v[102:105], v[176:179], v[202:205], v[102:105]
	v_mfma_f32_16x16x32_bf16 v[98:101], v[184:187], v[202:205], v[98:101]
	v_mfma_f32_16x16x32_bf16 v[86:89], v[176:179], v[210:213], v[86:89]
	v_mfma_f32_16x16x32_bf16 v[82:85], v[184:187], v[210:213], v[82:85]
	v_mfma_f32_16x16x32_bf16 v[70:73], v[176:179], v[218:221], v[70:73]
	v_mfma_f32_16x16x32_bf16 v[66:69], v[184:187], v[218:221], v[66:69]
	s_barrier
	s_setprio 0
	s_add_i32 s79, s74, s33
	s_mov_b32 m0, s79
	ds_read_b128 v[188:191], v161 offset:16384
	ds_read_b128 v[192:195], v161 offset:17408
	ds_read_b128 v[198:201], v161 offset:18432
	ds_read_b128 v[202:205], v161 offset:19456
	ds_read_b128 v[206:209], v161 offset:20480
	ds_read_b128 v[210:213], v161 offset:21504
	ds_read_b128 v[214:217], v161 offset:22528
	ds_read_b128 v[218:221], v161 offset:23552
	global_load_lds_dwordx4 v132, s[60:61]
	s_add_i32 m0, s79, 0x2000
	s_add_u32 s80, s60, 0x100000
	s_addc_u32 s81, s61, 0
	s_add_i32 s79, s75, s33
	global_load_lds_dwordx4 v136, s[60:61]
	s_mov_b32 m0, s79
	global_load_lds_dwordx4 v132, s[80:81]
	s_add_i32 m0, s79, 0x2000
	s_nop 0
	global_load_lds_dwordx4 v136, s[80:81]
	s_mov_b32 m0, s64
	s_nop 0
	global_load_lds_dwordx4 v130, s[62:63]
	s_mov_b32 m0, s65
	s_nop 0
	global_load_lds_dwordx4 v134, s[62:63]
	s_waitcnt vmcnt(8)
	s_waitcnt lgkmcnt(0)
	s_setprio 1
	s_barrier
	v_mfma_f32_16x16x32_bf16 v[62:65], v[148:151], v[188:191], v[62:65]
	v_mfma_f32_16x16x32_bf16 v[58:61], v[164:167], v[188:191], v[58:61]
	v_mfma_f32_16x16x32_bf16 v[46:49], v[148:151], v[198:201], v[46:49]
	v_mfma_f32_16x16x32_bf16 v[42:45], v[164:167], v[198:201], v[42:45]
	v_mfma_f32_16x16x32_bf16 v[30:33], v[148:151], v[206:209], v[30:33]
	v_mfma_f32_16x16x32_bf16 v[26:29], v[164:167], v[206:209], v[26:29]
	v_mfma_f32_16x16x32_bf16 v[14:17], v[148:151], v[214:217], v[14:17]
	v_mfma_f32_16x16x32_bf16 v[10:13], v[164:167], v[214:217], v[10:13]
	v_mfma_f32_16x16x32_bf16 v[62:65], v[152:155], v[192:195], v[62:65]
	v_mfma_f32_16x16x32_bf16 v[58:61], v[168:171], v[192:195], v[58:61]
	v_mfma_f32_16x16x32_bf16 v[46:49], v[152:155], v[202:205], v[46:49]
	v_mfma_f32_16x16x32_bf16 v[42:45], v[168:171], v[202:205], v[42:45]
	v_mfma_f32_16x16x32_bf16 v[30:33], v[152:155], v[210:213], v[30:33]
	v_mfma_f32_16x16x32_bf16 v[26:29], v[168:171], v[210:213], v[26:29]
	v_mfma_f32_16x16x32_bf16 v[14:17], v[152:155], v[218:221], v[14:17]
	v_mfma_f32_16x16x32_bf16 v[10:13], v[168:171], v[218:221], v[10:13]
	v_mfma_f32_16x16x32_bf16 v[54:57], v[172:175], v[188:191], v[54:57]
	v_mfma_f32_16x16x32_bf16 v[50:53], v[180:183], v[188:191], v[50:53]
	v_mfma_f32_16x16x32_bf16 v[38:41], v[172:175], v[198:201], v[38:41]
	v_mfma_f32_16x16x32_bf16 v[34:37], v[180:183], v[198:201], v[34:37]
	v_mfma_f32_16x16x32_bf16 v[22:25], v[172:175], v[206:209], v[22:25]
	v_mfma_f32_16x16x32_bf16 v[18:21], v[180:183], v[206:209], v[18:21]
	v_mfma_f32_16x16x32_bf16 v[6:9], v[172:175], v[214:217], v[6:9]
	v_mfma_f32_16x16x32_bf16 v[2:5], v[180:183], v[214:217], v[2:5]
	v_mfma_f32_16x16x32_bf16 v[54:57], v[176:179], v[192:195], v[54:57]
	v_mfma_f32_16x16x32_bf16 v[50:53], v[184:187], v[192:195], v[50:53]
	v_mfma_f32_16x16x32_bf16 v[38:41], v[176:179], v[202:205], v[38:41]
	v_mfma_f32_16x16x32_bf16 v[34:37], v[184:187], v[202:205], v[34:37]
	v_mfma_f32_16x16x32_bf16 v[22:25], v[176:179], v[210:213], v[22:25]
	v_mfma_f32_16x16x32_bf16 v[18:21], v[184:187], v[210:213], v[18:21]
	v_mfma_f32_16x16x32_bf16 v[6:9], v[176:179], v[218:221], v[6:9]
	v_mfma_f32_16x16x32_bf16 v[2:5], v[184:187], v[218:221], v[2:5]
	s_barrier
	s_setprio 0
	s_add_i32 s79, 0, 0x18000
	v_add_u32_e32 v138, s79, v157
	s_add_i32 s80, 0, 0x1c000
	ds_read_b128 v[148:151], v138
	ds_read_b128 v[152:155], v138 offset:1024
	ds_read_b128 v[164:167], v138 offset:2048
	ds_read_b128 v[168:171], v138 offset:3072
	v_add_u32_e32 v138, s80, v157
	ds_read_b128 v[172:175], v138
	ds_read_b128 v[176:179], v138 offset:1024
	ds_read_b128 v[180:183], v138 offset:2048
	ds_read_b128 v[184:187], v138 offset:3072
	s_add_u32 s62, s62, 0x100000
	s_addc_u32 s63, s63, 0
	s_mov_b32 m0, s66
	ds_read_b128 v[188:191], v161 offset:32768
	ds_read_b128 v[192:195], v161 offset:33792
	ds_read_b128 v[198:201], v161 offset:34816
	ds_read_b128 v[202:205], v161 offset:35840
	ds_read_b128 v[206:209], v161 offset:36864
	ds_read_b128 v[210:213], v161 offset:37888
	ds_read_b128 v[214:217], v161 offset:38912
	ds_read_b128 v[218:221], v161 offset:39936
	global_load_lds_dwordx4 v130, s[62:63]
	s_mov_b32 m0, s67
	s_nop 0
	global_load_lds_dwordx4 v134, s[62:63]
	s_waitcnt vmcnt(8)
	s_waitcnt lgkmcnt(0)
	s_setprio 1
	s_barrier
	v_mfma_f32_16x16x32_bf16 v[126:129], v[148:151], v[188:191], v[126:129]
	v_mfma_f32_16x16x32_bf16 v[122:125], v[164:167], v[188:191], v[122:125]
	v_mfma_f32_16x16x32_bf16 v[110:113], v[148:151], v[198:201], v[110:113]
	v_mfma_f32_16x16x32_bf16 v[106:109], v[164:167], v[198:201], v[106:109]
	v_mfma_f32_16x16x32_bf16 v[94:97], v[148:151], v[206:209], v[94:97]
	v_mfma_f32_16x16x32_bf16 v[90:93], v[164:167], v[206:209], v[90:93]
	v_mfma_f32_16x16x32_bf16 v[78:81], v[148:151], v[214:217], v[78:81]
	v_mfma_f32_16x16x32_bf16 v[74:77], v[164:167], v[214:217], v[74:77]
	v_mfma_f32_16x16x32_bf16 v[126:129], v[152:155], v[192:195], v[126:129]
	v_mfma_f32_16x16x32_bf16 v[122:125], v[168:171], v[192:195], v[122:125]
	v_mfma_f32_16x16x32_bf16 v[110:113], v[152:155], v[202:205], v[110:113]
	v_mfma_f32_16x16x32_bf16 v[106:109], v[168:171], v[202:205], v[106:109]
	v_mfma_f32_16x16x32_bf16 v[94:97], v[152:155], v[210:213], v[94:97]
	v_mfma_f32_16x16x32_bf16 v[90:93], v[168:171], v[210:213], v[90:93]
	v_mfma_f32_16x16x32_bf16 v[78:81], v[152:155], v[218:221], v[78:81]
	v_mfma_f32_16x16x32_bf16 v[74:77], v[168:171], v[218:221], v[74:77]
	v_mfma_f32_16x16x32_bf16 v[118:121], v[172:175], v[188:191], v[118:121]
	v_mfma_f32_16x16x32_bf16 v[114:117], v[180:183], v[188:191], v[114:117]
	v_mfma_f32_16x16x32_bf16 v[102:105], v[172:175], v[198:201], v[102:105]
	v_mfma_f32_16x16x32_bf16 v[98:101], v[180:183], v[198:201], v[98:101]
	v_mfma_f32_16x16x32_bf16 v[86:89], v[172:175], v[206:209], v[86:89]
	v_mfma_f32_16x16x32_bf16 v[82:85], v[180:183], v[206:209], v[82:85]
	v_mfma_f32_16x16x32_bf16 v[70:73], v[172:175], v[214:217], v[70:73]
	v_mfma_f32_16x16x32_bf16 v[66:69], v[180:183], v[214:217], v[66:69]
	v_mfma_f32_16x16x32_bf16 v[118:121], v[176:179], v[192:195], v[118:121]
	v_mfma_f32_16x16x32_bf16 v[114:117], v[184:187], v[192:195], v[114:117]
	v_mfma_f32_16x16x32_bf16 v[102:105], v[176:179], v[202:205], v[102:105]
	v_mfma_f32_16x16x32_bf16 v[98:101], v[184:187], v[202:205], v[98:101]
	v_mfma_f32_16x16x32_bf16 v[86:89], v[176:179], v[210:213], v[86:89]
	v_mfma_f32_16x16x32_bf16 v[82:85], v[184:187], v[210:213], v[82:85]
	v_mfma_f32_16x16x32_bf16 v[70:73], v[176:179], v[218:221], v[70:73]
	v_mfma_f32_16x16x32_bf16 v[66:69], v[184:187], v[218:221], v[66:69]
	s_barrier
	s_setprio 0
	s_add_u32 s60, s60, 0x80
	s_addc_u32 s61, s61, 0
	s_add_i32 m0, s33, 0x18000
	ds_read_b128 v[188:191], v161 offset:49152
	ds_read_b128 v[192:195], v161 offset:50176
	ds_read_b128 v[198:201], v161 offset:51200
	ds_read_b128 v[202:205], v161 offset:52224
	ds_read_b128 v[206:209], v161 offset:53248
	ds_read_b128 v[210:213], v161 offset:54272
	ds_read_b128 v[214:217], v161 offset:55296
	ds_read_b128 v[218:221], v161 offset:56320
	global_load_lds_dwordx4 v132, s[60:61]
	s_add_i32 m0, s33, 0x1a000
	s_add_u32 s62, s62, 0xfff00080
	global_load_lds_dwordx4 v136, s[60:61]
	s_addc_u32 s63, s63, -1
	s_add_u32 s60, s60, 0x100000
	s_addc_u32 s61, s61, 0
	s_add_i32 m0, s33, 0x1c000
	s_nop 0
	global_load_lds_dwordx4 v132, s[60:61]
	s_add_i32 m0, s33, 0x1e000
	s_nop 0
	global_load_lds_dwordx4 v136, s[60:61]
	s_mov_b32 m0, s69
	s_nop 0
	global_load_lds_dwordx4 v130, s[62:63]
	s_mov_b32 m0, s70
	s_nop 0
	global_load_lds_dwordx4 v134, s[62:63]
	s_add_i32 s78, s78, 2
	s_add_u32 s58, s58, 0x100
	s_addc_u32 s59, s59, 0
	s_add_u32 s76, s76, 0x100
	s_addc_u32 s77, s77, 0
	s_cmp_gt_u32 s78, 61
	s_waitcnt vmcnt(8)
	s_waitcnt lgkmcnt(0)
	s_setprio 1
	s_barrier
	v_mfma_f32_16x16x32_bf16 v[62:65], v[148:151], v[188:191], v[62:65]
	v_mfma_f32_16x16x32_bf16 v[58:61], v[164:167], v[188:191], v[58:61]
	v_mfma_f32_16x16x32_bf16 v[46:49], v[148:151], v[198:201], v[46:49]
	v_mfma_f32_16x16x32_bf16 v[42:45], v[164:167], v[198:201], v[42:45]
	v_mfma_f32_16x16x32_bf16 v[30:33], v[148:151], v[206:209], v[30:33]
	v_mfma_f32_16x16x32_bf16 v[26:29], v[164:167], v[206:209], v[26:29]
	v_mfma_f32_16x16x32_bf16 v[14:17], v[148:151], v[214:217], v[14:17]
	v_mfma_f32_16x16x32_bf16 v[10:13], v[164:167], v[214:217], v[10:13]
	v_mfma_f32_16x16x32_bf16 v[62:65], v[152:155], v[192:195], v[62:65]
	v_mfma_f32_16x16x32_bf16 v[58:61], v[168:171], v[192:195], v[58:61]
	v_mfma_f32_16x16x32_bf16 v[46:49], v[152:155], v[202:205], v[46:49]
	v_mfma_f32_16x16x32_bf16 v[42:45], v[168:171], v[202:205], v[42:45]
	v_mfma_f32_16x16x32_bf16 v[30:33], v[152:155], v[210:213], v[30:33]
	v_mfma_f32_16x16x32_bf16 v[26:29], v[168:171], v[210:213], v[26:29]
	v_mfma_f32_16x16x32_bf16 v[14:17], v[152:155], v[218:221], v[14:17]
	v_mfma_f32_16x16x32_bf16 v[10:13], v[168:171], v[218:221], v[10:13]
	v_mfma_f32_16x16x32_bf16 v[54:57], v[172:175], v[188:191], v[54:57]
	v_mfma_f32_16x16x32_bf16 v[50:53], v[180:183], v[188:191], v[50:53]
	v_mfma_f32_16x16x32_bf16 v[38:41], v[172:175], v[198:201], v[38:41]
	v_mfma_f32_16x16x32_bf16 v[34:37], v[180:183], v[198:201], v[34:37]
	v_mfma_f32_16x16x32_bf16 v[22:25], v[172:175], v[206:209], v[22:25]
	v_mfma_f32_16x16x32_bf16 v[18:21], v[180:183], v[206:209], v[18:21]
	v_mfma_f32_16x16x32_bf16 v[6:9], v[172:175], v[214:217], v[6:9]
	v_mfma_f32_16x16x32_bf16 v[2:5], v[180:183], v[214:217], v[2:5]
	v_mfma_f32_16x16x32_bf16 v[54:57], v[176:179], v[192:195], v[54:57]
	v_mfma_f32_16x16x32_bf16 v[50:53], v[184:187], v[192:195], v[50:53]
	v_mfma_f32_16x16x32_bf16 v[38:41], v[176:179], v[202:205], v[38:41]
	v_mfma_f32_16x16x32_bf16 v[34:37], v[184:187], v[202:205], v[34:37]
	v_mfma_f32_16x16x32_bf16 v[22:25], v[176:179], v[210:213], v[22:25]
	v_mfma_f32_16x16x32_bf16 v[18:21], v[184:187], v[210:213], v[18:21]
	v_mfma_f32_16x16x32_bf16 v[6:9], v[176:179], v[218:221], v[6:9]
	v_mfma_f32_16x16x32_bf16 v[2:5], v[184:187], v[218:221], v[2:5]
	s_barrier
	s_setprio 0
	s_cbranch_scc0 .LBB0_678
	s_and_b64 vcc, exec, s[18:19]
	s_cbranch_vccz .LBB0_681
	s_barrier

.LBB0_806:
	s_ashr_i32 s35, s34, 31
	s_lshl_b64 s[36:37], s[34:35], 21
	s_add_u32 s36, s8, s36
	s_addc_u32 s37, s9, s37
	s_and_b64 s[38:39], s[0:1], exec
	s_cselect_b32 s35, s37, s43
	s_cselect_b32 s64, s36, s42
	s_ashr_i32 s31, s30, 31
	s_lshl_b64 s[38:39], s[30:31], 21
	s_add_u32 s38, s76, s38
	s_addc_u32 s39, s77, s39
	s_and_b64 s[46:47], s[0:1], exec
	s_cselect_b32 s31, s39, s45
	s_cselect_b32 s65, s38, s44
	s_add_u32 s42, s42, 0x100080
	s_addc_u32 s43, s43, 0
	s_add_u32 s66, s44, 0x100
	s_addc_u32 s67, s45, 0
	s_mov_b32 s68, -2
	ds_read_b128 v[154:157], v150
	ds_read_b128 v[158:161], v150 offset:1024
	ds_read_b128 v[162:165], v150 offset:2048
	ds_read_b128 v[166:169], v150 offset:3072
	ds_read_b128 v[170:173], v151
	ds_read_b128 v[174:177], v151 offset:1024
	ds_read_b128 v[178:181], v151 offset:2048
	ds_read_b128 v[182:185], v151 offset:3072
	s_add_u32 s44, s42, 0xfff00080
	s_addc_u32 s45, s43, -1
	s_cmp_eq_u32 s68, 60
	s_cselect_b32 s47, s35, s45
	s_cselect_b32 s46, s64, s44
	s_cselect_b32 s45, s31, s67
	s_cselect_b32 s44, s65, s66
	s_add_i32 m0, s41, 0xc000
	ds_read_b128 v[186:189], v152
	ds_read_b128 v[190:193], v152 offset:1024
	ds_read_b128 v[198:201], v152 offset:2048
	ds_read_b128 v[202:205], v152 offset:3072
	ds_read_b128 v[206:209], v152 offset:4096
	ds_read_b128 v[210:213], v152 offset:5120
	ds_read_b128 v[214:217], v152 offset:6144
	ds_read_b128 v[218:221], v152 offset:7168
	global_load_lds_dwordx4 v138, s[42:43]
	s_add_i32 m0, s41, 0xe000
	s_nop 0
	global_load_lds_dwordx4 v140, s[42:43]
	s_waitcnt vmcnt(24)
	s_waitcnt lgkmcnt(0)
	s_setprio 1
	s_barrier
	v_mfma_f32_16x16x32_bf16 v[126:129], v[154:157], v[186:189], 0
	v_mfma_f32_16x16x32_bf16 v[122:125], v[162:165], v[186:189], 0
	v_mfma_f32_16x16x32_bf16 v[110:113], v[154:157], v[198:201], 0
	v_mfma_f32_16x16x32_bf16 v[106:109], v[162:165], v[198:201], 0
	v_mfma_f32_16x16x32_bf16 v[94:97], v[154:157], v[206:209], 0
	v_mfma_f32_16x16x32_bf16 v[90:93], v[162:165], v[206:209], 0
	v_mfma_f32_16x16x32_bf16 v[78:81], v[154:157], v[214:217], 0
	v_mfma_f32_16x16x32_bf16 v[74:77], v[162:165], v[214:217], 0
	v_mfma_f32_16x16x32_bf16 v[126:129], v[158:161], v[190:193], v[126:129]
	v_mfma_f32_16x16x32_bf16 v[122:125], v[166:169], v[190:193], v[122:125]
	v_mfma_f32_16x16x32_bf16 v[110:113], v[158:161], v[202:205], v[110:113]
	v_mfma_f32_16x16x32_bf16 v[106:109], v[166:169], v[202:205], v[106:109]
	v_mfma_f32_16x16x32_bf16 v[94:97], v[158:161], v[210:213], v[94:97]
	v_mfma_f32_16x16x32_bf16 v[90:93], v[166:169], v[210:213], v[90:93]
	v_mfma_f32_16x16x32_bf16 v[78:81], v[158:161], v[218:221], v[78:81]
	v_mfma_f32_16x16x32_bf16 v[74:77], v[166:169], v[218:221], v[74:77]
	v_mfma_f32_16x16x32_bf16 v[118:121], v[170:173], v[186:189], 0
	v_mfma_f32_16x16x32_bf16 v[114:117], v[178:181], v[186:189], 0
	v_mfma_f32_16x16x32_bf16 v[102:105], v[170:173], v[198:201], 0
	v_mfma_f32_16x16x32_bf16 v[98:101], v[178:181], v[198:201], 0
	v_mfma_f32_16x16x32_bf16 v[86:89], v[170:173], v[206:209], 0
	v_mfma_f32_16x16x32_bf16 v[82:85], v[178:181], v[206:209], 0
	v_mfma_f32_16x16x32_bf16 v[70:73], v[170:173], v[214:217], 0
	v_mfma_f32_16x16x32_bf16 v[66:69], v[178:181], v[214:217], 0
	v_mfma_f32_16x16x32_bf16 v[118:121], v[174:177], v[190:193], v[118:121]
	v_mfma_f32_16x16x32_bf16 v[114:117], v[182:185], v[190:193], v[114:117]
	v_mfma_f32_16x16x32_bf16 v[102:105], v[174:177], v[202:205], v[102:105]
	v_mfma_f32_16x16x32_bf16 v[98:101], v[182:185], v[202:205], v[98:101]
	v_mfma_f32_16x16x32_bf16 v[86:89], v[174:177], v[210:213], v[86:89]
	v_mfma_f32_16x16x32_bf16 v[82:85], v[182:185], v[210:213], v[82:85]
	v_mfma_f32_16x16x32_bf16 v[70:73], v[174:177], v[218:221], v[70:73]
	v_mfma_f32_16x16x32_bf16 v[66:69], v[182:185], v[218:221], v[66:69]
	s_barrier
	s_setprio 0
	s_add_i32 s69, s57, s33
	s_mov_b32 m0, s69
	ds_read_b128 v[186:189], v152 offset:16384
	ds_read_b128 v[190:193], v152 offset:17408
	ds_read_b128 v[198:201], v152 offset:18432
	ds_read_b128 v[202:205], v152 offset:19456
	ds_read_b128 v[206:209], v152 offset:20480
	ds_read_b128 v[210:213], v152 offset:21504
	ds_read_b128 v[214:217], v152 offset:22528
	ds_read_b128 v[218:221], v152 offset:23552
	global_load_lds_dwordx4 v132, s[44:45]
	s_add_i32 m0, s69, 0x2000
	s_add_u32 s70, s44, 0x100000
	s_addc_u32 s71, s45, 0
	s_add_i32 s69, s58, s33
	global_load_lds_dwordx4 v136, s[44:45]
	s_mov_b32 m0, s69
	global_load_lds_dwordx4 v132, s[70:71]
	s_add_i32 m0, s69, 0x2000
	s_nop 0
	global_load_lds_dwordx4 v136, s[70:71]
	s_mov_b32 m0, s41
	s_nop 0
	global_load_lds_dwordx4 v130, s[46:47]
	s_mov_b32 m0, s50
	s_nop 0
	global_load_lds_dwordx4 v134, s[46:47]
	s_waitcnt vmcnt(24)
	s_waitcnt lgkmcnt(0)
	s_setprio 1
	s_barrier
	v_mfma_f32_16x16x32_bf16 v[62:65], v[154:157], v[186:189], 0
	v_mfma_f32_16x16x32_bf16 v[58:61], v[162:165], v[186:189], 0
	v_mfma_f32_16x16x32_bf16 v[46:49], v[154:157], v[198:201], 0
	v_mfma_f32_16x16x32_bf16 v[42:45], v[162:165], v[198:201], 0
	v_mfma_f32_16x16x32_bf16 v[30:33], v[154:157], v[206:209], 0
	v_mfma_f32_16x16x32_bf16 v[26:29], v[162:165], v[206:209], 0
	v_mfma_f32_16x16x32_bf16 v[14:17], v[154:157], v[214:217], 0
	v_mfma_f32_16x16x32_bf16 v[10:13], v[162:165], v[214:217], 0
	v_mfma_f32_16x16x32_bf16 v[62:65], v[158:161], v[190:193], v[62:65]
	v_mfma_f32_16x16x32_bf16 v[58:61], v[166:169], v[190:193], v[58:61]
	v_mfma_f32_16x16x32_bf16 v[46:49], v[158:161], v[202:205], v[46:49]
	v_mfma_f32_16x16x32_bf16 v[42:45], v[166:169], v[202:205], v[42:45]
	v_mfma_f32_16x16x32_bf16 v[30:33], v[158:161], v[210:213], v[30:33]
	v_mfma_f32_16x16x32_bf16 v[26:29], v[166:169], v[210:213], v[26:29]
	v_mfma_f32_16x16x32_bf16 v[14:17], v[158:161], v[218:221], v[14:17]
	v_mfma_f32_16x16x32_bf16 v[10:13], v[166:169], v[218:221], v[10:13]
	v_mfma_f32_16x16x32_bf16 v[54:57], v[170:173], v[186:189], 0
	v_mfma_f32_16x16x32_bf16 v[50:53], v[178:181], v[186:189], 0
	v_mfma_f32_16x16x32_bf16 v[38:41], v[170:173], v[198:201], 0
	v_mfma_f32_16x16x32_bf16 v[34:37], v[178:181], v[198:201], 0
	v_mfma_f32_16x16x32_bf16 v[22:25], v[170:173], v[206:209], 0
	v_mfma_f32_16x16x32_bf16 v[18:21], v[178:181], v[206:209], 0
	v_mfma_f32_16x16x32_bf16 v[6:9], v[170:173], v[214:217], 0
	v_mfma_f32_16x16x32_bf16 v[2:5], v[178:181], v[214:217], 0
	v_mfma_f32_16x16x32_bf16 v[54:57], v[174:177], v[190:193], v[54:57]
	v_mfma_f32_16x16x32_bf16 v[50:53], v[182:185], v[190:193], v[50:53]
	v_mfma_f32_16x16x32_bf16 v[38:41], v[174:177], v[202:205], v[38:41]
	v_mfma_f32_16x16x32_bf16 v[34:37], v[182:185], v[202:205], v[34:37]
	v_mfma_f32_16x16x32_bf16 v[22:25], v[174:177], v[210:213], v[22:25]
	v_mfma_f32_16x16x32_bf16 v[18:21], v[182:185], v[210:213], v[18:21]
	v_mfma_f32_16x16x32_bf16 v[6:9], v[174:177], v[218:221], v[6:9]
	v_mfma_f32_16x16x32_bf16 v[2:5], v[182:185], v[218:221], v[2:5]
	s_barrier
	s_setprio 0
	s_add_i32 s69, 0, 0x18000
	v_add_u32_e32 v153, s69, v148
	s_add_i32 s70, 0, 0x1c000
	ds_read_b128 v[154:157], v153
	ds_read_b128 v[158:161], v153 offset:1024
	ds_read_b128 v[162:165], v153 offset:2048
	ds_read_b128 v[166:169], v153 offset:3072
	v_add_u32_e32 v153, s70, v148
	ds_read_b128 v[170:173], v153
	ds_read_b128 v[174:177], v153 offset:1024
	ds_read_b128 v[178:181], v153 offset:2048
	ds_read_b128 v[182:185], v153 offset:3072
	s_add_u32 s46, s46, 0x100000
	s_addc_u32 s47, s47, 0
	s_mov_b32 m0, s51
	ds_read_b128 v[186:189], v152 offset:32768
	ds_read_b128 v[190:193], v152 offset:33792
	ds_read_b128 v[198:201], v152 offset:34816
	ds_read_b128 v[202:205], v152 offset:35840
	ds_read_b128 v[206:209], v152 offset:36864
	ds_read_b128 v[210:213], v152 offset:37888
	ds_read_b128 v[214:217], v152 offset:38912
	ds_read_b128 v[218:221], v152 offset:39936
	global_load_lds_dwordx4 v130, s[46:47]
	s_mov_b32 m0, s52
	s_nop 0
	global_load_lds_dwordx4 v134, s[46:47]
	s_waitcnt vmcnt(8)
	s_waitcnt lgkmcnt(0)
	s_setprio 1
	s_barrier
	v_mfma_f32_16x16x32_bf16 v[126:129], v[154:157], v[186:189], v[126:129]
	v_mfma_f32_16x16x32_bf16 v[122:125], v[162:165], v[186:189], v[122:125]
	v_mfma_f32_16x16x32_bf16 v[110:113], v[154:157], v[198:201], v[110:113]
	v_mfma_f32_16x16x32_bf16 v[106:109], v[162:165], v[198:201], v[106:109]
	v_mfma_f32_16x16x32_bf16 v[94:97], v[154:157], v[206:209], v[94:97]
	v_mfma_f32_16x16x32_bf16 v[90:93], v[162:165], v[206:209], v[90:93]
	v_mfma_f32_16x16x32_bf16 v[78:81], v[154:157], v[214:217], v[78:81]
	v_mfma_f32_16x16x32_bf16 v[74:77], v[162:165], v[214:217], v[74:77]
	v_mfma_f32_16x16x32_bf16 v[126:129], v[158:161], v[190:193], v[126:129]
	v_mfma_f32_16x16x32_bf16 v[122:125], v[166:169], v[190:193], v[122:125]
	v_mfma_f32_16x16x32_bf16 v[110:113], v[158:161], v[202:205], v[110:113]
	v_mfma_f32_16x16x32_bf16 v[106:109], v[166:169], v[202:205], v[106:109]
	v_mfma_f32_16x16x32_bf16 v[94:97], v[158:161], v[210:213], v[94:97]
	v_mfma_f32_16x16x32_bf16 v[90:93], v[166:169], v[210:213], v[90:93]
	v_mfma_f32_16x16x32_bf16 v[78:81], v[158:161], v[218:221], v[78:81]
	v_mfma_f32_16x16x32_bf16 v[74:77], v[166:169], v[218:221], v[74:77]
	v_mfma_f32_16x16x32_bf16 v[118:121], v[170:173], v[186:189], v[118:121]
	v_mfma_f32_16x16x32_bf16 v[114:117], v[178:181], v[186:189], v[114:117]
	v_mfma_f32_16x16x32_bf16 v[102:105], v[170:173], v[198:201], v[102:105]
	v_mfma_f32_16x16x32_bf16 v[98:101], v[178:181], v[198:201], v[98:101]
	v_mfma_f32_16x16x32_bf16 v[86:89], v[170:173], v[206:209], v[86:89]
	v_mfma_f32_16x16x32_bf16 v[82:85], v[178:181], v[206:209], v[82:85]
	v_mfma_f32_16x16x32_bf16 v[70:73], v[170:173], v[214:217], v[70:73]
	v_mfma_f32_16x16x32_bf16 v[66:69], v[178:181], v[214:217], v[66:69]
	v_mfma_f32_16x16x32_bf16 v[118:121], v[174:177], v[190:193], v[118:121]
	v_mfma_f32_16x16x32_bf16 v[114:117], v[182:185], v[190:193], v[114:117]
	v_mfma_f32_16x16x32_bf16 v[102:105], v[174:177], v[202:205], v[102:105]
	v_mfma_f32_16x16x32_bf16 v[98:101], v[182:185], v[202:205], v[98:101]
	v_mfma_f32_16x16x32_bf16 v[86:89], v[174:177], v[210:213], v[86:89]
	v_mfma_f32_16x16x32_bf16 v[82:85], v[182:185], v[210:213], v[82:85]
	v_mfma_f32_16x16x32_bf16 v[70:73], v[174:177], v[218:221], v[70:73]
	v_mfma_f32_16x16x32_bf16 v[66:69], v[182:185], v[218:221], v[66:69]
	s_barrier
	s_setprio 0
	s_add_u32 s44, s44, 0x80
	s_addc_u32 s45, s45, 0
	s_add_i32 m0, s33, 0x18000
	ds_read_b128 v[186:189], v152 offset:49152
	ds_read_b128 v[190:193], v152 offset:50176
	ds_read_b128 v[198:201], v152 offset:51200
	ds_read_b128 v[202:205], v152 offset:52224
	ds_read_b128 v[206:209], v152 offset:53248
	ds_read_b128 v[210:213], v152 offset:54272
	ds_read_b128 v[214:217], v152 offset:55296
	ds_read_b128 v[218:221], v152 offset:56320
	global_load_lds_dwordx4 v132, s[44:45]
	s_add_i32 m0, s33, 0x1a000
	s_add_u32 s46, s46, 0xfff00080
	global_load_lds_dwordx4 v136, s[44:45]
	s_addc_u32 s47, s47, -1
	s_add_u32 s44, s44, 0x100000
	s_addc_u32 s45, s45, 0
	s_add_i32 m0, s33, 0x1c000
	s_nop 0
	global_load_lds_dwordx4 v132, s[44:45]
	s_add_i32 m0, s33, 0x1e000
	s_nop 0
	global_load_lds_dwordx4 v136, s[44:45]
	s_mov_b32 m0, s55
	s_nop 0
	global_load_lds_dwordx4 v130, s[46:47]
	s_mov_b32 m0, s56
	s_nop 0
	global_load_lds_dwordx4 v134, s[46:47]
	s_add_i32 s68, s68, 2
	s_add_u32 s42, s42, 0x100
	s_addc_u32 s43, s43, 0
	s_add_u32 s66, s66, 0x100
	s_addc_u32 s67, s67, 0
	s_cmp_gt_u32 s68, 61
	s_waitcnt vmcnt(8)
	s_waitcnt lgkmcnt(0)
	s_setprio 1
	s_barrier
	v_mfma_f32_16x16x32_bf16 v[62:65], v[154:157], v[186:189], v[62:65]
	v_mfma_f32_16x16x32_bf16 v[58:61], v[162:165], v[186:189], v[58:61]
	v_mfma_f32_16x16x32_bf16 v[46:49], v[154:157], v[198:201], v[46:49]
	v_mfma_f32_16x16x32_bf16 v[42:45], v[162:165], v[198:201], v[42:45]
	v_mfma_f32_16x16x32_bf16 v[30:33], v[154:157], v[206:209], v[30:33]
	v_mfma_f32_16x16x32_bf16 v[26:29], v[162:165], v[206:209], v[26:29]
	v_mfma_f32_16x16x32_bf16 v[14:17], v[154:157], v[214:217], v[14:17]
	v_mfma_f32_16x16x32_bf16 v[10:13], v[162:165], v[214:217], v[10:13]
	v_mfma_f32_16x16x32_bf16 v[62:65], v[158:161], v[190:193], v[62:65]
	v_mfma_f32_16x16x32_bf16 v[58:61], v[166:169], v[190:193], v[58:61]
	v_mfma_f32_16x16x32_bf16 v[46:49], v[158:161], v[202:205], v[46:49]
	v_mfma_f32_16x16x32_bf16 v[42:45], v[166:169], v[202:205], v[42:45]
	v_mfma_f32_16x16x32_bf16 v[30:33], v[158:161], v[210:213], v[30:33]
	v_mfma_f32_16x16x32_bf16 v[26:29], v[166:169], v[210:213], v[26:29]
	v_mfma_f32_16x16x32_bf16 v[14:17], v[158:161], v[218:221], v[14:17]
	v_mfma_f32_16x16x32_bf16 v[10:13], v[166:169], v[218:221], v[10:13]
	v_mfma_f32_16x16x32_bf16 v[54:57], v[170:173], v[186:189], v[54:57]
	v_mfma_f32_16x16x32_bf16 v[50:53], v[178:181], v[186:189], v[50:53]
	v_mfma_f32_16x16x32_bf16 v[38:41], v[170:173], v[198:201], v[38:41]
	v_mfma_f32_16x16x32_bf16 v[34:37], v[178:181], v[198:201], v[34:37]
	v_mfma_f32_16x16x32_bf16 v[22:25], v[170:173], v[206:209], v[22:25]
	v_mfma_f32_16x16x32_bf16 v[18:21], v[178:181], v[206:209], v[18:21]
	v_mfma_f32_16x16x32_bf16 v[6:9], v[170:173], v[214:217], v[6:9]
	v_mfma_f32_16x16x32_bf16 v[2:5], v[178:181], v[214:217], v[2:5]
	v_mfma_f32_16x16x32_bf16 v[54:57], v[174:177], v[190:193], v[54:57]
	v_mfma_f32_16x16x32_bf16 v[50:53], v[182:185], v[190:193], v[50:53]
	v_mfma_f32_16x16x32_bf16 v[38:41], v[174:177], v[202:205], v[38:41]
	v_mfma_f32_16x16x32_bf16 v[34:37], v[182:185], v[202:205], v[34:37]
	v_mfma_f32_16x16x32_bf16 v[22:25], v[174:177], v[210:213], v[22:25]
	v_mfma_f32_16x16x32_bf16 v[18:21], v[182:185], v[210:213], v[18:21]
	v_mfma_f32_16x16x32_bf16 v[6:9], v[174:177], v[218:221], v[6:9]
	v_mfma_f32_16x16x32_bf16 v[2:5], v[182:185], v[218:221], v[2:5]
	s_barrier
	s_setprio 0
	.p2align	8
.LBB0_807:
	ds_read_b128 v[154:157], v150
	ds_read_b128 v[158:161], v150 offset:1024
	ds_read_b128 v[162:165], v150 offset:2048
	ds_read_b128 v[166:169], v150 offset:3072
	ds_read_b128 v[170:173], v151
	ds_read_b128 v[174:177], v151 offset:1024
	ds_read_b128 v[178:181], v151 offset:2048
	ds_read_b128 v[182:185], v151 offset:3072
	s_add_u32 s44, s42, 0xfff00080
	s_addc_u32 s45, s43, -1
	s_cmp_eq_u32 s68, 60
	s_cselect_b32 s47, s35, s45
	s_cselect_b32 s46, s64, s44
	s_cselect_b32 s45, s31, s67
	s_cselect_b32 s44, s65, s66
	s_add_i32 m0, s41, 0xc000
	ds_read_b128 v[186:189], v152
	ds_read_b128 v[190:193], v152 offset:1024
	ds_read_b128 v[198:201], v152 offset:2048
	ds_read_b128 v[202:205], v152 offset:3072
	ds_read_b128 v[206:209], v152 offset:4096
	ds_read_b128 v[210:213], v152 offset:5120
	ds_read_b128 v[214:217], v152 offset:6144
	ds_read_b128 v[218:221], v152 offset:7168
	global_load_lds_dwordx4 v138, s[42:43]
	s_add_i32 m0, s41, 0xe000
	s_nop 0
	global_load_lds_dwordx4 v140, s[42:43]
	s_waitcnt vmcnt(8)
	s_waitcnt lgkmcnt(0)
	s_setprio 1
	s_barrier
	v_mfma_f32_16x16x32_bf16 v[126:129], v[154:157], v[186:189], v[126:129]
	v_mfma_f32_16x16x32_bf16 v[122:125], v[162:165], v[186:189], v[122:125]
	v_mfma_f32_16x16x32_bf16 v[110:113], v[154:157], v[198:201], v[110:113]
	v_mfma_f32_16x16x32_bf16 v[106:109], v[162:165], v[198:201], v[106:109]
	v_mfma_f32_16x16x32_bf16 v[94:97], v[154:157], v[206:209], v[94:97]
	v_mfma_f32_16x16x32_bf16 v[90:93], v[162:165], v[206:209], v[90:93]
	v_mfma_f32_16x16x32_bf16 v[78:81], v[154:157], v[214:217], v[78:81]
	v_mfma_f32_16x16x32_bf16 v[74:77], v[162:165], v[214:217], v[74:77]
	v_mfma_f32_16x16x32_bf16 v[126:129], v[158:161], v[190:193], v[126:129]
	v_mfma_f32_16x16x32_bf16 v[122:125], v[166:169], v[190:193], v[122:125]
	v_mfma_f32_16x16x32_bf16 v[110:113], v[158:161], v[202:205], v[110:113]
	v_mfma_f32_16x16x32_bf16 v[106:109], v[166:169], v[202:205], v[106:109]
	v_mfma_f32_16x16x32_bf16 v[94:97], v[158:161], v[210:213], v[94:97]
	v_mfma_f32_16x16x32_bf16 v[90:93], v[166:169], v[210:213], v[90:93]
	v_mfma_f32_16x16x32_bf16 v[78:81], v[158:161], v[218:221], v[78:81]
	v_mfma_f32_16x16x32_bf16 v[74:77], v[166:169], v[218:221], v[74:77]
	v_mfma_f32_16x16x32_bf16 v[118:121], v[170:173], v[186:189], v[118:121]
	v_mfma_f32_16x16x32_bf16 v[114:117], v[178:181], v[186:189], v[114:117]
	v_mfma_f32_16x16x32_bf16 v[102:105], v[170:173], v[198:201], v[102:105]
	v_mfma_f32_16x16x32_bf16 v[98:101], v[178:181], v[198:201], v[98:101]
	v_mfma_f32_16x16x32_bf16 v[86:89], v[170:173], v[206:209], v[86:89]
	v_mfma_f32_16x16x32_bf16 v[82:85], v[178:181], v[206:209], v[82:85]
	v_mfma_f32_16x16x32_bf16 v[70:73], v[170:173], v[214:217], v[70:73]
	v_mfma_f32_16x16x32_bf16 v[66:69], v[178:181], v[214:217], v[66:69]
	v_mfma_f32_16x16x32_bf16 v[118:121], v[174:177], v[190:193], v[118:121]
	v_mfma_f32_16x16x32_bf16 v[114:117], v[182:185], v[190:193], v[114:117]
	v_mfma_f32_16x16x32_bf16 v[102:105], v[174:177], v[202:205], v[102:105]
	v_mfma_f32_16x16x32_bf16 v[98:101], v[182:185], v[202:205], v[98:101]
	v_mfma_f32_16x16x32_bf16 v[86:89], v[174:177], v[210:213], v[86:89]
	v_mfma_f32_16x16x32_bf16 v[82:85], v[182:185], v[210:213], v[82:85]
	v_mfma_f32_16x16x32_bf16 v[70:73], v[174:177], v[218:221], v[70:73]
	v_mfma_f32_16x16x32_bf16 v[66:69], v[182:185], v[218:221], v[66:69]
	s_barrier
	s_setprio 0
	s_add_i32 s69, s57, s33
	s_mov_b32 m0, s69
	ds_read_b128 v[186:189], v152 offset:16384
	ds_read_b128 v[190:193], v152 offset:17408
	ds_read_b128 v[198:201], v152 offset:18432
	ds_read_b128 v[202:205], v152 offset:19456
	ds_read_b128 v[206:209], v152 offset:20480
	ds_read_b128 v[210:213], v152 offset:21504
	ds_read_b128 v[214:217], v152 offset:22528
	ds_read_b128 v[218:221], v152 offset:23552
	global_load_lds_dwordx4 v132, s[44:45]
	s_add_i32 m0, s69, 0x2000
	s_add_u32 s70, s44, 0x100000
	s_addc_u32 s71, s45, 0
	s_add_i32 s69, s58, s33
	global_load_lds_dwordx4 v136, s[44:45]
	s_mov_b32 m0, s69
	global_load_lds_dwordx4 v132, s[70:71]
	s_add_i32 m0, s69, 0x2000
	s_nop 0
	global_load_lds_dwordx4 v136, s[70:71]
	s_mov_b32 m0, s41
	s_nop 0
	global_load_lds_dwordx4 v130, s[46:47]
	s_mov_b32 m0, s50
	s_nop 0
	global_load_lds_dwordx4 v134, s[46:47]
	s_waitcnt vmcnt(8)
	s_waitcnt lgkmcnt(0)
	s_setprio 1
	s_barrier
	v_mfma_f32_16x16x32_bf16 v[62:65], v[154:157], v[186:189], v[62:65]
	v_mfma_f32_16x16x32_bf16 v[58:61], v[162:165], v[186:189], v[58:61]
	v_mfma_f32_16x16x32_bf16 v[46:49], v[154:157], v[198:201], v[46:49]
	v_mfma_f32_16x16x32_bf16 v[42:45], v[162:165], v[198:201], v[42:45]
	v_mfma_f32_16x16x32_bf16 v[30:33], v[154:157], v[206:209], v[30:33]
	v_mfma_f32_16x16x32_bf16 v[26:29], v[162:165], v[206:209], v[26:29]
	v_mfma_f32_16x16x32_bf16 v[14:17], v[154:157], v[214:217], v[14:17]
	v_mfma_f32_16x16x32_bf16 v[10:13], v[162:165], v[214:217], v[10:13]
	v_mfma_f32_16x16x32_bf16 v[62:65], v[158:161], v[190:193], v[62:65]
	v_mfma_f32_16x16x32_bf16 v[58:61], v[166:169], v[190:193], v[58:61]
	v_mfma_f32_16x16x32_bf16 v[46:49], v[158:161], v[202:205], v[46:49]
	v_mfma_f32_16x16x32_bf16 v[42:45], v[166:169], v[202:205], v[42:45]
	v_mfma_f32_16x16x32_bf16 v[30:33], v[158:161], v[210:213], v[30:33]
	v_mfma_f32_16x16x32_bf16 v[26:29], v[166:169], v[210:213], v[26:29]
	v_mfma_f32_16x16x32_bf16 v[14:17], v[158:161], v[218:221], v[14:17]
	v_mfma_f32_16x16x32_bf16 v[10:13], v[166:169], v[218:221], v[10:13]
	v_mfma_f32_16x16x32_bf16 v[54:57], v[170:173], v[186:189], v[54:57]
	v_mfma_f32_16x16x32_bf16 v[50:53], v[178:181], v[186:189], v[50:53]
	v_mfma_f32_16x16x32_bf16 v[38:41], v[170:173], v[198:201], v[38:41]
	v_mfma_f32_16x16x32_bf16 v[34:37], v[178:181], v[198:201], v[34:37]
	v_mfma_f32_16x16x32_bf16 v[22:25], v[170:173], v[206:209], v[22:25]
	v_mfma_f32_16x16x32_bf16 v[18:21], v[178:181], v[206:209], v[18:21]
	v_mfma_f32_16x16x32_bf16 v[6:9], v[170:173], v[214:217], v[6:9]
	v_mfma_f32_16x16x32_bf16 v[2:5], v[178:181], v[214:217], v[2:5]
	v_mfma_f32_16x16x32_bf16 v[54:57], v[174:177], v[190:193], v[54:57]
	v_mfma_f32_16x16x32_bf16 v[50:53], v[182:185], v[190:193], v[50:53]
	v_mfma_f32_16x16x32_bf16 v[38:41], v[174:177], v[202:205], v[38:41]
	v_mfma_f32_16x16x32_bf16 v[34:37], v[182:185], v[202:205], v[34:37]
	v_mfma_f32_16x16x32_bf16 v[22:25], v[174:177], v[210:213], v[22:25]
	v_mfma_f32_16x16x32_bf16 v[18:21], v[182:185], v[210:213], v[18:21]
	v_mfma_f32_16x16x32_bf16 v[6:9], v[174:177], v[218:221], v[6:9]
	v_mfma_f32_16x16x32_bf16 v[2:5], v[182:185], v[218:221], v[2:5]
	s_barrier
	s_setprio 0
	s_add_i32 s69, 0, 0x18000
	v_add_u32_e32 v153, s69, v148
	s_add_i32 s70, 0, 0x1c000
	ds_read_b128 v[154:157], v153
	ds_read_b128 v[158:161], v153 offset:1024
	ds_read_b128 v[162:165], v153 offset:2048
	ds_read_b128 v[166:169], v153 offset:3072
	v_add_u32_e32 v153, s70, v148
	ds_read_b128 v[170:173], v153
	ds_read_b128 v[174:177], v153 offset:1024
	ds_read_b128 v[178:181], v153 offset:2048
	ds_read_b128 v[182:185], v153 offset:3072
	s_add_u32 s46, s46, 0x100000
	s_addc_u32 s47, s47, 0
	s_mov_b32 m0, s51
	ds_read_b128 v[186:189], v152 offset:32768
	ds_read_b128 v[190:193], v152 offset:33792
	ds_read_b128 v[198:201], v152 offset:34816
	ds_read_b128 v[202:205], v152 offset:35840
	ds_read_b128 v[206:209], v152 offset:36864
	ds_read_b128 v[210:213], v152 offset:37888
	ds_read_b128 v[214:217], v152 offset:38912
	ds_read_b128 v[218:221], v152 offset:39936
	global_load_lds_dwordx4 v130, s[46:47]
	s_mov_b32 m0, s52
	s_nop 0
	global_load_lds_dwordx4 v134, s[46:47]
	s_waitcnt vmcnt(8)
	s_waitcnt lgkmcnt(0)
	s_setprio 1
	s_barrier
	v_mfma_f32_16x16x32_bf16 v[126:129], v[154:157], v[186:189], v[126:129]
	v_mfma_f32_16x16x32_bf16 v[122:125], v[162:165], v[186:189], v[122:125]
	v_mfma_f32_16x16x32_bf16 v[110:113], v[154:157], v[198:201], v[110:113]
	v_mfma_f32_16x16x32_bf16 v[106:109], v[162:165], v[198:201], v[106:109]
	v_mfma_f32_16x16x32_bf16 v[94:97], v[154:157], v[206:209], v[94:97]
	v_mfma_f32_16x16x32_bf16 v[90:93], v[162:165], v[206:209], v[90:93]
	v_mfma_f32_16x16x32_bf16 v[78:81], v[154:157], v[214:217], v[78:81]
	v_mfma_f32_16x16x32_bf16 v[74:77], v[162:165], v[214:217], v[74:77]
	v_mfma_f32_16x16x32_bf16 v[126:129], v[158:161], v[190:193], v[126:129]
	v_mfma_f32_16x16x32_bf16 v[122:125], v[166:169], v[190:193], v[122:125]
	v_mfma_f32_16x16x32_bf16 v[110:113], v[158:161], v[202:205], v[110:113]
	v_mfma_f32_16x16x32_bf16 v[106:109], v[166:169], v[202:205], v[106:109]
	v_mfma_f32_16x16x32_bf16 v[94:97], v[158:161], v[210:213], v[94:97]
	v_mfma_f32_16x16x32_bf16 v[90:93], v[166:169], v[210:213], v[90:93]
	v_mfma_f32_16x16x32_bf16 v[78:81], v[158:161], v[218:221], v[78:81]
	v_mfma_f32_16x16x32_bf16 v[74:77], v[166:169], v[218:221], v[74:77]
	v_mfma_f32_16x16x32_bf16 v[118:121], v[170:173], v[186:189], v[118:121]
	v_mfma_f32_16x16x32_bf16 v[114:117], v[178:181], v[186:189], v[114:117]
	v_mfma_f32_16x16x32_bf16 v[102:105], v[170:173], v[198:201], v[102:105]
	v_mfma_f32_16x16x32_bf16 v[98:101], v[178:181], v[198:201], v[98:101]
	v_mfma_f32_16x16x32_bf16 v[86:89], v[170:173], v[206:209], v[86:89]
	v_mfma_f32_16x16x32_bf16 v[82:85], v[178:181], v[206:209], v[82:85]
	v_mfma_f32_16x16x32_bf16 v[70:73], v[170:173], v[214:217], v[70:73]
	v_mfma_f32_16x16x32_bf16 v[66:69], v[178:181], v[214:217], v[66:69]
	v_mfma_f32_16x16x32_bf16 v[118:121], v[174:177], v[190:193], v[118:121]
	v_mfma_f32_16x16x32_bf16 v[114:117], v[182:185], v[190:193], v[114:117]
	v_mfma_f32_16x16x32_bf16 v[102:105], v[174:177], v[202:205], v[102:105]
	v_mfma_f32_16x16x32_bf16 v[98:101], v[182:185], v[202:205], v[98:101]
	v_mfma_f32_16x16x32_bf16 v[86:89], v[174:177], v[210:213], v[86:89]
	v_mfma_f32_16x16x32_bf16 v[82:85], v[182:185], v[210:213], v[82:85]
	v_mfma_f32_16x16x32_bf16 v[70:73], v[174:177], v[218:221], v[70:73]
	v_mfma_f32_16x16x32_bf16 v[66:69], v[182:185], v[218:221], v[66:69]
	s_barrier
	s_setprio 0
	s_add_u32 s44, s44, 0x80
	s_addc_u32 s45, s45, 0
	s_add_i32 m0, s33, 0x18000
	ds_read_b128 v[186:189], v152 offset:49152
	ds_read_b128 v[190:193], v152 offset:50176
	ds_read_b128 v[198:201], v152 offset:51200
	ds_read_b128 v[202:205], v152 offset:52224
	ds_read_b128 v[206:209], v152 offset:53248
	ds_read_b128 v[210:213], v152 offset:54272
	ds_read_b128 v[214:217], v152 offset:55296
	ds_read_b128 v[218:221], v152 offset:56320
	global_load_lds_dwordx4 v132, s[44:45]
	s_add_i32 m0, s33, 0x1a000
	s_add_u32 s46, s46, 0xfff00080
	global_load_lds_dwordx4 v136, s[44:45]
	s_addc_u32 s47, s47, -1
	s_add_u32 s44, s44, 0x100000
	s_addc_u32 s45, s45, 0
	s_add_i32 m0, s33, 0x1c000
	s_nop 0
	global_load_lds_dwordx4 v132, s[44:45]
	s_add_i32 m0, s33, 0x1e000
	s_nop 0
	global_load_lds_dwordx4 v136, s[44:45]
	s_mov_b32 m0, s55
	s_nop 0
	global_load_lds_dwordx4 v130, s[46:47]
	s_mov_b32 m0, s56
	s_nop 0
	global_load_lds_dwordx4 v134, s[46:47]
	s_add_i32 s68, s68, 2
	s_add_u32 s42, s42, 0x100
	s_addc_u32 s43, s43, 0
	s_add_u32 s66, s66, 0x100
	s_addc_u32 s67, s67, 0
	s_cmp_gt_u32 s68, 61
	s_waitcnt vmcnt(8)
	s_waitcnt lgkmcnt(0)
	s_setprio 1
	s_barrier
	v_mfma_f32_16x16x32_bf16 v[62:65], v[154:157], v[186:189], v[62:65]
	v_mfma_f32_16x16x32_bf16 v[58:61], v[162:165], v[186:189], v[58:61]
	v_mfma_f32_16x16x32_bf16 v[46:49], v[154:157], v[198:201], v[46:49]
	v_mfma_f32_16x16x32_bf16 v[42:45], v[162:165], v[198:201], v[42:45]
	v_mfma_f32_16x16x32_bf16 v[30:33], v[154:157], v[206:209], v[30:33]
	v_mfma_f32_16x16x32_bf16 v[26:29], v[162:165], v[206:209], v[26:29]
	v_mfma_f32_16x16x32_bf16 v[14:17], v[154:157], v[214:217], v[14:17]
	v_mfma_f32_16x16x32_bf16 v[10:13], v[162:165], v[214:217], v[10:13]
	v_mfma_f32_16x16x32_bf16 v[62:65], v[158:161], v[190:193], v[62:65]
	v_mfma_f32_16x16x32_bf16 v[58:61], v[166:169], v[190:193], v[58:61]
	v_mfma_f32_16x16x32_bf16 v[46:49], v[158:161], v[202:205], v[46:49]
	v_mfma_f32_16x16x32_bf16 v[42:45], v[166:169], v[202:205], v[42:45]
	v_mfma_f32_16x16x32_bf16 v[30:33], v[158:161], v[210:213], v[30:33]
	v_mfma_f32_16x16x32_bf16 v[26:29], v[166:169], v[210:213], v[26:29]
	v_mfma_f32_16x16x32_bf16 v[14:17], v[158:161], v[218:221], v[14:17]
	v_mfma_f32_16x16x32_bf16 v[10:13], v[166:169], v[218:221], v[10:13]
	v_mfma_f32_16x16x32_bf16 v[54:57], v[170:173], v[186:189], v[54:57]
	v_mfma_f32_16x16x32_bf16 v[50:53], v[178:181], v[186:189], v[50:53]
	v_mfma_f32_16x16x32_bf16 v[38:41], v[170:173], v[198:201], v[38:41]
	v_mfma_f32_16x16x32_bf16 v[34:37], v[178:181], v[198:201], v[34:37]
	v_mfma_f32_16x16x32_bf16 v[22:25], v[170:173], v[206:209], v[22:25]
	v_mfma_f32_16x16x32_bf16 v[18:21], v[178:181], v[206:209], v[18:21]
	v_mfma_f32_16x16x32_bf16 v[6:9], v[170:173], v[214:217], v[6:9]
	v_mfma_f32_16x16x32_bf16 v[2:5], v[178:181], v[214:217], v[2:5]
	v_mfma_f32_16x16x32_bf16 v[54:57], v[174:177], v[190:193], v[54:57]
	v_mfma_f32_16x16x32_bf16 v[50:53], v[182:185], v[190:193], v[50:53]
	v_mfma_f32_16x16x32_bf16 v[38:41], v[174:177], v[202:205], v[38:41]
	v_mfma_f32_16x16x32_bf16 v[34:37], v[182:185], v[202:205], v[34:37]
	v_mfma_f32_16x16x32_bf16 v[22:25], v[174:177], v[210:213], v[22:25]
	v_mfma_f32_16x16x32_bf16 v[18:21], v[182:185], v[210:213], v[18:21]
	v_mfma_f32_16x16x32_bf16 v[6:9], v[174:177], v[218:221], v[6:9]
	v_mfma_f32_16x16x32_bf16 v[2:5], v[182:185], v[218:221], v[2:5]
	s_barrier
	s_setprio 0
	s_cbranch_scc0 .LBB0_807
	s_and_b64 vcc, exec, s[14:15]
	s_cbranch_vccz .LBB0_810
	s_barrier

.LBB0_873:
	ds_read_b128 v[158:161], v153
	ds_read_b128 v[162:165], v153 offset:1024
	ds_read_b128 v[166:169], v153 offset:2048
	ds_read_b128 v[170:173], v153 offset:3072
	ds_read_b128 v[174:177], v154
	ds_read_b128 v[178:181], v154 offset:1024
	ds_read_b128 v[182:185], v154 offset:2048
	ds_read_b128 v[186:189], v154 offset:3072
	s_add_u32 s20, s16, s18
	s_addc_u32 s21, s17, s19
	s_add_u32 s20, s20, 0x3f400100
	s_addc_u32 s21, s21, 0
	s_add_u32 s53, s40, s18
	s_addc_u32 s54, s41, s19
	s_cmpk_eq_i32 s18, 0x3f00
	s_cselect_b32 s29, s7, s21
	s_cselect_b32 s28, s6, s20
	s_cselect_b32 s21, s5, s54
	s_cselect_b32 s20, s4, s53
	s_mov_b32 m0, s43
	v_lshl_add_u64 v[194:195], v[138:139], 0, s[18:19]
	ds_read_b128 v[190:193], v155
	ds_read_b128 v[198:201], v155 offset:1024
	ds_read_b128 v[202:205], v155 offset:2048
	ds_read_b128 v[206:209], v155 offset:3072
	ds_read_b128 v[210:213], v155 offset:4096
	ds_read_b128 v[214:217], v155 offset:5120
	ds_read_b128 v[218:221], v155 offset:6144
	ds_read_b128 v[222:225], v155 offset:7168
	global_load_lds_dwordx4 v[194:195], off
	v_lshl_add_u64 v[194:195], v[140:141], 0, s[18:19]
	s_mov_b32 m0, s44
	s_nop 0
	global_load_lds_dwordx4 v[194:195], off
	s_waitcnt vmcnt(8)
	s_waitcnt lgkmcnt(0)
	s_setprio 1
	s_barrier
	v_mfma_f32_16x16x32_bf16 v[126:129], v[158:161], v[190:193], v[126:129]
	v_mfma_f32_16x16x32_bf16 v[122:125], v[166:169], v[190:193], v[122:125]
	v_mfma_f32_16x16x32_bf16 v[110:113], v[158:161], v[202:205], v[110:113]
	v_mfma_f32_16x16x32_bf16 v[106:109], v[166:169], v[202:205], v[106:109]
	v_mfma_f32_16x16x32_bf16 v[94:97], v[158:161], v[210:213], v[94:97]
	v_mfma_f32_16x16x32_bf16 v[90:93], v[166:169], v[210:213], v[90:93]
	v_mfma_f32_16x16x32_bf16 v[78:81], v[158:161], v[218:221], v[78:81]
	v_mfma_f32_16x16x32_bf16 v[74:77], v[166:169], v[218:221], v[74:77]
	v_mfma_f32_16x16x32_bf16 v[126:129], v[162:165], v[198:201], v[126:129]
	v_mfma_f32_16x16x32_bf16 v[122:125], v[170:173], v[198:201], v[122:125]
	v_mfma_f32_16x16x32_bf16 v[110:113], v[162:165], v[206:209], v[110:113]
	v_mfma_f32_16x16x32_bf16 v[106:109], v[170:173], v[206:209], v[106:109]
	v_mfma_f32_16x16x32_bf16 v[94:97], v[162:165], v[214:217], v[94:97]
	v_mfma_f32_16x16x32_bf16 v[90:93], v[170:173], v[214:217], v[90:93]
	v_mfma_f32_16x16x32_bf16 v[78:81], v[162:165], v[222:225], v[78:81]
	v_mfma_f32_16x16x32_bf16 v[74:77], v[170:173], v[222:225], v[74:77]
	v_mfma_f32_16x16x32_bf16 v[118:121], v[174:177], v[190:193], v[118:121]
	v_mfma_f32_16x16x32_bf16 v[114:117], v[182:185], v[190:193], v[114:117]
	v_mfma_f32_16x16x32_bf16 v[102:105], v[174:177], v[202:205], v[102:105]
	v_mfma_f32_16x16x32_bf16 v[98:101], v[182:185], v[202:205], v[98:101]
	v_mfma_f32_16x16x32_bf16 v[86:89], v[174:177], v[210:213], v[86:89]
	v_mfma_f32_16x16x32_bf16 v[82:85], v[182:185], v[210:213], v[82:85]
	v_mfma_f32_16x16x32_bf16 v[70:73], v[174:177], v[218:221], v[70:73]
	v_mfma_f32_16x16x32_bf16 v[66:69], v[182:185], v[218:221], v[66:69]
	v_mfma_f32_16x16x32_bf16 v[118:121], v[178:181], v[198:201], v[118:121]
	v_mfma_f32_16x16x32_bf16 v[114:117], v[186:189], v[198:201], v[114:117]
	v_mfma_f32_16x16x32_bf16 v[102:105], v[178:181], v[206:209], v[102:105]
	v_mfma_f32_16x16x32_bf16 v[98:101], v[186:189], v[206:209], v[98:101]
	v_mfma_f32_16x16x32_bf16 v[86:89], v[178:181], v[214:217], v[86:89]
	v_mfma_f32_16x16x32_bf16 v[82:85], v[186:189], v[214:217], v[82:85]
	v_mfma_f32_16x16x32_bf16 v[70:73], v[178:181], v[222:225], v[70:73]
	v_mfma_f32_16x16x32_bf16 v[66:69], v[186:189], v[222:225], v[66:69]
	s_barrier
	s_setprio 0
	s_mov_b32 m0, s45
	v_lshl_add_u64 v[194:195], s[20:21], 0, v[134:135]
	s_add_u32 s54, s20, 0x400000
	ds_read_b128 v[190:193], v155 offset:16384
	ds_read_b128 v[198:201], v155 offset:17408
	ds_read_b128 v[202:205], v155 offset:18432
	ds_read_b128 v[206:209], v155 offset:19456
	ds_read_b128 v[210:213], v155 offset:20480
	ds_read_b128 v[214:217], v155 offset:21504
	ds_read_b128 v[218:221], v155 offset:22528
	ds_read_b128 v[222:225], v155 offset:23552
	global_load_lds_dwordx4 v[194:195], off
	v_lshl_add_u64 v[226:227], s[20:21], 0, v[130:131]
	s_mov_b32 m0, s46
	s_addc_u32 s55, s21, 0
	global_load_lds_dwordx4 v[226:227], off
	v_lshl_add_u64 v[228:229], s[54:55], 0, v[134:135]
	s_mov_b32 m0, s47
	v_lshl_add_u64 v[230:231], s[28:29], 0, v[132:133]
	global_load_lds_dwordx4 v[228:229], off
	v_lshl_add_u64 v[228:229], s[54:55], 0, v[130:131]
	s_mov_b32 m0, s48
	s_nop 0
	global_load_lds_dwordx4 v[228:229], off
	v_lshl_add_u64 v[228:229], s[28:29], 0, v[136:137]
	s_mov_b32 m0, s0
	s_nop 0
	global_load_lds_dwordx4 v[228:229], off
	s_mov_b32 m0, s34
	s_nop 0
	global_load_lds_dwordx4 v[230:231], off
	s_waitcnt vmcnt(8)
	s_waitcnt lgkmcnt(0)
	s_setprio 1
	s_barrier
	v_mfma_f32_16x16x32_bf16 v[62:65], v[158:161], v[190:193], v[62:65]
	v_mfma_f32_16x16x32_bf16 v[58:61], v[166:169], v[190:193], v[58:61]
	v_mfma_f32_16x16x32_bf16 v[46:49], v[158:161], v[202:205], v[46:49]
	v_mfma_f32_16x16x32_bf16 v[42:45], v[166:169], v[202:205], v[42:45]
	v_mfma_f32_16x16x32_bf16 v[30:33], v[158:161], v[210:213], v[30:33]
	v_mfma_f32_16x16x32_bf16 v[26:29], v[166:169], v[210:213], v[26:29]
	v_mfma_f32_16x16x32_bf16 v[14:17], v[158:161], v[218:221], v[14:17]
	v_mfma_f32_16x16x32_bf16 v[10:13], v[166:169], v[218:221], v[10:13]
	v_mfma_f32_16x16x32_bf16 v[62:65], v[162:165], v[198:201], v[62:65]
	v_mfma_f32_16x16x32_bf16 v[58:61], v[170:173], v[198:201], v[58:61]
	v_mfma_f32_16x16x32_bf16 v[46:49], v[162:165], v[206:209], v[46:49]
	v_mfma_f32_16x16x32_bf16 v[42:45], v[170:173], v[206:209], v[42:45]
	v_mfma_f32_16x16x32_bf16 v[30:33], v[162:165], v[214:217], v[30:33]
	v_mfma_f32_16x16x32_bf16 v[26:29], v[170:173], v[214:217], v[26:29]
	v_mfma_f32_16x16x32_bf16 v[14:17], v[162:165], v[222:225], v[14:17]
	v_mfma_f32_16x16x32_bf16 v[10:13], v[170:173], v[222:225], v[10:13]
	v_mfma_f32_16x16x32_bf16 v[54:57], v[174:177], v[190:193], v[54:57]
	v_mfma_f32_16x16x32_bf16 v[50:53], v[182:185], v[190:193], v[50:53]
	v_mfma_f32_16x16x32_bf16 v[38:41], v[174:177], v[202:205], v[38:41]
	v_mfma_f32_16x16x32_bf16 v[34:37], v[182:185], v[202:205], v[34:37]
	v_mfma_f32_16x16x32_bf16 v[22:25], v[174:177], v[210:213], v[22:25]
	v_mfma_f32_16x16x32_bf16 v[18:21], v[182:185], v[210:213], v[18:21]
	v_mfma_f32_16x16x32_bf16 v[6:9], v[174:177], v[218:221], v[6:9]
	v_mfma_f32_16x16x32_bf16 v[2:5], v[182:185], v[218:221], v[2:5]
	v_mfma_f32_16x16x32_bf16 v[54:57], v[178:181], v[198:201], v[54:57]
	v_mfma_f32_16x16x32_bf16 v[50:53], v[186:189], v[198:201], v[50:53]
	v_mfma_f32_16x16x32_bf16 v[38:41], v[178:181], v[206:209], v[38:41]
	v_mfma_f32_16x16x32_bf16 v[34:37], v[186:189], v[206:209], v[34:37]
	v_mfma_f32_16x16x32_bf16 v[22:25], v[178:181], v[214:217], v[22:25]
	v_mfma_f32_16x16x32_bf16 v[18:21], v[186:189], v[214:217], v[18:21]
	v_mfma_f32_16x16x32_bf16 v[6:9], v[178:181], v[222:225], v[6:9]
	v_mfma_f32_16x16x32_bf16 v[2:5], v[186:189], v[222:225], v[2:5]
	s_barrier
	s_setprio 0
	ds_read_b128 v[158:161], v156
	ds_read_b128 v[162:165], v156 offset:1024
	ds_read_b128 v[166:169], v156 offset:2048
	ds_read_b128 v[170:173], v156 offset:3072
	ds_read_b128 v[174:177], v157
	ds_read_b128 v[178:181], v157 offset:1024
	ds_read_b128 v[182:185], v157 offset:2048
	ds_read_b128 v[186:189], v157 offset:3072
	s_add_u32 s28, s28, 0x400000
	s_addc_u32 s29, s29, 0
	s_mov_b32 m0, s36
	v_lshl_add_u64 v[232:233], s[28:29], 0, v[136:137]
	ds_read_b128 v[190:193], v155 offset:32768
	ds_read_b128 v[198:201], v155 offset:33792
	ds_read_b128 v[202:205], v155 offset:34816
	ds_read_b128 v[206:209], v155 offset:35840
	ds_read_b128 v[210:213], v155 offset:36864
	ds_read_b128 v[214:217], v155 offset:37888
	ds_read_b128 v[218:221], v155 offset:38912
	ds_read_b128 v[222:225], v155 offset:39936
	global_load_lds_dwordx4 v[232:233], off
	v_lshl_add_u64 v[232:233], s[28:29], 0, v[132:133]
	s_mov_b32 m0, s37
	s_nop 0
	global_load_lds_dwordx4 v[232:233], off
	s_waitcnt vmcnt(8)
	s_waitcnt lgkmcnt(0)
	s_setprio 1
	s_barrier
	v_mfma_f32_16x16x32_bf16 v[126:129], v[158:161], v[190:193], v[126:129]
	v_mfma_f32_16x16x32_bf16 v[122:125], v[166:169], v[190:193], v[122:125]
	v_mfma_f32_16x16x32_bf16 v[110:113], v[158:161], v[202:205], v[110:113]
	v_mfma_f32_16x16x32_bf16 v[106:109], v[166:169], v[202:205], v[106:109]
	v_mfma_f32_16x16x32_bf16 v[94:97], v[158:161], v[210:213], v[94:97]
	v_mfma_f32_16x16x32_bf16 v[90:93], v[166:169], v[210:213], v[90:93]
	v_mfma_f32_16x16x32_bf16 v[78:81], v[158:161], v[218:221], v[78:81]
	v_mfma_f32_16x16x32_bf16 v[74:77], v[166:169], v[218:221], v[74:77]
	v_mfma_f32_16x16x32_bf16 v[126:129], v[162:165], v[198:201], v[126:129]
	v_mfma_f32_16x16x32_bf16 v[122:125], v[170:173], v[198:201], v[122:125]
	v_mfma_f32_16x16x32_bf16 v[110:113], v[162:165], v[206:209], v[110:113]
	v_mfma_f32_16x16x32_bf16 v[106:109], v[170:173], v[206:209], v[106:109]
	v_mfma_f32_16x16x32_bf16 v[94:97], v[162:165], v[214:217], v[94:97]
	v_mfma_f32_16x16x32_bf16 v[90:93], v[170:173], v[214:217], v[90:93]
	v_mfma_f32_16x16x32_bf16 v[78:81], v[162:165], v[222:225], v[78:81]
	v_mfma_f32_16x16x32_bf16 v[74:77], v[170:173], v[222:225], v[74:77]
	v_mfma_f32_16x16x32_bf16 v[118:121], v[174:177], v[190:193], v[118:121]
	v_mfma_f32_16x16x32_bf16 v[114:117], v[182:185], v[190:193], v[114:117]
	v_mfma_f32_16x16x32_bf16 v[102:105], v[174:177], v[202:205], v[102:105]
	v_mfma_f32_16x16x32_bf16 v[98:101], v[182:185], v[202:205], v[98:101]
	v_mfma_f32_16x16x32_bf16 v[86:89], v[174:177], v[210:213], v[86:89]
	v_mfma_f32_16x16x32_bf16 v[82:85], v[182:185], v[210:213], v[82:85]
	v_mfma_f32_16x16x32_bf16 v[70:73], v[174:177], v[218:221], v[70:73]
	v_mfma_f32_16x16x32_bf16 v[66:69], v[182:185], v[218:221], v[66:69]
	v_mfma_f32_16x16x32_bf16 v[118:121], v[178:181], v[198:201], v[118:121]
	v_mfma_f32_16x16x32_bf16 v[114:117], v[186:189], v[198:201], v[114:117]
	v_mfma_f32_16x16x32_bf16 v[102:105], v[178:181], v[206:209], v[102:105]
	v_mfma_f32_16x16x32_bf16 v[98:101], v[186:189], v[206:209], v[98:101]
	v_mfma_f32_16x16x32_bf16 v[86:89], v[178:181], v[214:217], v[86:89]
	v_mfma_f32_16x16x32_bf16 v[82:85], v[186:189], v[214:217], v[82:85]
	v_mfma_f32_16x16x32_bf16 v[70:73], v[178:181], v[222:225], v[70:73]
	v_mfma_f32_16x16x32_bf16 v[66:69], v[186:189], v[222:225], v[66:69]
	s_barrier
	s_setprio 0
	s_mov_b32 m0, s49
	v_lshl_add_u64 v[194:195], v[194:195], 0, s[14:15]
	s_add_u32 s20, s20, 0x400080
	ds_read_b128 v[190:193], v155 offset:49152
	ds_read_b128 v[198:201], v155 offset:50176
	ds_read_b128 v[202:205], v155 offset:51200
	ds_read_b128 v[206:209], v155 offset:52224
	ds_read_b128 v[210:213], v155 offset:53248
	ds_read_b128 v[214:217], v155 offset:54272
	ds_read_b128 v[218:221], v155 offset:55296
	ds_read_b128 v[222:225], v155 offset:56320
	global_load_lds_dwordx4 v[194:195], off
	v_lshl_add_u64 v[194:195], v[226:227], 0, s[14:15]
	s_mov_b32 m0, s50
	s_addc_u32 s21, s21, 0
	global_load_lds_dwordx4 v[194:195], off
	v_lshl_add_u64 v[194:195], s[20:21], 0, v[134:135]
	s_mov_b32 m0, s51
	s_nop 0
	global_load_lds_dwordx4 v[194:195], off
	v_lshl_add_u64 v[194:195], s[20:21], 0, v[130:131]
	s_mov_b32 m0, s52
	s_nop 0
	global_load_lds_dwordx4 v[194:195], off
	v_lshl_add_u64 v[194:195], v[228:229], 0, s[14:15]
	s_mov_b32 m0, s38
	s_nop 0
	global_load_lds_dwordx4 v[194:195], off
	v_lshl_add_u64 v[194:195], v[230:231], 0, s[14:15]
	s_mov_b32 m0, s39
	s_nop 0
	global_load_lds_dwordx4 v[194:195], off
	s_add_i32 s42, s42, 2
	s_add_u32 s18, s18, 0x100
	s_addc_u32 s19, s19, 0
	s_cmpk_gt_u32 s42, 0x7d
	s_waitcnt vmcnt(8)
	s_waitcnt lgkmcnt(0)
	s_setprio 1
	s_barrier
	v_mfma_f32_16x16x32_bf16 v[62:65], v[158:161], v[190:193], v[62:65]
	v_mfma_f32_16x16x32_bf16 v[58:61], v[166:169], v[190:193], v[58:61]
	v_mfma_f32_16x16x32_bf16 v[46:49], v[158:161], v[202:205], v[46:49]
	v_mfma_f32_16x16x32_bf16 v[42:45], v[166:169], v[202:205], v[42:45]
	v_mfma_f32_16x16x32_bf16 v[30:33], v[158:161], v[210:213], v[30:33]
	v_mfma_f32_16x16x32_bf16 v[26:29], v[166:169], v[210:213], v[26:29]
	v_mfma_f32_16x16x32_bf16 v[14:17], v[158:161], v[218:221], v[14:17]
	v_mfma_f32_16x16x32_bf16 v[10:13], v[166:169], v[218:221], v[10:13]
	v_mfma_f32_16x16x32_bf16 v[62:65], v[162:165], v[198:201], v[62:65]
	v_mfma_f32_16x16x32_bf16 v[58:61], v[170:173], v[198:201], v[58:61]
	v_mfma_f32_16x16x32_bf16 v[46:49], v[162:165], v[206:209], v[46:49]
	v_mfma_f32_16x16x32_bf16 v[42:45], v[170:173], v[206:209], v[42:45]
	v_mfma_f32_16x16x32_bf16 v[30:33], v[162:165], v[214:217], v[30:33]
	v_mfma_f32_16x16x32_bf16 v[26:29], v[170:173], v[214:217], v[26:29]
	v_mfma_f32_16x16x32_bf16 v[14:17], v[162:165], v[222:225], v[14:17]
	v_mfma_f32_16x16x32_bf16 v[10:13], v[170:173], v[222:225], v[10:13]
	v_mfma_f32_16x16x32_bf16 v[54:57], v[174:177], v[190:193], v[54:57]
	v_mfma_f32_16x16x32_bf16 v[50:53], v[182:185], v[190:193], v[50:53]
	v_mfma_f32_16x16x32_bf16 v[38:41], v[174:177], v[202:205], v[38:41]
	v_mfma_f32_16x16x32_bf16 v[34:37], v[182:185], v[202:205], v[34:37]
	v_mfma_f32_16x16x32_bf16 v[22:25], v[174:177], v[210:213], v[22:25]
	v_mfma_f32_16x16x32_bf16 v[18:21], v[182:185], v[210:213], v[18:21]
	v_mfma_f32_16x16x32_bf16 v[6:9], v[174:177], v[218:221], v[6:9]
	v_mfma_f32_16x16x32_bf16 v[2:5], v[182:185], v[218:221], v[2:5]
	v_mfma_f32_16x16x32_bf16 v[54:57], v[178:181], v[198:201], v[54:57]
	v_mfma_f32_16x16x32_bf16 v[50:53], v[186:189], v[198:201], v[50:53]
	v_mfma_f32_16x16x32_bf16 v[38:41], v[178:181], v[206:209], v[38:41]
	v_mfma_f32_16x16x32_bf16 v[34:37], v[186:189], v[206:209], v[34:37]
	v_mfma_f32_16x16x32_bf16 v[22:25], v[178:181], v[214:217], v[22:25]
	v_mfma_f32_16x16x32_bf16 v[18:21], v[186:189], v[214:217], v[18:21]
	v_mfma_f32_16x16x32_bf16 v[6:9], v[178:181], v[222:225], v[6:9]
	v_mfma_f32_16x16x32_bf16 v[2:5], v[186:189], v[222:225], v[2:5]
	s_barrier
	s_setprio 0
	s_cbranch_scc0 .LBB0_873
	s_lshl_b32 s0, s33, 25
	s_add_u32 s0, s22, s0
	s_addc_u32 s5, s23, 0
	s_add_u32 s4, s0, 0x43800000
	s_addc_u32 s5, s5, 0
	s_add_u32 s6, s22, 0x20000
	s_addc_u32 s7, s23, 0
	v_lshl_add_u32 v130, s31, 8, v152
	v_mov_b32_e32 v131, 0
	v_lshl_add_u64 v[132:133], v[130:131], 2, s[6:7]
	global_load_dword v137, v[132:133], off
	v_mov_b32_e32 v136, 0x358637bd
	v_lshl_or_b32 v134, s1, 8, v142
	v_or_b32_e32 v134, s35, v134
	v_lshlrev_b64 v[138:139], 14, v[130:131]
	v_ashrrev_i32_e32 v135, 31, v134
	v_lshlrev_b64 v[134:135], 2, v[134:135]
	v_lshl_add_u64 v[138:139], s[4:5], 0, v[138:139]
	v_or_b32_e32 v140, 16, v130
	v_mov_b32_e32 v141, v131
	v_lshl_add_u64 v[138:139], v[138:139], 0, v[134:135]
	v_lshl_add_u64 v[152:153], v[140:141], 2, s[6:7]
	s_cmpk_lt_u32 s30, 0x100
	s_waitcnt vmcnt(0)
	v_fmamk_f32 v137, v137, 0x39800000, v136
	v_div_scale_f32 v154, s[0:1], v137, v137, 1.0
	v_rcp_f32_e32 v155, v154
	v_div_scale_f32 v156, vcc, 1.0, v137, 1.0
	v_fma_f32 v157, -v154, v155, 1.0
	v_fmac_f32_e32 v155, v157, v155
	v_mul_f32_e32 v157, v156, v155
	v_fma_f32 v158, -v154, v157, v156
	v_fmac_f32_e32 v157, v158, v155
	v_fma_f32 v154, -v154, v157, v156
	v_div_fmas_f32 v154, v154, v155, v157
	v_div_fixup_f32 v154, v154, v137, 1.0
	v_pk_mul_f32 v[128:129], v[128:129], v[154:155] op_sel_hi:[1,0]
	v_pk_mul_f32 v[126:127], v[126:127], v[154:155] op_sel_hi:[1,0]
	v_pk_mul_f32 v[124:125], v[124:125], v[154:155] op_sel_hi:[1,0]
	v_pk_mul_f32 v[122:123], v[122:123], v[154:155] op_sel_hi:[1,0]
	v_pk_mul_f32 v[120:121], v[120:121], v[154:155] op_sel_hi:[1,0]
	v_pk_mul_f32 v[118:119], v[118:119], v[154:155] op_sel_hi:[1,0]
	v_pk_mul_f32 v[116:117], v[116:117], v[154:155] op_sel_hi:[1,0]
	v_pk_mul_f32 v[114:115], v[114:115], v[154:155] op_sel_hi:[1,0]
	global_store_dwordx4 v[138:139], v[126:129], off
	global_store_dwordx4 v[138:139], v[122:125], off offset:16
	global_store_dwordx4 v[138:139], v[118:121], off offset:512
	global_store_dwordx4 v[138:139], v[114:117], off offset:528
	global_load_dword v118, v[152:153], off
	s_waitcnt vmcnt(0)
	v_fmamk_f32 v120, v118, 0x39800000, v136
	v_div_scale_f32 v121, s[0:1], v120, v120, 1.0
	v_rcp_f32_e32 v122, v121
	v_div_scale_f32 v123, vcc, 1.0, v120, 1.0
	v_lshlrev_b64 v[116:117], 14, v[140:141]
	v_fma_f32 v124, -v121, v122, 1.0
	v_fmac_f32_e32 v122, v124, v122
	v_mul_f32_e32 v124, v123, v122
	v_fma_f32 v125, -v121, v124, v123
	v_fmac_f32_e32 v124, v125, v122
	v_fma_f32 v121, -v121, v124, v123
	v_div_fmas_f32 v121, v121, v122, v124
	v_lshl_add_u64 v[116:117], s[4:5], 0, v[116:117]
	v_div_fixup_f32 v120, v121, v120, 1.0
	v_or_b32_e32 v114, 32, v130
	v_mov_b32_e32 v115, v131
	v_lshl_add_u64 v[116:117], v[116:117], 0, v[134:135]
	v_pk_mul_f32 v[112:113], v[112:113], v[120:121] op_sel_hi:[1,0]
	v_pk_mul_f32 v[110:111], v[110:111], v[120:121] op_sel_hi:[1,0]
	v_lshl_add_u64 v[118:119], v[114:115], 2, s[6:7]
	v_pk_mul_f32 v[108:109], v[108:109], v[120:121] op_sel_hi:[1,0]
	v_pk_mul_f32 v[106:107], v[106:107], v[120:121] op_sel_hi:[1,0]
	v_pk_mul_f32 v[104:105], v[104:105], v[120:121] op_sel_hi:[1,0]
	v_pk_mul_f32 v[102:103], v[102:103], v[120:121] op_sel_hi:[1,0]
	v_pk_mul_f32 v[100:101], v[100:101], v[120:121] op_sel_hi:[1,0]
	v_pk_mul_f32 v[98:99], v[98:99], v[120:121] op_sel_hi:[1,0]
	global_store_dwordx4 v[116:117], v[110:113], off
	global_store_dwordx4 v[116:117], v[106:109], off offset:16
	global_store_dwordx4 v[116:117], v[102:105], off offset:512
	global_store_dwordx4 v[116:117], v[98:101], off offset:528
	global_load_dword v102, v[118:119], off
	s_waitcnt vmcnt(0)
	v_fmamk_f32 v104, v102, 0x39800000, v136
	v_div_scale_f32 v105, s[0:1], v104, v104, 1.0
	v_rcp_f32_e32 v106, v105
	v_div_scale_f32 v107, vcc, 1.0, v104, 1.0
	v_lshlrev_b64 v[100:101], 14, v[114:115]
	v_fma_f32 v108, -v105, v106, 1.0
	v_fmac_f32_e32 v106, v108, v106
	v_mul_f32_e32 v108, v107, v106
	v_fma_f32 v109, -v105, v108, v107
	v_fmac_f32_e32 v108, v109, v106
	v_fma_f32 v105, -v105, v108, v107
	v_div_fmas_f32 v105, v105, v106, v108
	v_lshl_add_u64 v[100:101], s[4:5], 0, v[100:101]
	v_div_fixup_f32 v104, v105, v104, 1.0
	v_or_b32_e32 v98, 48, v130
	v_mov_b32_e32 v99, v131
	v_lshl_add_u64 v[100:101], v[100:101], 0, v[134:135]
	v_pk_mul_f32 v[96:97], v[96:97], v[104:105] op_sel_hi:[1,0]
	v_pk_mul_f32 v[94:95], v[94:95], v[104:105] op_sel_hi:[1,0]
	v_lshl_add_u64 v[102:103], v[98:99], 2, s[6:7]
	v_pk_mul_f32 v[92:93], v[92:93], v[104:105] op_sel_hi:[1,0]
	v_pk_mul_f32 v[90:91], v[90:91], v[104:105] op_sel_hi:[1,0]
	v_pk_mul_f32 v[88:89], v[88:89], v[104:105] op_sel_hi:[1,0]
	v_pk_mul_f32 v[86:87], v[86:87], v[104:105] op_sel_hi:[1,0]
	v_pk_mul_f32 v[84:85], v[84:85], v[104:105] op_sel_hi:[1,0]
	v_pk_mul_f32 v[82:83], v[82:83], v[104:105] op_sel_hi:[1,0]
	global_store_dwordx4 v[100:101], v[94:97], off
	global_store_dwordx4 v[100:101], v[90:93], off offset:16
	global_store_dwordx4 v[100:101], v[86:89], off offset:512
	global_store_dwordx4 v[100:101], v[82:85], off offset:528
	global_load_dword v84, v[102:103], off
	s_nop 0
	v_lshlrev_b64 v[82:83], 14, v[98:99]
	v_lshl_add_u64 v[82:83], s[4:5], 0, v[82:83]
	v_lshl_add_u64 v[82:83], v[82:83], 0, v[134:135]
	s_waitcnt vmcnt(0)
	v_fmamk_f32 v84, v84, 0x39800000, v136
	v_div_scale_f32 v85, s[0:1], v84, v84, 1.0
	v_rcp_f32_e32 v86, v85
	v_div_scale_f32 v87, vcc, 1.0, v84, 1.0
	v_fma_f32 v88, -v85, v86, 1.0
	v_fmac_f32_e32 v86, v88, v86
	v_mul_f32_e32 v88, v87, v86
	v_fma_f32 v89, -v85, v88, v87
	v_fmac_f32_e32 v88, v89, v86
	v_fma_f32 v85, -v85, v88, v87
	v_div_fmas_f32 v85, v85, v86, v88
	v_div_fixup_f32 v84, v85, v84, 1.0
	v_pk_mul_f32 v[80:81], v[80:81], v[84:85] op_sel_hi:[1,0]
	v_pk_mul_f32 v[78:79], v[78:79], v[84:85] op_sel_hi:[1,0]
	v_pk_mul_f32 v[76:77], v[76:77], v[84:85] op_sel_hi:[1,0]
	v_pk_mul_f32 v[74:75], v[74:75], v[84:85] op_sel_hi:[1,0]
	v_pk_mul_f32 v[72:73], v[72:73], v[84:85] op_sel_hi:[1,0]
	v_pk_mul_f32 v[70:71], v[70:71], v[84:85] op_sel_hi:[1,0]
	v_pk_mul_f32 v[68:69], v[68:69], v[84:85] op_sel_hi:[1,0]
	v_pk_mul_f32 v[66:67], v[66:67], v[84:85] op_sel_hi:[1,0]
	global_store_dwordx4 v[82:83], v[78:81], off
	global_store_dwordx4 v[82:83], v[74:77], off offset:16
	global_store_dwordx4 v[82:83], v[70:73], off offset:512
	global_store_dwordx4 v[82:83], v[66:69], off offset:528
	global_load_dword v68, v[132:133], off offset:512
	s_nop 0
	v_add_u32_e32 v66, 0x80, v130
	v_mov_b32_e32 v67, v131
	v_lshlrev_b64 v[66:67], 14, v[66:67]
	v_lshl_add_u64 v[66:67], s[4:5], 0, v[66:67]
	v_lshl_add_u64 v[66:67], v[66:67], 0, v[134:135]
	s_waitcnt vmcnt(0)
	v_fmamk_f32 v68, v68, 0x39800000, v136
	v_div_scale_f32 v69, s[0:1], v68, v68, 1.0
	v_rcp_f32_e32 v70, v69
	v_div_scale_f32 v71, vcc, 1.0, v68, 1.0
	v_fma_f32 v72, -v69, v70, 1.0
	v_fmac_f32_e32 v70, v72, v70
	v_mul_f32_e32 v72, v71, v70
	v_fma_f32 v73, -v69, v72, v71
	v_fmac_f32_e32 v72, v73, v70
	v_fma_f32 v69, -v69, v72, v71
	v_div_fmas_f32 v69, v69, v70, v72
	v_div_fixup_f32 v68, v69, v68, 1.0
	v_pk_mul_f32 v[64:65], v[64:65], v[68:69] op_sel_hi:[1,0]
	v_pk_mul_f32 v[62:63], v[62:63], v[68:69] op_sel_hi:[1,0]
	v_pk_mul_f32 v[60:61], v[60:61], v[68:69] op_sel_hi:[1,0]
	v_pk_mul_f32 v[58:59], v[58:59], v[68:69] op_sel_hi:[1,0]
	v_pk_mul_f32 v[56:57], v[56:57], v[68:69] op_sel_hi:[1,0]
	v_pk_mul_f32 v[54:55], v[54:55], v[68:69] op_sel_hi:[1,0]
	v_pk_mul_f32 v[52:53], v[52:53], v[68:69] op_sel_hi:[1,0]
	v_pk_mul_f32 v[50:51], v[50:51], v[68:69] op_sel_hi:[1,0]
	global_store_dwordx4 v[66:67], v[62:65], off
	global_store_dwordx4 v[66:67], v[58:61], off offset:16
	global_store_dwordx4 v[66:67], v[54:57], off offset:512
	global_store_dwordx4 v[66:67], v[50:53], off offset:528
	global_load_dword v52, v[132:133], off offset:576
	s_nop 0
	v_add_u32_e32 v50, 0x90, v130
	v_mov_b32_e32 v51, v131
	v_lshlrev_b64 v[50:51], 14, v[50:51]
	v_lshl_add_u64 v[50:51], s[4:5], 0, v[50:51]
	v_lshl_add_u64 v[50:51], v[50:51], 0, v[134:135]
	s_waitcnt vmcnt(0)
	v_fmamk_f32 v52, v52, 0x39800000, v136
	v_div_scale_f32 v53, s[0:1], v52, v52, 1.0
	v_rcp_f32_e32 v54, v53
	v_div_scale_f32 v55, vcc, 1.0, v52, 1.0
	v_fma_f32 v56, -v53, v54, 1.0
	v_fmac_f32_e32 v54, v56, v54
	v_mul_f32_e32 v56, v55, v54
	v_fma_f32 v57, -v53, v56, v55
	v_fmac_f32_e32 v56, v57, v54
	v_fma_f32 v53, -v53, v56, v55
	v_div_fmas_f32 v53, v53, v54, v56
	v_div_fixup_f32 v52, v53, v52, 1.0
	v_pk_mul_f32 v[48:49], v[48:49], v[52:53] op_sel_hi:[1,0]
	v_pk_mul_f32 v[46:47], v[46:47], v[52:53] op_sel_hi:[1,0]
	v_pk_mul_f32 v[44:45], v[44:45], v[52:53] op_sel_hi:[1,0]
	v_pk_mul_f32 v[42:43], v[42:43], v[52:53] op_sel_hi:[1,0]
	v_pk_mul_f32 v[40:41], v[40:41], v[52:53] op_sel_hi:[1,0]
	v_pk_mul_f32 v[38:39], v[38:39], v[52:53] op_sel_hi:[1,0]
	v_pk_mul_f32 v[36:37], v[36:37], v[52:53] op_sel_hi:[1,0]
	v_pk_mul_f32 v[34:35], v[34:35], v[52:53] op_sel_hi:[1,0]
	global_store_dwordx4 v[50:51], v[46:49], off
	global_store_dwordx4 v[50:51], v[42:45], off offset:16
	global_store_dwordx4 v[50:51], v[38:41], off offset:512
	global_store_dwordx4 v[50:51], v[34:37], off offset:528
	global_load_dword v36, v[132:133], off offset:640
	s_nop 0
	v_add_u32_e32 v34, 0xa0, v130
	v_mov_b32_e32 v35, v131
	v_lshlrev_b64 v[34:35], 14, v[34:35]
	v_lshl_add_u64 v[34:35], s[4:5], 0, v[34:35]
	v_lshl_add_u64 v[34:35], v[34:35], 0, v[134:135]
	v_add_u32_e32 v130, 0xb0, v130
	s_waitcnt vmcnt(0)
	v_fmamk_f32 v36, v36, 0x39800000, v136
	v_div_scale_f32 v37, s[0:1], v36, v36, 1.0
	v_rcp_f32_e32 v38, v37
	v_div_scale_f32 v39, vcc, 1.0, v36, 1.0
	v_fma_f32 v40, -v37, v38, 1.0
	v_fmac_f32_e32 v38, v40, v38
	v_mul_f32_e32 v40, v39, v38
	v_fma_f32 v41, -v37, v40, v39
	v_fmac_f32_e32 v40, v41, v38
	v_fma_f32 v37, -v37, v40, v39
	v_div_fmas_f32 v37, v37, v38, v40
	v_div_fixup_f32 v36, v37, v36, 1.0
	v_pk_mul_f32 v[32:33], v[32:33], v[36:37] op_sel_hi:[1,0]
	v_pk_mul_f32 v[30:31], v[30:31], v[36:37] op_sel_hi:[1,0]
	v_pk_mul_f32 v[28:29], v[28:29], v[36:37] op_sel_hi:[1,0]
	v_pk_mul_f32 v[26:27], v[26:27], v[36:37] op_sel_hi:[1,0]
	v_pk_mul_f32 v[24:25], v[24:25], v[36:37] op_sel_hi:[1,0]
	v_pk_mul_f32 v[22:23], v[22:23], v[36:37] op_sel_hi:[1,0]
	v_pk_mul_f32 v[20:21], v[20:21], v[36:37] op_sel_hi:[1,0]
	v_pk_mul_f32 v[18:19], v[18:19], v[36:37] op_sel_hi:[1,0]
	global_store_dwordx4 v[34:35], v[30:33], off
	global_store_dwordx4 v[34:35], v[26:29], off offset:16
	global_store_dwordx4 v[34:35], v[22:25], off offset:512
	global_store_dwordx4 v[34:35], v[18:21], off offset:528
	global_load_dword v20, v[132:133], off offset:704
	s_waitcnt vmcnt(0)
	v_fmac_f32_e32 v136, 0x39800000, v20
	v_div_scale_f32 v20, s[0:1], v136, v136, 1.0
	v_rcp_f32_e32 v21, v20
	v_div_scale_f32 v22, vcc, 1.0, v136, 1.0
	v_lshlrev_b64 v[18:19], 14, v[130:131]
	v_fma_f32 v23, -v20, v21, 1.0
	v_fmac_f32_e32 v21, v23, v21
	v_mul_f32_e32 v23, v22, v21
	v_fma_f32 v24, -v20, v23, v22
	v_fmac_f32_e32 v23, v24, v21
	v_fma_f32 v20, -v20, v23, v22
	v_div_fmas_f32 v20, v20, v21, v23
	v_lshl_add_u64 v[18:19], s[4:5], 0, v[18:19]
	v_div_fixup_f32 v20, v20, v136, 1.0
	v_lshl_add_u64 v[18:19], v[18:19], 0, v[134:135]
	v_pk_mul_f32 v[16:17], v[16:17], v[20:21] op_sel_hi:[1,0]
	v_pk_mul_f32 v[14:15], v[14:15], v[20:21] op_sel_hi:[1,0]
	v_pk_mul_f32 v[12:13], v[12:13], v[20:21] op_sel_hi:[1,0]
	v_pk_mul_f32 v[10:11], v[10:11], v[20:21] op_sel_hi:[1,0]
	v_pk_mul_f32 v[8:9], v[8:9], v[20:21] op_sel_hi:[1,0]
	v_pk_mul_f32 v[6:7], v[6:7], v[20:21] op_sel_hi:[1,0]
	v_pk_mul_f32 v[4:5], v[4:5], v[20:21] op_sel_hi:[1,0]
	v_pk_mul_f32 v[2:3], v[2:3], v[20:21] op_sel_hi:[1,0]
	global_store_dwordx4 v[18:19], v[14:17], off
	global_store_dwordx4 v[18:19], v[10:13], off offset:16
	global_store_dwordx4 v[18:19], v[6:9], off offset:512
	global_store_dwordx4 v[18:19], v[2:5], off offset:528
	s_waitcnt vmcnt(0)
	s_cbranch_scc0 .LBB0_876
	s_barrier

.LBB0_896:
	s_ashr_i32 s35, s34, 31
	s_lshl_b64 s[36:37], s[34:35], 23
	s_add_u32 s36, s86, s36
	s_addc_u32 s37, s87, s37
	s_and_b64 s[38:39], s[0:1], exec
	s_cselect_b32 s35, s37, s43
	s_cselect_b32 s63, s36, s42
	s_ashr_i32 s31, s30, 31
	s_lshl_b64 s[38:39], s[30:31], 23
	s_add_u32 s38, s10, s38
	s_addc_u32 s39, s11, s39
	s_and_b64 s[46:47], s[0:1], exec
	s_cselect_b32 s31, s39, s45
	s_cselect_b32 s64, s38, s44
	s_add_u32 s42, s42, 0x400080
	s_addc_u32 s43, s43, 0
	s_add_u32 s65, s44, 0x100
	s_addc_u32 s66, s45, 0
	s_mov_b32 s67, -2
	ds_read_b128 v[146:149], v156
	ds_read_b128 v[150:153], v156 offset:1024
	ds_read_b128 v[160:163], v156 offset:2048
	ds_read_b128 v[164:167], v156 offset:3072
	ds_read_b128 v[168:171], v157
	ds_read_b128 v[172:175], v157 offset:1024
	ds_read_b128 v[176:179], v157 offset:2048
	ds_read_b128 v[180:183], v157 offset:3072
	s_add_u32 s44, s42, 0xffc00080
	s_addc_u32 s45, s43, -1
	s_cmpk_eq_i32 s67, 0xfc
	s_cselect_b32 s47, s35, s45
	s_cselect_b32 s46, s63, s44
	s_cselect_b32 s45, s31, s66
	s_cselect_b32 s44, s64, s65
	s_add_i32 m0, s41, 0xc000
	ds_read_b128 v[184:187], v158
	ds_read_b128 v[188:191], v158 offset:1024
	ds_read_b128 v[192:195], v158 offset:2048
	ds_read_b128 v[198:201], v158 offset:3072
	ds_read_b128 v[202:205], v158 offset:4096
	ds_read_b128 v[206:209], v158 offset:5120
	ds_read_b128 v[210:213], v158 offset:6144
	ds_read_b128 v[214:217], v158 offset:7168
	global_load_lds_dwordx4 v138, s[42:43]
	s_add_i32 m0, s41, 0xe000
	s_nop 0
	global_load_lds_dwordx4 v140, s[42:43]
	s_waitcnt vmcnt(24)
	s_waitcnt lgkmcnt(0)
	s_setprio 1
	s_barrier
	v_mfma_f32_16x16x32_bf16 v[126:129], v[146:149], v[184:187], 0
	v_mfma_f32_16x16x32_bf16 v[122:125], v[160:163], v[184:187], 0
	v_mfma_f32_16x16x32_bf16 v[110:113], v[146:149], v[192:195], 0
	v_mfma_f32_16x16x32_bf16 v[106:109], v[160:163], v[192:195], 0
	v_mfma_f32_16x16x32_bf16 v[94:97], v[146:149], v[202:205], 0
	v_mfma_f32_16x16x32_bf16 v[90:93], v[160:163], v[202:205], 0
	v_mfma_f32_16x16x32_bf16 v[78:81], v[146:149], v[210:213], 0
	v_mfma_f32_16x16x32_bf16 v[74:77], v[160:163], v[210:213], 0
	v_mfma_f32_16x16x32_bf16 v[126:129], v[150:153], v[188:191], v[126:129]
	v_mfma_f32_16x16x32_bf16 v[122:125], v[164:167], v[188:191], v[122:125]
	v_mfma_f32_16x16x32_bf16 v[110:113], v[150:153], v[198:201], v[110:113]
	v_mfma_f32_16x16x32_bf16 v[106:109], v[164:167], v[198:201], v[106:109]
	v_mfma_f32_16x16x32_bf16 v[94:97], v[150:153], v[206:209], v[94:97]
	v_mfma_f32_16x16x32_bf16 v[90:93], v[164:167], v[206:209], v[90:93]
	v_mfma_f32_16x16x32_bf16 v[78:81], v[150:153], v[214:217], v[78:81]
	v_mfma_f32_16x16x32_bf16 v[74:77], v[164:167], v[214:217], v[74:77]
	v_mfma_f32_16x16x32_bf16 v[118:121], v[168:171], v[184:187], 0
	v_mfma_f32_16x16x32_bf16 v[114:117], v[176:179], v[184:187], 0
	v_mfma_f32_16x16x32_bf16 v[102:105], v[168:171], v[192:195], 0
	v_mfma_f32_16x16x32_bf16 v[98:101], v[176:179], v[192:195], 0
	v_mfma_f32_16x16x32_bf16 v[86:89], v[168:171], v[202:205], 0
	v_mfma_f32_16x16x32_bf16 v[82:85], v[176:179], v[202:205], 0
	v_mfma_f32_16x16x32_bf16 v[70:73], v[168:171], v[210:213], 0
	v_mfma_f32_16x16x32_bf16 v[66:69], v[176:179], v[210:213], 0
	v_mfma_f32_16x16x32_bf16 v[118:121], v[172:175], v[188:191], v[118:121]
	v_mfma_f32_16x16x32_bf16 v[114:117], v[180:183], v[188:191], v[114:117]
	v_mfma_f32_16x16x32_bf16 v[102:105], v[172:175], v[198:201], v[102:105]
	v_mfma_f32_16x16x32_bf16 v[98:101], v[180:183], v[198:201], v[98:101]
	v_mfma_f32_16x16x32_bf16 v[86:89], v[172:175], v[206:209], v[86:89]
	v_mfma_f32_16x16x32_bf16 v[82:85], v[180:183], v[206:209], v[82:85]
	v_mfma_f32_16x16x32_bf16 v[70:73], v[172:175], v[214:217], v[70:73]
	v_mfma_f32_16x16x32_bf16 v[66:69], v[180:183], v[214:217], v[66:69]
	s_barrier
	s_setprio 0
	s_add_i32 s68, s56, s48
	s_mov_b32 m0, s68
	ds_read_b128 v[184:187], v158 offset:16384
	ds_read_b128 v[188:191], v158 offset:17408
	ds_read_b128 v[192:195], v158 offset:18432
	ds_read_b128 v[198:201], v158 offset:19456
	ds_read_b128 v[202:205], v158 offset:20480
	ds_read_b128 v[206:209], v158 offset:21504
	ds_read_b128 v[210:213], v158 offset:22528
	ds_read_b128 v[214:217], v158 offset:23552
	global_load_lds_dwordx4 v132, s[44:45]
	s_add_i32 m0, s68, 0x2000
	s_add_u32 s68, s44, 0x400000
	s_addc_u32 s69, s45, 0
	s_add_i32 s70, s57, s48
	global_load_lds_dwordx4 v136, s[44:45]
	s_mov_b32 m0, s70
	global_load_lds_dwordx4 v132, s[68:69]
	s_add_i32 m0, s70, 0x2000
	s_nop 0
	global_load_lds_dwordx4 v136, s[68:69]
	s_mov_b32 m0, s41
	s_nop 0
	global_load_lds_dwordx4 v130, s[46:47]
	s_mov_b32 m0, s49
	s_nop 0
	global_load_lds_dwordx4 v134, s[46:47]
	s_waitcnt vmcnt(24)
	s_waitcnt lgkmcnt(0)
	s_setprio 1
	s_barrier
	v_mfma_f32_16x16x32_bf16 v[62:65], v[146:149], v[184:187], 0
	v_mfma_f32_16x16x32_bf16 v[58:61], v[160:163], v[184:187], 0
	v_mfma_f32_16x16x32_bf16 v[46:49], v[146:149], v[192:195], 0
	v_mfma_f32_16x16x32_bf16 v[42:45], v[160:163], v[192:195], 0
	v_mfma_f32_16x16x32_bf16 v[30:33], v[146:149], v[202:205], 0
	v_mfma_f32_16x16x32_bf16 v[26:29], v[160:163], v[202:205], 0
	v_mfma_f32_16x16x32_bf16 v[14:17], v[146:149], v[210:213], 0
	v_mfma_f32_16x16x32_bf16 v[10:13], v[160:163], v[210:213], 0
	v_mfma_f32_16x16x32_bf16 v[62:65], v[150:153], v[188:191], v[62:65]
	v_mfma_f32_16x16x32_bf16 v[58:61], v[164:167], v[188:191], v[58:61]
	v_mfma_f32_16x16x32_bf16 v[46:49], v[150:153], v[198:201], v[46:49]
	v_mfma_f32_16x16x32_bf16 v[42:45], v[164:167], v[198:201], v[42:45]
	v_mfma_f32_16x16x32_bf16 v[30:33], v[150:153], v[206:209], v[30:33]
	v_mfma_f32_16x16x32_bf16 v[26:29], v[164:167], v[206:209], v[26:29]
	v_mfma_f32_16x16x32_bf16 v[14:17], v[150:153], v[214:217], v[14:17]
	v_mfma_f32_16x16x32_bf16 v[10:13], v[164:167], v[214:217], v[10:13]
	v_mfma_f32_16x16x32_bf16 v[54:57], v[168:171], v[184:187], 0
	v_mfma_f32_16x16x32_bf16 v[50:53], v[176:179], v[184:187], 0
	v_mfma_f32_16x16x32_bf16 v[38:41], v[168:171], v[192:195], 0
	v_mfma_f32_16x16x32_bf16 v[34:37], v[176:179], v[192:195], 0
	v_mfma_f32_16x16x32_bf16 v[22:25], v[168:171], v[202:205], 0
	v_mfma_f32_16x16x32_bf16 v[18:21], v[176:179], v[202:205], 0
	v_mfma_f32_16x16x32_bf16 v[6:9], v[168:171], v[210:213], 0
	v_mfma_f32_16x16x32_bf16 v[2:5], v[176:179], v[210:213], 0
	v_mfma_f32_16x16x32_bf16 v[54:57], v[172:175], v[188:191], v[54:57]
	v_mfma_f32_16x16x32_bf16 v[50:53], v[180:183], v[188:191], v[50:53]
	v_mfma_f32_16x16x32_bf16 v[38:41], v[172:175], v[198:201], v[38:41]
	v_mfma_f32_16x16x32_bf16 v[34:37], v[180:183], v[198:201], v[34:37]
	v_mfma_f32_16x16x32_bf16 v[22:25], v[172:175], v[206:209], v[22:25]
	v_mfma_f32_16x16x32_bf16 v[18:21], v[180:183], v[206:209], v[18:21]
	v_mfma_f32_16x16x32_bf16 v[6:9], v[172:175], v[214:217], v[6:9]
	v_mfma_f32_16x16x32_bf16 v[2:5], v[180:183], v[214:217], v[2:5]
	s_barrier
	s_setprio 0
	s_add_i32 s68, 0, 0x18000
	s_add_i32 s69, 0, 0x1c000
	v_add_u32_e32 v164, s68, v154
	v_add_u32_e32 v180, s69, v154
	ds_read_b128 v[146:149], v164
	ds_read_b128 v[150:153], v164 offset:1024
	ds_read_b128 v[160:163], v164 offset:2048
	ds_read_b128 v[164:167], v164 offset:3072
	ds_read_b128 v[168:171], v180
	ds_read_b128 v[172:175], v180 offset:1024
	ds_read_b128 v[176:179], v180 offset:2048
	ds_read_b128 v[180:183], v180 offset:3072
	s_add_u32 s46, s46, 0x400000
	s_addc_u32 s47, s47, 0
	s_mov_b32 m0, s50
	ds_read_b128 v[184:187], v158 offset:32768
	ds_read_b128 v[188:191], v158 offset:33792
	ds_read_b128 v[192:195], v158 offset:34816
	ds_read_b128 v[198:201], v158 offset:35840
	ds_read_b128 v[202:205], v158 offset:36864
	ds_read_b128 v[206:209], v158 offset:37888
	ds_read_b128 v[210:213], v158 offset:38912
	ds_read_b128 v[214:217], v158 offset:39936
	global_load_lds_dwordx4 v130, s[46:47]
	s_mov_b32 m0, s51
	s_nop 0
	global_load_lds_dwordx4 v134, s[46:47]
	s_waitcnt vmcnt(8)
	s_waitcnt lgkmcnt(0)
	s_setprio 1
	s_barrier
	v_mfma_f32_16x16x32_bf16 v[126:129], v[146:149], v[184:187], v[126:129]
	v_mfma_f32_16x16x32_bf16 v[122:125], v[160:163], v[184:187], v[122:125]
	v_mfma_f32_16x16x32_bf16 v[110:113], v[146:149], v[192:195], v[110:113]
	v_mfma_f32_16x16x32_bf16 v[106:109], v[160:163], v[192:195], v[106:109]
	v_mfma_f32_16x16x32_bf16 v[94:97], v[146:149], v[202:205], v[94:97]
	v_mfma_f32_16x16x32_bf16 v[90:93], v[160:163], v[202:205], v[90:93]
	v_mfma_f32_16x16x32_bf16 v[78:81], v[146:149], v[210:213], v[78:81]
	v_mfma_f32_16x16x32_bf16 v[74:77], v[160:163], v[210:213], v[74:77]
	v_mfma_f32_16x16x32_bf16 v[126:129], v[150:153], v[188:191], v[126:129]
	v_mfma_f32_16x16x32_bf16 v[122:125], v[164:167], v[188:191], v[122:125]
	v_mfma_f32_16x16x32_bf16 v[110:113], v[150:153], v[198:201], v[110:113]
	v_mfma_f32_16x16x32_bf16 v[106:109], v[164:167], v[198:201], v[106:109]
	v_mfma_f32_16x16x32_bf16 v[94:97], v[150:153], v[206:209], v[94:97]
	v_mfma_f32_16x16x32_bf16 v[90:93], v[164:167], v[206:209], v[90:93]
	v_mfma_f32_16x16x32_bf16 v[78:81], v[150:153], v[214:217], v[78:81]
	v_mfma_f32_16x16x32_bf16 v[74:77], v[164:167], v[214:217], v[74:77]
	v_mfma_f32_16x16x32_bf16 v[118:121], v[168:171], v[184:187], v[118:121]
	v_mfma_f32_16x16x32_bf16 v[114:117], v[176:179], v[184:187], v[114:117]
	v_mfma_f32_16x16x32_bf16 v[102:105], v[168:171], v[192:195], v[102:105]
	v_mfma_f32_16x16x32_bf16 v[98:101], v[176:179], v[192:195], v[98:101]
	v_mfma_f32_16x16x32_bf16 v[86:89], v[168:171], v[202:205], v[86:89]
	v_mfma_f32_16x16x32_bf16 v[82:85], v[176:179], v[202:205], v[82:85]
	v_mfma_f32_16x16x32_bf16 v[70:73], v[168:171], v[210:213], v[70:73]
	v_mfma_f32_16x16x32_bf16 v[66:69], v[176:179], v[210:213], v[66:69]
	v_mfma_f32_16x16x32_bf16 v[118:121], v[172:175], v[188:191], v[118:121]
	v_mfma_f32_16x16x32_bf16 v[114:117], v[180:183], v[188:191], v[114:117]
	v_mfma_f32_16x16x32_bf16 v[102:105], v[172:175], v[198:201], v[102:105]
	v_mfma_f32_16x16x32_bf16 v[98:101], v[180:183], v[198:201], v[98:101]
	v_mfma_f32_16x16x32_bf16 v[86:89], v[172:175], v[206:209], v[86:89]
	v_mfma_f32_16x16x32_bf16 v[82:85], v[180:183], v[206:209], v[82:85]
	v_mfma_f32_16x16x32_bf16 v[70:73], v[172:175], v[214:217], v[70:73]
	v_mfma_f32_16x16x32_bf16 v[66:69], v[180:183], v[214:217], v[66:69]
	s_barrier
	s_setprio 0
	s_add_u32 s44, s44, 0x80
	s_addc_u32 s45, s45, 0
	s_add_i32 m0, s48, 0x18000
	ds_read_b128 v[184:187], v158 offset:49152
	ds_read_b128 v[188:191], v158 offset:50176
	ds_read_b128 v[192:195], v158 offset:51200
	ds_read_b128 v[198:201], v158 offset:52224
	ds_read_b128 v[202:205], v158 offset:53248
	ds_read_b128 v[206:209], v158 offset:54272
	ds_read_b128 v[210:213], v158 offset:55296
	ds_read_b128 v[214:217], v158 offset:56320
	global_load_lds_dwordx4 v132, s[44:45]
	s_add_i32 m0, s48, 0x1a000
	s_add_u32 s46, s46, 0xffc00080
	global_load_lds_dwordx4 v136, s[44:45]
	s_addc_u32 s47, s47, -1
	s_add_u32 s44, s44, 0x400000
	s_addc_u32 s45, s45, 0
	s_add_i32 m0, s48, 0x1c000
	s_nop 0
	global_load_lds_dwordx4 v132, s[44:45]
	s_add_i32 m0, s48, 0x1e000
	s_nop 0
	global_load_lds_dwordx4 v136, s[44:45]
	s_mov_b32 m0, s53
	s_nop 0
	global_load_lds_dwordx4 v130, s[46:47]
	s_mov_b32 m0, s54
	s_nop 0
	global_load_lds_dwordx4 v134, s[46:47]
	s_add_i32 s67, s67, 2
	s_add_u32 s42, s42, 0x100
	s_addc_u32 s43, s43, 0
	s_add_u32 s65, s65, 0x100
	s_addc_u32 s66, s66, 0
	s_cmpk_gt_u32 s67, 0xfd
	s_waitcnt vmcnt(8)
	s_waitcnt lgkmcnt(0)
	s_setprio 1
	s_barrier
	v_mfma_f32_16x16x32_bf16 v[62:65], v[146:149], v[184:187], v[62:65]
	v_mfma_f32_16x16x32_bf16 v[58:61], v[160:163], v[184:187], v[58:61]
	v_mfma_f32_16x16x32_bf16 v[46:49], v[146:149], v[192:195], v[46:49]
	v_mfma_f32_16x16x32_bf16 v[42:45], v[160:163], v[192:195], v[42:45]
	v_mfma_f32_16x16x32_bf16 v[30:33], v[146:149], v[202:205], v[30:33]
	v_mfma_f32_16x16x32_bf16 v[26:29], v[160:163], v[202:205], v[26:29]
	v_mfma_f32_16x16x32_bf16 v[14:17], v[146:149], v[210:213], v[14:17]
	v_mfma_f32_16x16x32_bf16 v[10:13], v[160:163], v[210:213], v[10:13]
	v_mfma_f32_16x16x32_bf16 v[62:65], v[150:153], v[188:191], v[62:65]
	v_mfma_f32_16x16x32_bf16 v[58:61], v[164:167], v[188:191], v[58:61]
	v_mfma_f32_16x16x32_bf16 v[46:49], v[150:153], v[198:201], v[46:49]
	v_mfma_f32_16x16x32_bf16 v[42:45], v[164:167], v[198:201], v[42:45]
	v_mfma_f32_16x16x32_bf16 v[30:33], v[150:153], v[206:209], v[30:33]
	v_mfma_f32_16x16x32_bf16 v[26:29], v[164:167], v[206:209], v[26:29]
	v_mfma_f32_16x16x32_bf16 v[14:17], v[150:153], v[214:217], v[14:17]
	v_mfma_f32_16x16x32_bf16 v[10:13], v[164:167], v[214:217], v[10:13]
	v_mfma_f32_16x16x32_bf16 v[54:57], v[168:171], v[184:187], v[54:57]
	v_mfma_f32_16x16x32_bf16 v[50:53], v[176:179], v[184:187], v[50:53]
	v_mfma_f32_16x16x32_bf16 v[38:41], v[168:171], v[192:195], v[38:41]
	v_mfma_f32_16x16x32_bf16 v[34:37], v[176:179], v[192:195], v[34:37]
	v_mfma_f32_16x16x32_bf16 v[22:25], v[168:171], v[202:205], v[22:25]
	v_mfma_f32_16x16x32_bf16 v[18:21], v[176:179], v[202:205], v[18:21]
	v_mfma_f32_16x16x32_bf16 v[6:9], v[168:171], v[210:213], v[6:9]
	v_mfma_f32_16x16x32_bf16 v[2:5], v[176:179], v[210:213], v[2:5]
	v_mfma_f32_16x16x32_bf16 v[54:57], v[172:175], v[188:191], v[54:57]
	v_mfma_f32_16x16x32_bf16 v[50:53], v[180:183], v[188:191], v[50:53]
	v_mfma_f32_16x16x32_bf16 v[38:41], v[172:175], v[198:201], v[38:41]
	v_mfma_f32_16x16x32_bf16 v[34:37], v[180:183], v[198:201], v[34:37]
	v_mfma_f32_16x16x32_bf16 v[22:25], v[172:175], v[206:209], v[22:25]
	v_mfma_f32_16x16x32_bf16 v[18:21], v[180:183], v[206:209], v[18:21]
	v_mfma_f32_16x16x32_bf16 v[6:9], v[172:175], v[214:217], v[6:9]
	v_mfma_f32_16x16x32_bf16 v[2:5], v[180:183], v[214:217], v[2:5]
	s_barrier
	s_setprio 0
	.p2align	8
.LBB0_897:
	ds_read_b128 v[146:149], v156
	ds_read_b128 v[150:153], v156 offset:1024
	ds_read_b128 v[160:163], v156 offset:2048
	ds_read_b128 v[164:167], v156 offset:3072
	ds_read_b128 v[168:171], v157
	ds_read_b128 v[172:175], v157 offset:1024
	ds_read_b128 v[176:179], v157 offset:2048
	ds_read_b128 v[180:183], v157 offset:3072
	s_add_u32 s44, s42, 0xffc00080
	s_addc_u32 s45, s43, -1
	s_cmpk_eq_i32 s67, 0xfc
	s_cselect_b32 s47, s35, s45
	s_cselect_b32 s46, s63, s44
	s_cselect_b32 s45, s31, s66
	s_cselect_b32 s44, s64, s65
	s_add_i32 m0, s41, 0xc000
	ds_read_b128 v[184:187], v158
	ds_read_b128 v[188:191], v158 offset:1024
	ds_read_b128 v[192:195], v158 offset:2048
	ds_read_b128 v[198:201], v158 offset:3072
	ds_read_b128 v[202:205], v158 offset:4096
	ds_read_b128 v[206:209], v158 offset:5120
	ds_read_b128 v[210:213], v158 offset:6144
	ds_read_b128 v[214:217], v158 offset:7168
	global_load_lds_dwordx4 v138, s[42:43]
	s_add_i32 m0, s41, 0xe000
	s_nop 0
	global_load_lds_dwordx4 v140, s[42:43]
	s_waitcnt vmcnt(8)
	s_waitcnt lgkmcnt(0)
	s_setprio 1
	s_barrier
	v_mfma_f32_16x16x32_bf16 v[126:129], v[146:149], v[184:187], v[126:129]
	v_mfma_f32_16x16x32_bf16 v[122:125], v[160:163], v[184:187], v[122:125]
	v_mfma_f32_16x16x32_bf16 v[110:113], v[146:149], v[192:195], v[110:113]
	v_mfma_f32_16x16x32_bf16 v[106:109], v[160:163], v[192:195], v[106:109]
	v_mfma_f32_16x16x32_bf16 v[94:97], v[146:149], v[202:205], v[94:97]
	v_mfma_f32_16x16x32_bf16 v[90:93], v[160:163], v[202:205], v[90:93]
	v_mfma_f32_16x16x32_bf16 v[78:81], v[146:149], v[210:213], v[78:81]
	v_mfma_f32_16x16x32_bf16 v[74:77], v[160:163], v[210:213], v[74:77]
	v_mfma_f32_16x16x32_bf16 v[126:129], v[150:153], v[188:191], v[126:129]
	v_mfma_f32_16x16x32_bf16 v[122:125], v[164:167], v[188:191], v[122:125]
	v_mfma_f32_16x16x32_bf16 v[110:113], v[150:153], v[198:201], v[110:113]
	v_mfma_f32_16x16x32_bf16 v[106:109], v[164:167], v[198:201], v[106:109]
	v_mfma_f32_16x16x32_bf16 v[94:97], v[150:153], v[206:209], v[94:97]
	v_mfma_f32_16x16x32_bf16 v[90:93], v[164:167], v[206:209], v[90:93]
	v_mfma_f32_16x16x32_bf16 v[78:81], v[150:153], v[214:217], v[78:81]
	v_mfma_f32_16x16x32_bf16 v[74:77], v[164:167], v[214:217], v[74:77]
	v_mfma_f32_16x16x32_bf16 v[118:121], v[168:171], v[184:187], v[118:121]
	v_mfma_f32_16x16x32_bf16 v[114:117], v[176:179], v[184:187], v[114:117]
	v_mfma_f32_16x16x32_bf16 v[102:105], v[168:171], v[192:195], v[102:105]
	v_mfma_f32_16x16x32_bf16 v[98:101], v[176:179], v[192:195], v[98:101]
	v_mfma_f32_16x16x32_bf16 v[86:89], v[168:171], v[202:205], v[86:89]
	v_mfma_f32_16x16x32_bf16 v[82:85], v[176:179], v[202:205], v[82:85]
	v_mfma_f32_16x16x32_bf16 v[70:73], v[168:171], v[210:213], v[70:73]
	v_mfma_f32_16x16x32_bf16 v[66:69], v[176:179], v[210:213], v[66:69]
	v_mfma_f32_16x16x32_bf16 v[118:121], v[172:175], v[188:191], v[118:121]
	v_mfma_f32_16x16x32_bf16 v[114:117], v[180:183], v[188:191], v[114:117]
	v_mfma_f32_16x16x32_bf16 v[102:105], v[172:175], v[198:201], v[102:105]
	v_mfma_f32_16x16x32_bf16 v[98:101], v[180:183], v[198:201], v[98:101]
	v_mfma_f32_16x16x32_bf16 v[86:89], v[172:175], v[206:209], v[86:89]
	v_mfma_f32_16x16x32_bf16 v[82:85], v[180:183], v[206:209], v[82:85]
	v_mfma_f32_16x16x32_bf16 v[70:73], v[172:175], v[214:217], v[70:73]
	v_mfma_f32_16x16x32_bf16 v[66:69], v[180:183], v[214:217], v[66:69]
	s_barrier
	s_setprio 0
	s_add_i32 s68, s56, s48
	s_mov_b32 m0, s68
	ds_read_b128 v[184:187], v158 offset:16384
	ds_read_b128 v[188:191], v158 offset:17408
	ds_read_b128 v[192:195], v158 offset:18432
	ds_read_b128 v[198:201], v158 offset:19456
	ds_read_b128 v[202:205], v158 offset:20480
	ds_read_b128 v[206:209], v158 offset:21504
	ds_read_b128 v[210:213], v158 offset:22528
	ds_read_b128 v[214:217], v158 offset:23552
	global_load_lds_dwordx4 v132, s[44:45]
	s_add_i32 m0, s68, 0x2000
	s_add_u32 s68, s44, 0x400000
	s_addc_u32 s69, s45, 0
	s_add_i32 s70, s57, s48
	global_load_lds_dwordx4 v136, s[44:45]
	s_mov_b32 m0, s70
	global_load_lds_dwordx4 v132, s[68:69]
	s_add_i32 m0, s70, 0x2000
	s_nop 0
	global_load_lds_dwordx4 v136, s[68:69]
	s_mov_b32 m0, s41
	s_nop 0
	global_load_lds_dwordx4 v130, s[46:47]
	s_mov_b32 m0, s49
	s_nop 0
	global_load_lds_dwordx4 v134, s[46:47]
	s_waitcnt vmcnt(8)
	s_waitcnt lgkmcnt(0)
	s_setprio 1
	s_barrier
	v_mfma_f32_16x16x32_bf16 v[62:65], v[146:149], v[184:187], v[62:65]
	v_mfma_f32_16x16x32_bf16 v[58:61], v[160:163], v[184:187], v[58:61]
	v_mfma_f32_16x16x32_bf16 v[46:49], v[146:149], v[192:195], v[46:49]
	v_mfma_f32_16x16x32_bf16 v[42:45], v[160:163], v[192:195], v[42:45]
	v_mfma_f32_16x16x32_bf16 v[30:33], v[146:149], v[202:205], v[30:33]
	v_mfma_f32_16x16x32_bf16 v[26:29], v[160:163], v[202:205], v[26:29]
	v_mfma_f32_16x16x32_bf16 v[14:17], v[146:149], v[210:213], v[14:17]
	v_mfma_f32_16x16x32_bf16 v[10:13], v[160:163], v[210:213], v[10:13]
	v_mfma_f32_16x16x32_bf16 v[62:65], v[150:153], v[188:191], v[62:65]
	v_mfma_f32_16x16x32_bf16 v[58:61], v[164:167], v[188:191], v[58:61]
	v_mfma_f32_16x16x32_bf16 v[46:49], v[150:153], v[198:201], v[46:49]
	v_mfma_f32_16x16x32_bf16 v[42:45], v[164:167], v[198:201], v[42:45]
	v_mfma_f32_16x16x32_bf16 v[30:33], v[150:153], v[206:209], v[30:33]
	v_mfma_f32_16x16x32_bf16 v[26:29], v[164:167], v[206:209], v[26:29]
	v_mfma_f32_16x16x32_bf16 v[14:17], v[150:153], v[214:217], v[14:17]
	v_mfma_f32_16x16x32_bf16 v[10:13], v[164:167], v[214:217], v[10:13]
	v_mfma_f32_16x16x32_bf16 v[54:57], v[168:171], v[184:187], v[54:57]
	v_mfma_f32_16x16x32_bf16 v[50:53], v[176:179], v[184:187], v[50:53]
	v_mfma_f32_16x16x32_bf16 v[38:41], v[168:171], v[192:195], v[38:41]
	v_mfma_f32_16x16x32_bf16 v[34:37], v[176:179], v[192:195], v[34:37]
	v_mfma_f32_16x16x32_bf16 v[22:25], v[168:171], v[202:205], v[22:25]
	v_mfma_f32_16x16x32_bf16 v[18:21], v[176:179], v[202:205], v[18:21]
	v_mfma_f32_16x16x32_bf16 v[6:9], v[168:171], v[210:213], v[6:9]
	v_mfma_f32_16x16x32_bf16 v[2:5], v[176:179], v[210:213], v[2:5]
	v_mfma_f32_16x16x32_bf16 v[54:57], v[172:175], v[188:191], v[54:57]
	v_mfma_f32_16x16x32_bf16 v[50:53], v[180:183], v[188:191], v[50:53]
	v_mfma_f32_16x16x32_bf16 v[38:41], v[172:175], v[198:201], v[38:41]
	v_mfma_f32_16x16x32_bf16 v[34:37], v[180:183], v[198:201], v[34:37]
	v_mfma_f32_16x16x32_bf16 v[22:25], v[172:175], v[206:209], v[22:25]
	v_mfma_f32_16x16x32_bf16 v[18:21], v[180:183], v[206:209], v[18:21]
	v_mfma_f32_16x16x32_bf16 v[6:9], v[172:175], v[214:217], v[6:9]
	v_mfma_f32_16x16x32_bf16 v[2:5], v[180:183], v[214:217], v[2:5]
	s_barrier
	s_setprio 0
	s_add_i32 s68, 0, 0x18000
	s_add_i32 s69, 0, 0x1c000
	v_add_u32_e32 v164, s68, v154
	v_add_u32_e32 v180, s69, v154
	ds_read_b128 v[146:149], v164
	ds_read_b128 v[150:153], v164 offset:1024
	ds_read_b128 v[160:163], v164 offset:2048
	ds_read_b128 v[164:167], v164 offset:3072
	ds_read_b128 v[168:171], v180
	ds_read_b128 v[172:175], v180 offset:1024
	ds_read_b128 v[176:179], v180 offset:2048
	ds_read_b128 v[180:183], v180 offset:3072
	s_add_u32 s46, s46, 0x400000
	s_addc_u32 s47, s47, 0
	s_mov_b32 m0, s50
	ds_read_b128 v[184:187], v158 offset:32768
	ds_read_b128 v[188:191], v158 offset:33792
	ds_read_b128 v[192:195], v158 offset:34816
	ds_read_b128 v[198:201], v158 offset:35840
	ds_read_b128 v[202:205], v158 offset:36864
	ds_read_b128 v[206:209], v158 offset:37888
	ds_read_b128 v[210:213], v158 offset:38912
	ds_read_b128 v[214:217], v158 offset:39936
	global_load_lds_dwordx4 v130, s[46:47]
	s_mov_b32 m0, s51
	s_nop 0
	global_load_lds_dwordx4 v134, s[46:47]
	s_waitcnt vmcnt(8)
	s_waitcnt lgkmcnt(0)
	s_setprio 1
	s_barrier
	v_mfma_f32_16x16x32_bf16 v[126:129], v[146:149], v[184:187], v[126:129]
	v_mfma_f32_16x16x32_bf16 v[122:125], v[160:163], v[184:187], v[122:125]
	v_mfma_f32_16x16x32_bf16 v[110:113], v[146:149], v[192:195], v[110:113]
	v_mfma_f32_16x16x32_bf16 v[106:109], v[160:163], v[192:195], v[106:109]
	v_mfma_f32_16x16x32_bf16 v[94:97], v[146:149], v[202:205], v[94:97]
	v_mfma_f32_16x16x32_bf16 v[90:93], v[160:163], v[202:205], v[90:93]
	v_mfma_f32_16x16x32_bf16 v[78:81], v[146:149], v[210:213], v[78:81]
	v_mfma_f32_16x16x32_bf16 v[74:77], v[160:163], v[210:213], v[74:77]
	v_mfma_f32_16x16x32_bf16 v[126:129], v[150:153], v[188:191], v[126:129]
	v_mfma_f32_16x16x32_bf16 v[122:125], v[164:167], v[188:191], v[122:125]
	v_mfma_f32_16x16x32_bf16 v[110:113], v[150:153], v[198:201], v[110:113]
	v_mfma_f32_16x16x32_bf16 v[106:109], v[164:167], v[198:201], v[106:109]
	v_mfma_f32_16x16x32_bf16 v[94:97], v[150:153], v[206:209], v[94:97]
	v_mfma_f32_16x16x32_bf16 v[90:93], v[164:167], v[206:209], v[90:93]
	v_mfma_f32_16x16x32_bf16 v[78:81], v[150:153], v[214:217], v[78:81]
	v_mfma_f32_16x16x32_bf16 v[74:77], v[164:167], v[214:217], v[74:77]
	v_mfma_f32_16x16x32_bf16 v[118:121], v[168:171], v[184:187], v[118:121]
	v_mfma_f32_16x16x32_bf16 v[114:117], v[176:179], v[184:187], v[114:117]
	v_mfma_f32_16x16x32_bf16 v[102:105], v[168:171], v[192:195], v[102:105]
	v_mfma_f32_16x16x32_bf16 v[98:101], v[176:179], v[192:195], v[98:101]
	v_mfma_f32_16x16x32_bf16 v[86:89], v[168:171], v[202:205], v[86:89]
	v_mfma_f32_16x16x32_bf16 v[82:85], v[176:179], v[202:205], v[82:85]
	v_mfma_f32_16x16x32_bf16 v[70:73], v[168:171], v[210:213], v[70:73]
	v_mfma_f32_16x16x32_bf16 v[66:69], v[176:179], v[210:213], v[66:69]
	v_mfma_f32_16x16x32_bf16 v[118:121], v[172:175], v[188:191], v[118:121]
	v_mfma_f32_16x16x32_bf16 v[114:117], v[180:183], v[188:191], v[114:117]
	v_mfma_f32_16x16x32_bf16 v[102:105], v[172:175], v[198:201], v[102:105]
	v_mfma_f32_16x16x32_bf16 v[98:101], v[180:183], v[198:201], v[98:101]
	v_mfma_f32_16x16x32_bf16 v[86:89], v[172:175], v[206:209], v[86:89]
	v_mfma_f32_16x16x32_bf16 v[82:85], v[180:183], v[206:209], v[82:85]
	v_mfma_f32_16x16x32_bf16 v[70:73], v[172:175], v[214:217], v[70:73]
	v_mfma_f32_16x16x32_bf16 v[66:69], v[180:183], v[214:217], v[66:69]
	s_barrier
	s_setprio 0
	s_add_u32 s44, s44, 0x80
	s_addc_u32 s45, s45, 0
	s_add_i32 m0, s48, 0x18000
	ds_read_b128 v[184:187], v158 offset:49152
	ds_read_b128 v[188:191], v158 offset:50176
	ds_read_b128 v[192:195], v158 offset:51200
	ds_read_b128 v[198:201], v158 offset:52224
	ds_read_b128 v[202:205], v158 offset:53248
	ds_read_b128 v[206:209], v158 offset:54272
	ds_read_b128 v[210:213], v158 offset:55296
	ds_read_b128 v[214:217], v158 offset:56320
	global_load_lds_dwordx4 v132, s[44:45]
	s_add_i32 m0, s48, 0x1a000
	s_add_u32 s46, s46, 0xffc00080
	global_load_lds_dwordx4 v136, s[44:45]
	s_addc_u32 s47, s47, -1
	s_add_u32 s44, s44, 0x400000
	s_addc_u32 s45, s45, 0
	s_add_i32 m0, s48, 0x1c000
	s_nop 0
	global_load_lds_dwordx4 v132, s[44:45]
	s_add_i32 m0, s48, 0x1e000
	s_nop 0
	global_load_lds_dwordx4 v136, s[44:45]
	s_mov_b32 m0, s53
	s_nop 0
	global_load_lds_dwordx4 v130, s[46:47]
	s_mov_b32 m0, s54
	s_nop 0
	global_load_lds_dwordx4 v134, s[46:47]
	s_add_i32 s67, s67, 2
	s_add_u32 s42, s42, 0x100
	s_addc_u32 s43, s43, 0
	s_add_u32 s65, s65, 0x100
	s_addc_u32 s66, s66, 0
	s_cmpk_gt_u32 s67, 0xfd
	s_waitcnt vmcnt(8)
	s_waitcnt lgkmcnt(0)
	s_setprio 1
	s_barrier
	v_mfma_f32_16x16x32_bf16 v[62:65], v[146:149], v[184:187], v[62:65]
	v_mfma_f32_16x16x32_bf16 v[58:61], v[160:163], v[184:187], v[58:61]
	v_mfma_f32_16x16x32_bf16 v[46:49], v[146:149], v[192:195], v[46:49]
	v_mfma_f32_16x16x32_bf16 v[42:45], v[160:163], v[192:195], v[42:45]
	v_mfma_f32_16x16x32_bf16 v[30:33], v[146:149], v[202:205], v[30:33]
	v_mfma_f32_16x16x32_bf16 v[26:29], v[160:163], v[202:205], v[26:29]
	v_mfma_f32_16x16x32_bf16 v[14:17], v[146:149], v[210:213], v[14:17]
	v_mfma_f32_16x16x32_bf16 v[10:13], v[160:163], v[210:213], v[10:13]
	v_mfma_f32_16x16x32_bf16 v[62:65], v[150:153], v[188:191], v[62:65]
	v_mfma_f32_16x16x32_bf16 v[58:61], v[164:167], v[188:191], v[58:61]
	v_mfma_f32_16x16x32_bf16 v[46:49], v[150:153], v[198:201], v[46:49]
	v_mfma_f32_16x16x32_bf16 v[42:45], v[164:167], v[198:201], v[42:45]
	v_mfma_f32_16x16x32_bf16 v[30:33], v[150:153], v[206:209], v[30:33]
	v_mfma_f32_16x16x32_bf16 v[26:29], v[164:167], v[206:209], v[26:29]
	v_mfma_f32_16x16x32_bf16 v[14:17], v[150:153], v[214:217], v[14:17]
	v_mfma_f32_16x16x32_bf16 v[10:13], v[164:167], v[214:217], v[10:13]
	v_mfma_f32_16x16x32_bf16 v[54:57], v[168:171], v[184:187], v[54:57]
	v_mfma_f32_16x16x32_bf16 v[50:53], v[176:179], v[184:187], v[50:53]
	v_mfma_f32_16x16x32_bf16 v[38:41], v[168:171], v[192:195], v[38:41]
	v_mfma_f32_16x16x32_bf16 v[34:37], v[176:179], v[192:195], v[34:37]
	v_mfma_f32_16x16x32_bf16 v[22:25], v[168:171], v[202:205], v[22:25]
	v_mfma_f32_16x16x32_bf16 v[18:21], v[176:179], v[202:205], v[18:21]
	v_mfma_f32_16x16x32_bf16 v[6:9], v[168:171], v[210:213], v[6:9]
	v_mfma_f32_16x16x32_bf16 v[2:5], v[176:179], v[210:213], v[2:5]
	v_mfma_f32_16x16x32_bf16 v[54:57], v[172:175], v[188:191], v[54:57]
	v_mfma_f32_16x16x32_bf16 v[50:53], v[180:183], v[188:191], v[50:53]
	v_mfma_f32_16x16x32_bf16 v[38:41], v[172:175], v[198:201], v[38:41]
	v_mfma_f32_16x16x32_bf16 v[34:37], v[180:183], v[198:201], v[34:37]
	v_mfma_f32_16x16x32_bf16 v[22:25], v[172:175], v[206:209], v[22:25]
	v_mfma_f32_16x16x32_bf16 v[18:21], v[180:183], v[206:209], v[18:21]
	v_mfma_f32_16x16x32_bf16 v[6:9], v[172:175], v[214:217], v[6:9]
	v_mfma_f32_16x16x32_bf16 v[2:5], v[180:183], v[214:217], v[2:5]
	s_barrier
	s_setprio 0
	s_cbranch_scc0 .LBB0_897
	s_and_b64 vcc, exec, s[14:15]
	s_cbranch_vccz .LBB0_900
	s_barrier
